# v070 + the branches left behind by the removed offset barriers (conditional branch whose both successors are the same block) deleted: 14 sites
# baseline (speedup 1.0000x reference)
; #define PG8_STAGE(bufoff, gbase, voff) do { _Pragma("unroll") for (int _i = 0; _i < 2; ++_i) \
;         __builtin_amdgcn_global_load_lds((const unsigned*)((const char*)(gbase) + (voff)[_i]), (PG8_LAS unsigned*)(lds + (bufoff) + ldsw + _i * 8192), 16, 0, AUX_A); } while (0)
; #define PG8_STAGEB(bufoff, gbase, voff) do { _Pragma("unroll") for (int _i = 0; _i < 2; ++_i) \
;         __builtin_amdgcn_global_load_lds((const unsigned*)((const char*)(gbase) + (voff)[_i]), (PG8_LAS unsigned*)(lds + (bufoff) + ldsw + _i * 8192), 16, 0, AUX_B); } while (0)
; template <class Epi, class Sched, bool ALIGN_EPI = false, bool SP2 = false>
; __device__ __forceinline__ void gemm_phase(PG8_LAS unsigned char* lds, const Gemm g, const Sched& S, const Epi& E) {
;     ...
;     const int tid = tid_l, wid = __builtin_amdgcn_readfirstlane(tid >> 6), lane = tid & 63, wr = wid >> 2, wc = wid & 3, fr = lane & 15, fq = lane >> 4;
;     const int K = g.K;
;     unsigned voffA[2], voffB[2];
; #pragma unroll
;     for (int i = 0; i < 2; ++i) { int R, C; stage_rc(tid * 16 + i * 8192, R, C); const int Rb = Epi::PERM ? ((R & ~31) + perm32(R & 31)) : R;
;         voffA[i] = (unsigned)(R * K + C) * 2u; voffB[i] = (unsigned)(Rb * K + C) * 2u; }
;     const size_t kstep = (size_t)(BK * 2);
;     const size_t hstep = (size_t)HALF * K * 2;
;     const size_t tstep = 2 * hstep;
;     const unsigned ldsw = (unsigned)wid * 1024u;
;     const int aoff = lds_byte(wr * 64 + fr, fq * 8), boff = lds_byte(wc * 32 + fr, fq * 8);
;     ...
;     { const int rot0 = cur.krot, nt0 = cur.nkt; const char* sA0 = PG8_KP(cA, 0, rot0, nt0); const char* sA1 = PG8_KP(cA, 1, rot0, nt0); const char* sB0 = PG8_KP(cB, 0, rot0, nt0); const char* sB1 = PG8_KP(cB, 1, rot0, nt0);
;     if constexpr (SP2) {
;         PG8_STAGEB(PG8_SB(0, 0), sB0, voffB); PG8_STAGEB(PG8_SB(0, 1), sB0 + hstep, voffB); PG8_STAGE(PG8_SA(0, 0), sA0, voffA); PG8_STAGE(PG8_SA(0, 1), sA0 + hstep, voffA);
.LBB0_260:
	s_cmp_le_i32 s90, s30
	s_cselect_b64 s[0:1], -1, 0
	s_cmp_lt_i32 s30, s91
	s_cselect_b64 s[4:5], -1, 0
	s_and_b64 s[0:1], s[0:1], s[4:5]
	s_andn2_b64 vcc, exec, s[0:1]
	s_cbranch_vccnz .LBB0_741
	v_readlane_b32 s2, v254, 53
	v_readlane_b32 s3, v254, 54
	s_mov_b32 s3, s79
	s_mul_hi_u32 s0, s2, 0x1a00000
	v_writelane_b32 v254, s2, 53
	s_mul_i32 s1, s2, 0x1a00000
	s_mov_b64 s[82:83], s[66:67]
	s_add_u32 s1, s82, s1
	s_addc_u32 s0, s83, s0
	s_add_u32 s24, s1, 0x1000000
	s_addc_u32 s25, s0, 0
	v_readlane_b32 s0, v251, 53
	v_mov_b32_e32 v16, v0
	v_readlane_b32 s1, v251, 54
	v_writelane_b32 v254, s3, 54
	s_andn2_b64 vcc, exec, s[0:1]
	v_readfirstlane_b32 s16, v16
	s_cbranch_vccnz .LBB0_592
	v_lshlrev_b32_e32 v1, 4, v16
	v_add_u32_e32 v2, 0x2000, v1
	v_ashrrev_i32_e32 v3, 31, v2
	v_lshrrev_b32_e32 v3, 22, v3
	v_add_u32_e32 v3, v2, v3
	v_ashrrev_i32_e32 v10, 10, v3
	v_mul_i32_i24_e32 v3, 0x400, v10
	v_sub_u32_e32 v2, v2, v3
	v_lshrrev_b32_e32 v3, 4, v2
	v_bitop3_b32 v2, v3, v2, 32 bitop3:0x6c
	v_ashrrev_i32_e32 v3, 31, v2
	v_lshrrev_b32_e32 v3, 26, v3
	v_add_u32_e32 v3, v2, v3
	v_lshlrev_b32_e32 v4, 3, v10
	v_ashrrev_i32_e32 v11, 6, v3
	v_and_b32_e32 v4, -16, v4
	v_add_u32_e32 v4, v11, v4
	v_and_b32_e32 v5, 3, v11
	s_mov_b32 s2, 0xfffe0
	v_lshrrev_b32_e32 v6, 2, v4
	v_lshlrev_b32_e32 v7, 1, v4
	v_and_b32_e32 v3, 0xc0, v3
	v_and_or_b32 v5, v4, s2, v5
	v_and_b32_e32 v6, 4, v6
	v_and_b32_e32 v7, 24, v7
	v_sub_u32_e32 v2, v2, v3
	v_or3_b32 v5, v5, v6, v7
	v_lshlrev_b32_e32 v6, 5, v10
	v_ashrrev_i16_sdwa v2, v207, sext(v2) dst_sel:DWORD dst_unused:UNUSED_PAD src0_sel:DWORD src1_sel:BYTE_0
	v_and_b32_e32 v6, 32, v6
	v_bfe_i32 v12, v2, 0, 16
	v_add_lshl_u32 v2, v6, v12, 1
	v_lshl_add_u32 v180, v5, 12, v2
	v_lshl_add_u32 v182, v4, 12, v2
	v_bfe_i32 v2, v16, 27, 1
	v_lshrrev_b32_e32 v2, 22, v2
	v_add_u32_e32 v2, v1, v2
	v_and_b32_e32 v2, 0xfffffc00, v2
	v_sub_u32_e32 v1, v1, v2
	v_lshrrev_b32_e32 v2, 4, v1
	v_ashrrev_i32_e32 v3, 31, v16
	v_bitop3_b32 v1, v2, v1, 32 bitop3:0x6c
	v_lshrrev_b32_e32 v3, 26, v3
	v_ashrrev_i32_e32 v2, 31, v1
	v_add_u32_e32 v3, v16, v3
	v_lshrrev_b32_e32 v2, 26, v2
	v_ashrrev_i32_e32 v14, 6, v3
	v_add_u32_e32 v2, v1, v2
	v_lshlrev_b32_e32 v3, 3, v14
	v_ashrrev_i32_e32 v13, 6, v2
	v_and_b32_e32 v3, -16, v3
	v_add_u32_e32 v3, v13, v3
	s_add_u32 s88, s82, 0x1c800000
	v_and_b32_e32 v4, 3, v13
	v_lshrrev_b32_e32 v5, 2, v3
	v_lshlrev_b32_e32 v6, 1, v3
	v_and_b32_e32 v2, 0xc0, v2
	s_addc_u32 s8, s83, 0
	s_ashr_i32 s1, s16, 6
	v_and_or_b32 v4, v3, s2, v4
	v_and_b32_e32 v5, 4, v5
	v_and_b32_e32 v6, 24, v6
	v_sub_u32_e32 v1, v1, v2
	s_ashr_i32 s0, s16, 8
	s_lshl_b32 s70, s1, 10
	v_or3_b32 v4, v4, v5, v6
	v_lshlrev_b32_e32 v5, 5, v14
	v_ashrrev_i16_sdwa v1, v207, sext(v1) dst_sel:DWORD dst_unused:UNUSED_PAD src0_sel:DWORD src1_sel:BYTE_0
	v_readlane_b32 s2, v252, 47
	v_and_b32_e32 v5, 32, v5
	v_bfe_i32 v15, v1, 0, 16
	v_readlane_b32 s3, v252, 48
	s_add_u32 s38, s24, s2
	v_add_lshl_u32 v1, v5, v15, 1
	s_addc_u32 s39, s25, s3
	s_add_i32 s96, s70, 0
	v_lshl_add_u32 v184, v4, 12, v1
	s_add_i32 m0, s96, 0x10000
	v_readlane_b32 s2, v252, 51
	global_load_lds_dwordx4 v184, s[38:39]
	s_add_i32 m0, s96, 0x12000
	v_readlane_b32 s3, v252, 52
	s_add_u32 s40, s88, s2
	s_addc_u32 s41, s8, s3
	s_add_u32 s4, s38, 0x80000
	global_load_lds_dwordx4 v180, s[38:39]
	s_addc_u32 s5, s39, 0
	s_add_i32 m0, s96, 0x14000
	s_add_i32 s71, s96, 0x2000
	global_load_lds_dwordx4 v184, s[4:5]
	s_add_i32 m0, s96, 0x16000
	v_lshl_add_u32 v186, v3, 12, v1
	global_load_lds_dwordx4 v180, s[4:5]
	s_mov_b32 m0, s96
	s_add_u32 s4, s40, 0x80000
	global_load_lds_dwordx4 v186, s[40:41]
	s_mov_b32 m0, s71
	s_addc_u32 s5, s41, 0
	s_add_i32 s33, s96, 0x4000
	global_load_lds_dwordx4 v182, s[40:41]
	s_mov_b32 m0, s33
	s_add_i32 s30, s96, 0x6000
	global_load_lds_dwordx4 v186, s[4:5]
	s_mov_b32 m0, s30
	s_cmp_eq_u32 s0, 1
	global_load_lds_dwordx4 v182, s[4:5]
	s_cselect_b64 s[2:3], -1, 0
	v_mov_b32_e32 v185, v98
	v_mov_b32_e32 v181, v98
	v_mov_b32_e32 v187, v98
	v_mov_b32_e32 v183, v98
	v_writelane_b32 v254, s2, 58
	v_lshl_add_u64 v[6:7], s[38:39], 0, v[184:185]
	v_lshl_add_u64 v[4:5], s[38:39], 0, v[180:181]
	v_lshl_add_u64 v[2:3], s[40:41], 0, v[186:187]
	v_writelane_b32 v254, s3, 59
	s_cmp_lg_u32 s0, 1
	v_lshl_add_u64 v[8:9], s[40:41], 0, v[182:183]
; #define PG8_STAGE(bufoff, gbase, voff) do { _Pragma("unroll") for (int _i = 0; _i < 2; ++_i) \
;         __builtin_amdgcn_global_load_lds((const unsigned*)((const char*)(gbase) + (voff)[_i]), (PG8_LAS unsigned*)(lds + (bufoff) + ldsw + _i * 8192), 16, 0, AUX_A); } while (0)
; #define PG8_STAGEB(bufoff, gbase, voff) do { _Pragma("unroll") for (int _i = 0; _i < 2; ++_i) \
;         __builtin_amdgcn_global_load_lds((const unsigned*)((const char*)(gbase) + (voff)[_i]), (PG8_LAS unsigned*)(lds + (bufoff) + ldsw + _i * 8192), 16, 0, AUX_B); } while (0)
; #define PG8_WAIT_V(n) asm volatile("s_waitcnt vmcnt(" #n ")" ::: "memory")
; #define PG8_BAR __builtin_amdgcn_s_barrier()
; template <class Epi, class Sched, bool ALIGN_EPI = false, bool SP2 = false>
; __device__ __forceinline__ void gemm_phase(PG8_LAS unsigned char* lds, const Gemm g, const Sched& S, const Epi& E) {
;     ...
;     const int aoff = lds_byte(wr * 64 + fr, fq * 8), boff = lds_byte(wc * 32 + fr, fq * 8);
;     ...
;         PG8_STAGEB(PG8_SB(1, 0), sB1, voffB); PG8_STAGE(PG8_SA(1, 0), sA1, voffA); PG8_STAGEB(PG8_SB(1, 1), sB1 + hstep, voffB);
;         PG8_WAIT_V(6); PG8_BAR;
.LBB0_264:
	v_readlane_b32 s2, v254, 53
	v_readlane_b32 s3, v254, 54
	v_readlane_b32 s44, v249, 50
	s_lshl_b64 s[6:7], s[2:3], 14
	v_readlane_b32 s50, v249, 56
	v_readlane_b32 s51, v249, 57
	s_add_u32 s4, s50, s6
	s_addc_u32 s5, s51, s7
	s_lshl_b32 s78, s2, 6
	s_lshl_b32 s31, s2, 4
	s_lshl_b32 s75, s2, 2
	s_add_u32 s20, s82, 0x1ec00000
	s_addc_u32 s21, s83, 0
	v_writelane_b32 v254, s4, 60
	s_add_u32 s22, s82, 0x26100000
	s_addc_u32 s23, s83, 0
	v_writelane_b32 v254, s5, 61
	s_mov_b64 s[4:5], s[82:83]
	s_add_u32 s82, s4, 0x27300000
	s_addc_u32 s83, s5, 0
	v_bfe_u32 v99, v16, 4, 2
	s_add_u32 s2, s4, 0x800000
	v_and_b32_e32 v1, 15, v16
	v_lshlrev_b32_e32 v17, 4, v99
	v_lshlrev_b32_e32 v16, 2, v16
	v_writelane_b32 v254, s4, 62
	s_addc_u32 s3, s5, 0
	s_and_b32 s18, s1, 3
	s_lshl_b32 s6, s0, 6
	v_lshl_or_b32 v17, v1, 6, v17
	s_lshl_b32 s0, s0, 13
	v_and_b32_e32 v16, 32, v16
	v_bitop3_b32 v18, v17, s0, v16 bitop3:0xde
	s_lshl_b32 s0, s18, 5
	s_add_i32 m0, s96, 0x18000
	v_lshl_add_u64 v[6:7], v[6:7], 0, s[76:77]
	v_writelane_b32 v255, s0, 0
	s_lshl_b32 s0, s18, 12
	global_load_lds_dwordx4 v[6:7], off
	v_lshl_add_u64 v[4:5], v[4:5], 0, s[76:77]
	s_add_i32 m0, s96, 0x1a000
	s_add_i32 s90, s96, 0x8000
	s_add_i32 s91, s96, 0xa000
	v_bitop3_b32 v221, v17, s0, v16 bitop3:0xde
	global_load_lds_dwordx4 v[4:5], off
	v_lshl_add_u64 v[2:3], v[2:3], 0, s[76:77]
	s_mov_b32 m0, s90
	s_add_u32 s0, s38, 0x80080
	global_load_lds_dwordx4 v[2:3], off
	v_lshl_add_u64 v[2:3], v[8:9], 0, s[76:77]
	s_mov_b32 m0, s91
	s_addc_u32 s1, s39, 0
	global_load_lds_dwordx4 v[2:3], off
	s_add_i32 m0, s96, 0x1c000
	v_lshl_add_u64 v[2:3], s[0:1], 0, v[184:185]
	global_load_lds_dwordx4 v[2:3], off
	v_lshl_add_u64 v[2:3], s[0:1], 0, v[180:181]
	s_add_i32 m0, s96, 0x1e000
	s_cmpk_lt_u32 s16, 0x100
	global_load_lds_dwordx4 v[2:3], off
	v_lshlrev_b32_e32 v2, 15, v10
	v_and_b32_e32 v2, 0xffff0000, v2
	v_lshl_add_u32 v2, v11, 12, v2
	v_and_b32_e32 v3, 1, v10
	v_lshl_or_b32 v2, v3, 6, v2
	s_cselect_b64 s[10:11], -1, 0
	s_lshl_b32 s0, s18, 6
	v_lshl_add_u32 v188, v12, 1, v2
	v_lshlrev_b32_e32 v2, 15, v14
	v_writelane_b32 v255, s0, 1
	s_or_b32 s93, s0, 0xfffffc00
	v_and_b32_e32 v2, 0xffff0000, v2
	s_lshl_b64 s[0:1], s[78:79], 2
	s_waitcnt vmcnt(6)
	v_lshl_add_u32 v2, v13, 12, v2
	v_and_b32_e32 v3, 1, v14
	v_writelane_b32 v255, s0, 2
	v_lshl_or_b32 v2, v3, 6, v2
	v_writelane_b32 v254, s5, 63
	v_writelane_b32 v255, s1, 3
	v_readlane_b32 s0, v252, 49
	v_mov_b32_e32 v189, v98
	v_lshl_add_u32 v190, v15, 1, v2
	v_mov_b32_e32 v191, v98
	s_mov_b32 s94, 0
	v_add_u32_e32 v222, 0, v18
	v_readlane_b32 s95, v253, 5
	s_mov_b32 s78, s0
	v_readlane_b32 s45, v249, 51
	v_readlane_b32 s46, v249, 52
	v_readlane_b32 s47, v249, 53
	v_readlane_b32 s48, v249, 54
	v_readlane_b32 s49, v249, 55
	v_readlane_b32 s52, v249, 58
	v_readlane_b32 s53, v249, 59
	v_readlane_b32 s54, v249, 60
	v_readlane_b32 s55, v249, 61
	v_readlane_b32 s56, v249, 62
	v_readlane_b32 s57, v249, 63
	v_readlane_b32 s58, v250, 0
	v_readlane_b32 s59, v250, 1
	s_barrier
	v_readlane_b32 s1, v252, 50
	s_branch .LBB0_267

; #define PG8_BAR __builtin_amdgcn_s_barrier()
; template <class Epi, class Sched, bool ALIGN_EPI = false, bool SP2 = false>
; __device__ __forceinline__ void gemm_phase(PG8_LAS unsigned char* lds, const Gemm g, const Sched& S, const Epi& E) {
;     ...
;         if (!has_next) break;
; #pragma unroll
;         for (int a = 0; a < 2; ++a)
; #pragma unroll
;             for (int b = 0; b < 2; ++b)
; #pragma unroll
;                 for (int m = 0; m < 4; ++m)
; #pragma unroll
;                     for (int n = 0; n < 2; ++n) acc[a][b][m][n] = (f32x4){0.f, 0.f, 0.f, 0.f};
;         cur = nxt; cA = nA; cB = nB; ++ui;
;         if constexpr (ALIGN_EPI) { if (wr == 1) PG8_BAR; }
.LBB0_588:
	s_andn2_b64 vcc, exec, s[26:27]
	s_mov_b64 s[36:37], -1
	s_cbranch_vccnz .LBB0_266
	v_readlane_b32 s0, v254, 58
	v_readlane_b32 s1, v254, 59
	s_andn2_b64 vcc, exec, s[0:1]
	s_branch .LBB0_265

; #define PG8_STAGE(bufoff, gbase, voff) do { _Pragma("unroll") for (int _i = 0; _i < 2; ++_i) \
;         __builtin_amdgcn_global_load_lds((const unsigned*)((const char*)(gbase) + (voff)[_i]), (PG8_LAS unsigned*)(lds + (bufoff) + ldsw + _i * 8192), 16, 0, AUX_A); } while (0)
; #define PG8_STAGEB(bufoff, gbase, voff) do { _Pragma("unroll") for (int _i = 0; _i < 2; ++_i) \
;         __builtin_amdgcn_global_load_lds((const unsigned*)((const char*)(gbase) + (voff)[_i]), (PG8_LAS unsigned*)(lds + (bufoff) + ldsw + _i * 8192), 16, 0, AUX_B); } while (0)
; #define PG8_WAIT_V(n) asm volatile("s_waitcnt vmcnt(" #n ")" ::: "memory")
; #define PG8_BAR __builtin_amdgcn_s_barrier()
; template <class Epi, class Sched, bool ALIGN_EPI = false, bool SP2 = false>
; __device__ __forceinline__ void gemm_phase(PG8_LAS unsigned char* lds, const Gemm g, const Sched& S, const Epi& E) {
;     ...
;     const int tid = tid_l, wid = __builtin_amdgcn_readfirstlane(tid >> 6), lane = tid & 63, wr = wid >> 2, wc = wid & 3, fr = lane & 15, fq = lane >> 4;
;     const int K = g.K;
;     unsigned voffA[2], voffB[2];
; #pragma unroll
;     for (int i = 0; i < 2; ++i) { int R, C; stage_rc(tid * 16 + i * 8192, R, C); const int Rb = Epi::PERM ? ((R & ~31) + perm32(R & 31)) : R;
;         voffA[i] = (unsigned)(R * K + C) * 2u; voffB[i] = (unsigned)(Rb * K + C) * 2u; }
;     const size_t kstep = (size_t)(BK * 2);
;     const size_t hstep = (size_t)HALF * K * 2;
;     const size_t tstep = 2 * hstep;
;     const unsigned ldsw = (unsigned)wid * 1024u;
;     const int aoff = lds_byte(wr * 64 + fr, fq * 8), boff = lds_byte(wc * 32 + fr, fq * 8);
;     ...
;     { const int rot0 = cur.krot, nt0 = cur.nkt; const char* sA0 = PG8_KP(cA, 0, rot0, nt0); const char* sA1 = PG8_KP(cA, 1, rot0, nt0); const char* sB0 = PG8_KP(cB, 0, rot0, nt0); const char* sB1 = PG8_KP(cB, 1, rot0, nt0);
;     if constexpr (SP2) {
;         PG8_STAGEB(PG8_SB(0, 0), sB0, voffB); PG8_STAGEB(PG8_SB(0, 1), sB0 + hstep, voffB); PG8_STAGE(PG8_SA(0, 0), sA0, voffA); PG8_STAGE(PG8_SA(0, 1), sA0 + hstep, voffA);
;         if (wr == 1) PG8_BAR;
;         PG8_WAIT_V(2); PG8_BAR;
;         PG8_STAGEB(PG8_SB(1, 0), sB1, voffB); PG8_STAGE(PG8_SA(1, 0), sA1, voffA); PG8_STAGEB(PG8_SB(1, 1), sB1 + hstep, voffB);
;         PG8_WAIT_V(6); PG8_BAR;
.LBB0_918:
	v_readlane_b32 s0, v254, 53
	v_readlane_b32 s1, v254, 54
	s_mov_b32 s1, s79
	v_writelane_b32 v254, s0, 53
	s_andn2_b64 vcc, exec, s[4:5]
	s_nop 0
	v_writelane_b32 v254, s1, 54
	s_cbranch_vccnz .LBB0_943
	v_ashrrev_i32_e32 v2, 31, v13
	v_lshrrev_b32_e32 v2, 26, v2
	v_add_u32_e32 v2, v13, v2
	v_ashrrev_i32_e32 v10, 6, v2
	v_bfe_i32 v2, v13, 27, 1
	v_lshlrev_b32_e32 v1, 4, v13
	v_lshrrev_b32_e32 v2, 22, v2
	v_add_u32_e32 v2, v1, v2
	v_and_b32_e32 v2, 0xfffffc00, v2
	v_sub_u32_e32 v2, v1, v2
	v_readlane_b32 s2, v254, 53
	v_lshrrev_b32_e32 v3, 4, v2
	v_readlane_b32 s3, v254, 54
	v_bitop3_b32 v2, v3, v2, 32 bitop3:0x6c
	s_lshl_b64 s[0:1], s[2:3], 21
	v_ashrrev_i32_e32 v4, 31, v2
	s_add_u32 s4, s34, 0x27780000
	v_lshrrev_b32_e32 v4, 26, v4
	s_addc_u32 s5, s35, 0
	v_add_u32_e32 v4, v2, v4
	s_add_u32 s0, s34, s0
	v_lshlrev_b32_e32 v3, 3, v10
	v_ashrrev_i32_e32 v11, 6, v4
	v_and_b32_e32 v4, 0xc0, v4
	s_addc_u32 s1, s35, s1
	v_and_b32_e32 v3, -16, v3
	v_sub_u32_e32 v2, v2, v4
	s_add_u32 s30, s0, 0x7800000
	v_add_u32_e32 v3, v11, v3
	v_ashrrev_i16_sdwa v2, v207, sext(v2) dst_sel:DWORD dst_unused:UNUSED_PAD src0_sel:DWORD src1_sel:BYTE_0
	s_addc_u32 s31, s1, 0
	v_lshlrev_b32_e32 v5, 5, v10
	v_bfe_i32 v12, v2, 0, 16
	v_lshlrev_b32_e32 v2, 1, v3
	v_lshrrev_b32_e32 v4, 2, v3
	v_and_b32_e32 v6, 3, v11
	s_mov_b32 s1, 0x1fffe0
	v_and_b32_e32 v5, 32, v5
	v_and_b32_e32 v2, 24, v2
	v_and_b32_e32 v4, 4, v4
	v_and_or_b32 v6, v3, s1, v6
	v_or3_b32 v2, v6, v4, v2
	v_add_lshl_u32 v4, v5, v12, 1
	v_add_u32_e32 v1, 0x2000, v1
	v_lshl_add_u32 v150, v2, 11, v4
	v_ashrrev_i32_e32 v2, 31, v1
	v_lshrrev_b32_e32 v2, 22, v2
	v_add_u32_e32 v2, v1, v2
	v_ashrrev_i32_e32 v14, 10, v2
	v_mul_i32_i24_e32 v2, 0x400, v14
	v_sub_u32_e32 v1, v1, v2
	v_lshrrev_b32_e32 v2, 4, v1
	v_bitop3_b32 v1, v2, v1, 32 bitop3:0x6c
	v_lshl_add_u32 v148, v3, 11, v4
	v_ashrrev_i32_e32 v3, 31, v1
	v_lshrrev_b32_e32 v3, 26, v3
	v_lshlrev_b32_e32 v2, 3, v14
	v_add_u32_e32 v3, v1, v3
	v_and_b32_e32 v2, -16, v2
	v_ashrrev_i32_e32 v15, 6, v3
	v_add_u32_e32 v2, v15, v2
	v_and_b32_e32 v5, 3, v15
	v_and_or_b32 v5, v2, s1, v5
	s_ashr_i32 s1, s12, 6
	s_ashr_i32 s43, s42, 31
	s_ashr_i32 s25, s24, 31
	s_ashr_i32 s0, s12, 8
	s_lshl_b32 s33, s1, 10
	s_lshl_b64 s[6:7], s[42:43], 19
	s_lshl_b64 s[8:9], s[24:25], 19
	v_and_b32_e32 v3, 0xc0, v3
	s_add_u32 s26, s30, s8
	v_sub_u32_e32 v1, v1, v3
	s_addc_u32 s27, s31, s9
	s_add_i32 s25, s33, 0
	v_ashrrev_i16_sdwa v1, v207, sext(v1) dst_sel:DWORD dst_unused:UNUSED_PAD src0_sel:DWORD src1_sel:BYTE_0
	s_add_i32 m0, s25, 0x10000
	v_lshlrev_b32_e32 v4, 5, v14
	v_bfe_i32 v16, v1, 0, 16
	v_lshlrev_b32_e32 v1, 1, v2
	v_lshrrev_b32_e32 v3, 2, v2
	global_load_lds_dwordx4 v150, s[26:27]
	s_add_i32 m0, s25, 0x12000
	v_and_b32_e32 v4, 32, v4
	v_and_b32_e32 v1, 24, v1
	v_and_b32_e32 v3, 4, v3
	s_add_u32 s64, s4, s6
	v_or3_b32 v1, v5, v3, v1
	v_add_lshl_u32 v3, v4, v16, 1
	s_addc_u32 s65, s5, s7
	v_lshl_add_u32 v154, v1, 11, v3
	s_add_u32 s6, s26, 0x40000
	global_load_lds_dwordx4 v154, s[26:27]
	s_addc_u32 s7, s27, 0
	s_add_i32 m0, s25, 0x14000
	s_add_i32 s62, s25, 0x2000
	global_load_lds_dwordx4 v150, s[6:7]
	s_add_i32 m0, s25, 0x16000
	v_lshl_add_u32 v152, v2, 11, v3
	global_load_lds_dwordx4 v154, s[6:7]
	s_mov_b32 m0, s25
	s_add_u32 s6, s64, 0x40000
	global_load_lds_dwordx4 v148, s[64:65]
	s_mov_b32 m0, s62
	s_addc_u32 s7, s65, 0
	s_add_i32 s63, s25, 0x4000
	global_load_lds_dwordx4 v152, s[64:65]
	s_mov_b32 m0, s63
	s_add_i32 s69, s25, 0x6000
	global_load_lds_dwordx4 v148, s[6:7]
	s_mov_b32 m0, s69
	v_mov_b32_e32 v151, v98
	global_load_lds_dwordx4 v152, s[6:7]
	v_mov_b32_e32 v155, v98
	v_mov_b32_e32 v149, v98
	v_mov_b32_e32 v153, v98
	s_cmp_eq_u32 s0, 1
	v_lshl_add_u64 v[8:9], s[26:27], 0, v[150:151]
	v_lshl_add_u64 v[6:7], s[26:27], 0, v[154:155]
	v_lshl_add_u64 v[2:3], s[64:65], 0, v[148:149]
	s_cselect_b64 s[6:7], -1, 0
	s_cmp_lg_u32 s0, 1
	v_lshl_add_u64 v[4:5], s[64:65], 0, v[152:153]
.LBB0_921:
	v_readlane_b32 s44, v249, 34
	s_lshl_b64 s[8:9], s[2:3], 12
	v_readlane_b32 s56, v249, 46
	v_readlane_b32 s57, v249, 47
	s_add_u32 s8, s56, s8
	v_lshrrev_b32_e32 v18, 1, v13
	s_addc_u32 s9, s57, s9
	v_and_b32_e32 v18, 24, v18
	s_add_u32 s10, s34, 0x28980000
	v_and_b32_e32 v17, 15, v13
	v_lshlrev_b32_e32 v19, 1, v18
	v_lshlrev_b32_e32 v13, 2, v13
	s_addc_u32 s11, s35, 0
	v_lshl_or_b32 v1, s0, 6, v17
	v_lshl_or_b32 v17, v17, 6, v19
	s_lshl_b32 s0, s0, 13
	v_and_b32_e32 v13, 32, v13
	v_bitop3_b32 v19, v17, s0, v13 bitop3:0xde
	s_lshl_b32 s0, s1, 5
	s_and_b32 s2, s0, 0x60
	s_add_i32 m0, s25, 0x18000
	v_lshl_add_u64 v[8:9], v[8:9], 0, s[76:77]
	s_lshl_b32 s0, s2, 7
	global_load_lds_dwordx4 v[8:9], off
	v_lshl_add_u64 v[6:7], v[6:7], 0, s[76:77]
	s_add_i32 m0, s25, 0x1a000
	s_add_i32 s70, s25, 0x8000
	s_add_i32 s71, s25, 0xa000
	v_bitop3_b32 v99, v17, s0, v13 bitop3:0xde
	global_load_lds_dwordx4 v[6:7], off
	v_lshl_add_u64 v[2:3], v[2:3], 0, s[76:77]
	s_mov_b32 m0, s70
	s_add_u32 s0, s26, 0x40080
	global_load_lds_dwordx4 v[2:3], off
	v_lshl_add_u64 v[2:3], v[4:5], 0, s[76:77]
	s_mov_b32 m0, s71
	s_addc_u32 s1, s27, 0
	global_load_lds_dwordx4 v[2:3], off
	s_add_i32 m0, s25, 0x1c000
	v_lshl_add_u64 v[2:3], s[0:1], 0, v[150:151]
	global_load_lds_dwordx4 v[2:3], off
	v_lshl_add_u64 v[2:3], s[0:1], 0, v[154:155]
	s_add_i32 m0, s25, 0x1e000
	v_readlane_b32 s45, v249, 35
	global_load_lds_dwordx4 v[2:3], off
	v_lshlrev_b32_e32 v2, 14, v14
	v_and_b32_e32 v2, 0xffff8000, v2
	v_lshl_add_u32 v2, v15, 11, v2
	v_and_b32_e32 v3, 1, v14
	v_lshl_or_b32 v2, v3, 6, v2
	v_lshl_add_u32 v156, v16, 1, v2
	v_lshlrev_b32_e32 v2, 14, v10
	v_and_b32_e32 v2, 0xffff8000, v2
	s_waitcnt vmcnt(6)
	v_lshl_add_u32 v2, v11, 11, v2
	v_and_b32_e32 v3, 1, v10
	v_readlane_b32 s48, v249, 38
	v_readlane_b32 s49, v249, 39
	v_readlane_b32 s50, v249, 40
	v_readlane_b32 s51, v249, 41
	s_cmpk_lt_u32 s12, 0x100
	v_lshl_or_b32 v2, v3, 6, v2
	s_cselect_b64 s[12:13], -1, 0
	v_or_b32_e32 v164, s2, v18
	v_mov_b32_e32 v157, v98
	v_lshl_add_u32 v158, v12, 1, v2
	v_mov_b32_e32 v159, v98
	s_mov_b32 s75, 0
	v_add_u32_e32 v165, 0, v19
	v_readlane_b32 s3, v252, 31
	v_readlane_b32 s44, v252, 33
	v_readlane_b32 s45, v252, 11
	v_readlane_b32 s48, v252, 12
	s_mov_b32 s49, 0x40000
	s_mov_b32 s50, 0x48000
	s_mov_b32 s51, 0x50000
	s_mov_b32 s66, 0x58000
	v_readlane_b32 s46, v249, 36
	v_readlane_b32 s47, v249, 37
	v_readlane_b32 s52, v249, 42
	v_readlane_b32 s53, v249, 43
	v_readlane_b32 s54, v249, 44
	v_readlane_b32 s55, v249, 45
	v_readlane_b32 s58, v249, 48
	v_readlane_b32 s59, v249, 49
	s_barrier
	s_branch .LBB0_924

; #define GAS __attribute__((address_space(1)))
; __device__ __forceinline__ unsigned cvt_pk_bf16(float lo, float hi) { typedef float f32x2_l __attribute__((ext_vector_type(2))); const bf16x2_native b = __builtin_convertvector((f32x2_l){lo, hi}, bf16x2_native); return __builtin_bit_cast(unsigned, b); }
; __device__ __forceinline__ void unpack8(u32x4 w, f32x4& v0, f32x4& v1) { v0 = (f32x4){bflo(w.x), bfhi(w.x), bflo(w.y), bfhi(w.y)}; v1 = (f32x4){bflo(w.z), bfhi(w.z), bflo(w.w), bfhi(w.w)}; }
; #define GAS __attribute__((address_space(1)))
; __device__ __forceinline__ f32x4 sigmoid4(f32x4 v) {
;     const f32x2 t0 = (f32x2){v[0], v[1]} * -1.4426950408889634f, t1 = (f32x2){v[2], v[3]} * -1.4426950408889634f;
;     const f32x2 d0 = (f32x2){__builtin_amdgcn_exp2f(t0.x), __builtin_amdgcn_exp2f(t0.y)} + 1.0f, d1 = (f32x2){__builtin_amdgcn_exp2f(t1.x), __builtin_amdgcn_exp2f(t1.y)} + 1.0f;
;     return (f32x4){__builtin_amdgcn_rcpf(d0.x), __builtin_amdgcn_rcpf(d0.y), __builtin_amdgcn_rcpf(d1.x), __builtin_amdgcn_rcpf(d1.y)}; }
; __device__ __forceinline__ u32x4 pack8(f32x4 v0, f32x4 v1) { u32x4 w; w.x = cvt_pk_bf16(v0[0], v0[1]); w.y = cvt_pk_bf16(v0[2], v0[3]); w.z = cvt_pk_bf16(v1[0], v1[1]); w.w = cvt_pk_bf16(v1[2], v1[3]); return w; }
;     __device__ __forceinline__ void operator()(const f32x4 (&acc)[2][2][4][2], const Unit& u, int wr, int wc, int fr, int fq) const {
;     ...
;             for (int n = 0; n < 2; ++n) bv[bj][n] = *(const f32x4*)(bglu + col0 + bj * HALF + 4 * n);
;         const bf16_t* const zb = Z + (size_t)row0 * 1024 + col0; bf16_t* const sob = SO + (size_t)row0 * 1024 + col0;
; #pragma unroll
;         for (int ai = 0; ai < 2; ++ai)
; #pragma unroll
;             for (int m = 0; m < 4; ++m) { const size_t off = (size_t)(ai * HALF + m * 16) * 1024;
; #pragma unroll
;                 for (int bj = 0; bj < 2; ++bj) { f32x4 z0, z1; unpack8(*(const GAS u32x4*)(zb + off + bj * HALF), z0, z1);
;                     const f32x4 v0 = z0 * sigmoid4(acc[ai][bj][m][0] + bv[bj][0]), v1 = z1 * sigmoid4(acc[ai][bj][m][1] + bv[bj][1]);
;                     *(GAS u32x4*)(sob + off + bj * HALF) = pack8(v0, v1); } }
.LBB0_939:
	s_waitcnt vmcnt(9)
	v_mov_b32_e32 v180, v184
	v_mov_b32_e32 v181, v185
	v_mov_b32_e32 v182, v186
	v_mov_b32_e32 v183, v187
	v_add_co_u32_e32 v242, vcc, s50, v162
	v_addc_co_u32_e32 v243, vcc, 0, v163, vcc
	global_load_dwordx4 v[184:187], v[242:243], off
	v_pk_add_f32 v[142:143], v[142:143], v[36:37]
	v_pk_add_f32 v[146:147], v[146:147], v[40:41]
	v_pk_add_f32 v[144:145], v[144:145], v[38:39]
	v_pk_add_f32 v[140:141], v[140:141], v[34:35]
	v_pk_mul_f32 v[144:145], v[144:145], s[74:75] op_sel_hi:[1,0]
	v_pk_mul_f32 v[146:147], v[146:147], s[74:75] op_sel_hi:[1,0]
	v_pk_mul_f32 v[140:141], v[140:141], s[74:75] op_sel_hi:[1,0]
	v_pk_mul_f32 v[142:143], v[142:143], s[74:75] op_sel_hi:[1,0]
	v_exp_f32_e32 v144, v144
	v_exp_f32_e32 v145, v145
	v_exp_f32_e32 v146, v146
	v_exp_f32_e32 v147, v147
	v_exp_f32_e32 v140, v140
	v_exp_f32_e32 v141, v141
	v_exp_f32_e32 v142, v142
	v_exp_f32_e32 v143, v143
	v_pk_add_f32 v[144:145], v[144:145], 1.0 op_sel_hi:[1,0]
	v_pk_add_f32 v[146:147], v[146:147], 1.0 op_sel_hi:[1,0]
	v_pk_add_f32 v[140:141], v[140:141], 1.0 op_sel_hi:[1,0]
	v_pk_add_f32 v[142:143], v[142:143], 1.0 op_sel_hi:[1,0]
	v_rcp_f32_e32 v144, v144
	v_rcp_f32_e32 v145, v145
	v_rcp_f32_e32 v146, v146
	v_rcp_f32_e32 v147, v147
	v_rcp_f32_e32 v140, v140
	v_rcp_f32_e32 v141, v141
	v_rcp_f32_e32 v142, v142
	v_rcp_f32_e32 v143, v143
	v_lshlrev_b32_e32 v166, 16, v180
	v_and_b32_e32 v167, 0xffff0000, v180
	v_lshlrev_b32_e32 v168, 16, v181
	v_and_b32_e32 v169, 0xffff0000, v181
	v_lshlrev_b32_e32 v172, 16, v182
	v_and_b32_e32 v173, 0xffff0000, v182
	v_lshlrev_b32_e32 v180, 16, v183
	v_and_b32_e32 v181, 0xffff0000, v183
	v_pk_mul_f32 v[146:147], v[146:147], v[168:169]
	v_pk_mul_f32 v[144:145], v[144:145], v[166:167]
	v_pk_mul_f32 v[166:167], v[142:143], v[180:181]
	v_pk_mul_f32 v[142:143], v[140:141], v[172:173]
	v_cvt_pk_bf16_f32 v140, v144, v145
	v_cvt_pk_bf16_f32 v141, v146, v147
	v_cvt_pk_bf16_f32 v142, v142, v143
	v_cvt_pk_bf16_f32 v143, v166, v167
	global_store_dwordx4 v[160:161], v[140:143], off
	v_pk_add_f32 v[138:139], v[138:139], v[24:25]
	v_pk_add_f32 v[136:137], v[136:137], v[22:23]
	v_pk_add_f32 v[134:135], v[134:135], v[16:17]
	v_pk_add_f32 v[132:133], v[132:133], v[14:15]
	v_pk_mul_f32 v[136:137], v[136:137], s[74:75] op_sel_hi:[1,0]
	v_pk_mul_f32 v[138:139], v[138:139], s[74:75] op_sel_hi:[1,0]
	v_pk_mul_f32 v[132:133], v[132:133], s[74:75] op_sel_hi:[1,0]
	v_pk_mul_f32 v[134:135], v[134:135], s[74:75] op_sel_hi:[1,0]
	v_exp_f32_e32 v136, v136
	v_exp_f32_e32 v137, v137
	v_exp_f32_e32 v138, v138
	v_exp_f32_e32 v139, v139
	v_exp_f32_e32 v132, v132
	v_exp_f32_e32 v133, v133
	v_exp_f32_e32 v134, v134
	v_exp_f32_e32 v135, v135
	v_pk_add_f32 v[136:137], v[136:137], 1.0 op_sel_hi:[1,0]
	v_pk_add_f32 v[138:139], v[138:139], 1.0 op_sel_hi:[1,0]
	v_pk_add_f32 v[132:133], v[132:133], 1.0 op_sel_hi:[1,0]
	v_pk_add_f32 v[134:135], v[134:135], 1.0 op_sel_hi:[1,0]
	v_rcp_f32_e32 v136, v136
	v_rcp_f32_e32 v137, v137
	v_rcp_f32_e32 v138, v138
	v_rcp_f32_e32 v139, v139
	v_rcp_f32_e32 v132, v132
	v_rcp_f32_e32 v133, v133
	v_rcp_f32_e32 v134, v134
	v_rcp_f32_e32 v135, v135
	v_pk_add_f32 v[128:129], v[128:129], v[38:39]
	v_pk_add_f32 v[124:125], v[124:125], v[34:35]
	v_pk_add_f32 v[130:131], v[130:131], v[40:41]
	v_pk_mul_f32 v[128:129], v[128:129], s[74:75] op_sel_hi:[1,0]
	v_pk_add_f32 v[126:127], v[126:127], v[36:37]
	v_pk_mul_f32 v[124:125], v[124:125], s[74:75] op_sel_hi:[1,0]
	v_pk_mul_f32 v[130:131], v[130:131], s[74:75] op_sel_hi:[1,0]
	v_exp_f32_e32 v128, v128
	v_exp_f32_e32 v129, v129
	v_pk_mul_f32 v[126:127], v[126:127], s[74:75] op_sel_hi:[1,0]
	v_exp_f32_e32 v124, v124
	v_exp_f32_e32 v125, v125
	v_exp_f32_e32 v130, v130
	v_exp_f32_e32 v131, v131
	v_exp_f32_e32 v126, v126
	v_exp_f32_e32 v127, v127
	v_pk_add_f32 v[128:129], v[128:129], 1.0 op_sel_hi:[1,0]
	v_pk_add_f32 v[124:125], v[124:125], 1.0 op_sel_hi:[1,0]
	v_pk_add_f32 v[130:131], v[130:131], 1.0 op_sel_hi:[1,0]
	v_rcp_f32_e32 v128, v128
	v_rcp_f32_e32 v129, v129
	v_pk_add_f32 v[126:127], v[126:127], 1.0 op_sel_hi:[1,0]
	v_rcp_f32_e32 v124, v124
	v_rcp_f32_e32 v125, v125
	v_rcp_f32_e32 v130, v130
	v_rcp_f32_e32 v131, v131
	v_rcp_f32_e32 v126, v126
	v_rcp_f32_e32 v127, v127
	v_pk_add_f32 v[122:123], v[122:123], v[24:25]
	v_pk_add_f32 v[120:121], v[120:121], v[22:23]
	v_pk_add_f32 v[118:119], v[118:119], v[16:17]
	v_pk_add_f32 v[116:117], v[116:117], v[14:15]
	v_pk_mul_f32 v[120:121], v[120:121], s[74:75] op_sel_hi:[1,0]
	v_pk_mul_f32 v[122:123], v[122:123], s[74:75] op_sel_hi:[1,0]
	v_pk_mul_f32 v[116:117], v[116:117], s[74:75] op_sel_hi:[1,0]
	v_pk_mul_f32 v[118:119], v[118:119], s[74:75] op_sel_hi:[1,0]
	v_exp_f32_e32 v120, v120
	v_exp_f32_e32 v121, v121
	v_exp_f32_e32 v122, v122
	v_exp_f32_e32 v123, v123
	v_exp_f32_e32 v116, v116
	v_exp_f32_e32 v117, v117
	v_exp_f32_e32 v118, v118
	v_exp_f32_e32 v119, v119
	v_pk_add_f32 v[120:121], v[120:121], 1.0 op_sel_hi:[1,0]
	v_pk_add_f32 v[122:123], v[122:123], 1.0 op_sel_hi:[1,0]
	v_pk_add_f32 v[116:117], v[116:117], 1.0 op_sel_hi:[1,0]
	v_pk_add_f32 v[118:119], v[118:119], 1.0 op_sel_hi:[1,0]
	v_rcp_f32_e32 v120, v120
	v_rcp_f32_e32 v121, v121
	v_rcp_f32_e32 v122, v122
	s_waitcnt vmcnt(10)
; #define GAS __attribute__((address_space(1)))
; __device__ __forceinline__ unsigned cvt_pk_bf16(float lo, float hi) { typedef float f32x2_l __attribute__((ext_vector_type(2))); const bf16x2_native b = __builtin_convertvector((f32x2_l){lo, hi}, bf16x2_native); return __builtin_bit_cast(unsigned, b); }
; __device__ __forceinline__ void unpack8(u32x4 w, f32x4& v0, f32x4& v1) { v0 = (f32x4){bflo(w.x), bfhi(w.x), bflo(w.y), bfhi(w.y)}; v1 = (f32x4){bflo(w.z), bfhi(w.z), bflo(w.w), bfhi(w.w)}; }
; #define GAS __attribute__((address_space(1)))
; __device__ __forceinline__ f32x4 sigmoid4(f32x4 v) {
;     const f32x2 t0 = (f32x2){v[0], v[1]} * -1.4426950408889634f, t1 = (f32x2){v[2], v[3]} * -1.4426950408889634f;
;     const f32x2 d0 = (f32x2){__builtin_amdgcn_exp2f(t0.x), __builtin_amdgcn_exp2f(t0.y)} + 1.0f, d1 = (f32x2){__builtin_amdgcn_exp2f(t1.x), __builtin_amdgcn_exp2f(t1.y)} + 1.0f;
;     return (f32x4){__builtin_amdgcn_rcpf(d0.x), __builtin_amdgcn_rcpf(d0.y), __builtin_amdgcn_rcpf(d1.x), __builtin_amdgcn_rcpf(d1.y)}; }
; __device__ __forceinline__ u32x4 pack8(f32x4 v0, f32x4 v1) { u32x4 w; w.x = cvt_pk_bf16(v0[0], v0[1]); w.y = cvt_pk_bf16(v0[2], v0[3]); w.z = cvt_pk_bf16(v1[0], v1[1]); w.w = cvt_pk_bf16(v1[2], v1[3]); return w; }
;     __device__ __forceinline__ void operator()(const f32x4 (&acc)[2][2][4][2], const Unit& u, int wr, int wc, int fr, int fq) const {
;     ...
;             for (int n = 0; n < 2; ++n) bv[bj][n] = *(const f32x4*)(bglu + col0 + bj * HALF + 4 * n);
;         const bf16_t* const zb = Z + (size_t)row0 * 1024 + col0; bf16_t* const sob = SO + (size_t)row0 * 1024 + col0;
; #pragma unroll
;         for (int ai = 0; ai < 2; ++ai)
; #pragma unroll
;             for (int m = 0; m < 4; ++m) { const size_t off = (size_t)(ai * HALF + m * 16) * 1024;
; #pragma unroll
;                 for (int bj = 0; bj < 2; ++bj) { f32x4 z0, z1; unpack8(*(const GAS u32x4*)(zb + off + bj * HALF), z0, z1);
;                     const f32x4 v0 = z0 * sigmoid4(acc[ai][bj][m][0] + bv[bj][0]), v1 = z1 * sigmoid4(acc[ai][bj][m][1] + bv[bj][1]);
;                     *(GAS u32x4*)(sob + off + bj * HALF) = pack8(v0, v1); } }
	v_mov_b32_e32 v140, v188
	v_mov_b32_e32 v141, v189
	v_mov_b32_e32 v142, v190
	v_mov_b32_e32 v143, v191
	global_load_dwordx4 v[188:191], v[242:243], off offset:256
	v_lshlrev_b32_e32 v144, 16, v140
	v_and_b32_e32 v145, 0xffff0000, v140
	v_lshlrev_b32_e32 v140, 16, v141
	v_and_b32_e32 v141, 0xffff0000, v141
	v_lshlrev_b32_e32 v146, 16, v142
	v_and_b32_e32 v147, 0xffff0000, v142
	v_lshlrev_b32_e32 v142, 16, v143
	v_and_b32_e32 v143, 0xffff0000, v143
	v_pk_mul_f32 v[138:139], v[138:139], v[140:141]
	v_pk_mul_f32 v[136:137], v[136:137], v[144:145]
	v_pk_mul_f32 v[140:141], v[134:135], v[142:143]
	v_pk_mul_f32 v[134:135], v[132:133], v[146:147]
	v_cvt_pk_bf16_f32 v132, v136, v137
	v_cvt_pk_bf16_f32 v133, v138, v139
	v_cvt_pk_bf16_f32 v134, v134, v135
	v_cvt_pk_bf16_f32 v135, v140, v141
	global_store_dwordx4 v[160:161], v[132:135], off offset:256
	v_rcp_f32_e32 v123, v123
	v_rcp_f32_e32 v116, v116
	v_add_co_u32_e32 v132, vcc, s94, v162
	v_rcp_f32_e32 v117, v117
	s_nop 0
	v_addc_co_u32_e32 v133, vcc, 0, v163, vcc
	v_rcp_f32_e32 v118, v118
	v_rcp_f32_e32 v119, v119
	v_pk_add_f32 v[112:113], v[112:113], v[38:39]
	v_pk_add_f32 v[108:109], v[108:109], v[34:35]
	v_pk_add_f32 v[114:115], v[114:115], v[40:41]
	v_pk_mul_f32 v[112:113], v[112:113], s[74:75] op_sel_hi:[1,0]
	v_pk_add_f32 v[110:111], v[110:111], v[36:37]
	v_pk_mul_f32 v[108:109], v[108:109], s[74:75] op_sel_hi:[1,0]
	v_pk_mul_f32 v[114:115], v[114:115], s[74:75] op_sel_hi:[1,0]
	v_exp_f32_e32 v112, v112
	v_exp_f32_e32 v113, v113
	v_pk_mul_f32 v[110:111], v[110:111], s[74:75] op_sel_hi:[1,0]
	v_exp_f32_e32 v108, v108
	v_exp_f32_e32 v109, v109
	v_exp_f32_e32 v114, v114
	v_exp_f32_e32 v115, v115
	v_exp_f32_e32 v110, v110
	v_exp_f32_e32 v111, v111
	v_pk_add_f32 v[112:113], v[112:113], 1.0 op_sel_hi:[1,0]
	v_pk_add_f32 v[108:109], v[108:109], 1.0 op_sel_hi:[1,0]
	v_pk_add_f32 v[114:115], v[114:115], 1.0 op_sel_hi:[1,0]
	v_rcp_f32_e32 v112, v112
	v_rcp_f32_e32 v113, v113
	v_pk_add_f32 v[110:111], v[110:111], 1.0 op_sel_hi:[1,0]
	v_rcp_f32_e32 v108, v108
	v_rcp_f32_e32 v109, v109
	v_rcp_f32_e32 v114, v114
	v_rcp_f32_e32 v115, v115
	v_rcp_f32_e32 v110, v110
	v_rcp_f32_e32 v111, v111
	v_pk_add_f32 v[106:107], v[106:107], v[24:25]
	v_pk_add_f32 v[104:105], v[104:105], v[22:23]
	v_pk_add_f32 v[102:103], v[102:103], v[16:17]
	v_pk_add_f32 v[100:101], v[100:101], v[14:15]
	v_pk_mul_f32 v[104:105], v[104:105], s[74:75] op_sel_hi:[1,0]
	v_pk_mul_f32 v[106:107], v[106:107], s[74:75] op_sel_hi:[1,0]
	v_pk_mul_f32 v[100:101], v[100:101], s[74:75] op_sel_hi:[1,0]
	v_pk_mul_f32 v[102:103], v[102:103], s[74:75] op_sel_hi:[1,0]
	v_exp_f32_e32 v104, v104
	v_exp_f32_e32 v105, v105
	v_exp_f32_e32 v106, v106
	v_exp_f32_e32 v107, v107
	v_exp_f32_e32 v100, v100
	v_exp_f32_e32 v101, v101
	v_exp_f32_e32 v102, v102
	v_exp_f32_e32 v103, v103
	v_pk_add_f32 v[104:105], v[104:105], 1.0 op_sel_hi:[1,0]
	v_pk_add_f32 v[106:107], v[106:107], 1.0 op_sel_hi:[1,0]
	v_pk_add_f32 v[100:101], v[100:101], 1.0 op_sel_hi:[1,0]
	v_pk_add_f32 v[102:103], v[102:103], 1.0 op_sel_hi:[1,0]
	v_rcp_f32_e32 v104, v104
	v_rcp_f32_e32 v105, v105
	v_rcp_f32_e32 v106, v106
	v_rcp_f32_e32 v107, v107
	v_rcp_f32_e32 v100, v100
	v_rcp_f32_e32 v101, v101
	v_rcp_f32_e32 v102, v102
	v_rcp_f32_e32 v103, v103
	v_pk_add_f32 v[94:95], v[94:95], v[38:39]
	v_pk_add_f32 v[90:91], v[90:91], v[34:35]
	v_pk_add_f32 v[96:97], v[96:97], v[40:41]
	v_pk_mul_f32 v[94:95], v[94:95], s[74:75] op_sel_hi:[1,0]
	v_pk_add_f32 v[92:93], v[92:93], v[36:37]
	v_pk_mul_f32 v[90:91], v[90:91], s[74:75] op_sel_hi:[1,0]
	v_pk_mul_f32 v[96:97], v[96:97], s[74:75] op_sel_hi:[1,0]
	v_exp_f32_e32 v94, v94
	v_exp_f32_e32 v95, v95
	v_pk_mul_f32 v[92:93], v[92:93], s[74:75] op_sel_hi:[1,0]
	v_exp_f32_e32 v90, v90
	v_exp_f32_e32 v91, v91
	v_exp_f32_e32 v96, v96
	v_exp_f32_e32 v97, v97
	v_exp_f32_e32 v92, v92
	v_exp_f32_e32 v93, v93
	v_pk_add_f32 v[94:95], v[94:95], 1.0 op_sel_hi:[1,0]
	v_pk_add_f32 v[90:91], v[90:91], 1.0 op_sel_hi:[1,0]
	v_pk_add_f32 v[96:97], v[96:97], 1.0 op_sel_hi:[1,0]
	v_rcp_f32_e32 v94, v94
	v_rcp_f32_e32 v95, v95
	s_waitcnt vmcnt(11)
	v_mov_b32_e32 v134, v192
	v_mov_b32_e32 v135, v193
	v_mov_b32_e32 v136, v194
	v_mov_b32_e32 v137, v195
	v_add_co_u32_e32 v242, vcc, s51, v162
	v_addc_co_u32_e32 v243, vcc, 0, v163, vcc
	global_load_dwordx4 v[192:195], v[242:243], off
	v_lshlrev_b32_e32 v138, 16, v134
	v_and_b32_e32 v139, 0xffff0000, v134
	v_lshlrev_b32_e32 v140, 16, v136
	v_and_b32_e32 v141, 0xffff0000, v136
	v_lshlrev_b32_e32 v134, 16, v135
	v_and_b32_e32 v135, 0xffff0000, v135
	v_lshlrev_b32_e32 v136, 16, v137
	v_and_b32_e32 v137, 0xffff0000, v137
	v_pk_mul_f32 v[128:129], v[128:129], v[138:139]
	v_pk_mul_f32 v[124:125], v[124:125], v[140:141]
	v_pk_mul_f32 v[130:131], v[130:131], v[134:135]
	v_pk_mul_f32 v[134:135], v[126:127], v[136:137]
	v_cvt_pk_bf16_f32 v126, v128, v129
	v_cvt_pk_bf16_f32 v128, v124, v125
	v_add_co_u32_e32 v124, vcc, s94, v160
	v_cvt_pk_bf16_f32 v127, v130, v131
	v_cvt_pk_bf16_f32 v129, v134, v135
	v_addc_co_u32_e32 v125, vcc, 0, v161, vcc
	global_store_dwordx4 v[124:125], v[126:129], off
	v_pk_add_f32 v[92:93], v[92:93], 1.0 op_sel_hi:[1,0]
	v_rcp_f32_e32 v90, v90
	v_rcp_f32_e32 v91, v91
	v_rcp_f32_e32 v96, v96
	v_rcp_f32_e32 v97, v97
	v_rcp_f32_e32 v92, v92
	v_rcp_f32_e32 v93, v93
	v_pk_add_f32 v[88:89], v[88:89], v[24:25]
	v_pk_add_f32 v[86:87], v[86:87], v[22:23]
	v_pk_add_f32 v[84:85], v[84:85], v[16:17]
	v_pk_add_f32 v[82:83], v[82:83], v[14:15]
	v_pk_mul_f32 v[86:87], v[86:87], s[74:75] op_sel_hi:[1,0]
	v_pk_mul_f32 v[88:89], v[88:89], s[74:75] op_sel_hi:[1,0]
	v_pk_mul_f32 v[82:83], v[82:83], s[74:75] op_sel_hi:[1,0]
; #define GAS __attribute__((address_space(1)))
; __device__ __forceinline__ unsigned cvt_pk_bf16(float lo, float hi) { typedef float f32x2_l __attribute__((ext_vector_type(2))); const bf16x2_native b = __builtin_convertvector((f32x2_l){lo, hi}, bf16x2_native); return __builtin_bit_cast(unsigned, b); }
; __device__ __forceinline__ void unpack8(u32x4 w, f32x4& v0, f32x4& v1) { v0 = (f32x4){bflo(w.x), bfhi(w.x), bflo(w.y), bfhi(w.y)}; v1 = (f32x4){bflo(w.z), bfhi(w.z), bflo(w.w), bfhi(w.w)}; }
; #define GAS __attribute__((address_space(1)))
; __device__ __forceinline__ f32x4 sigmoid4(f32x4 v) {
;     const f32x2 t0 = (f32x2){v[0], v[1]} * -1.4426950408889634f, t1 = (f32x2){v[2], v[3]} * -1.4426950408889634f;
;     const f32x2 d0 = (f32x2){__builtin_amdgcn_exp2f(t0.x), __builtin_amdgcn_exp2f(t0.y)} + 1.0f, d1 = (f32x2){__builtin_amdgcn_exp2f(t1.x), __builtin_amdgcn_exp2f(t1.y)} + 1.0f;
;     return (f32x4){__builtin_amdgcn_rcpf(d0.x), __builtin_amdgcn_rcpf(d0.y), __builtin_amdgcn_rcpf(d1.x), __builtin_amdgcn_rcpf(d1.y)}; }
; __device__ __forceinline__ u32x4 pack8(f32x4 v0, f32x4 v1) { u32x4 w; w.x = cvt_pk_bf16(v0[0], v0[1]); w.y = cvt_pk_bf16(v0[2], v0[3]); w.z = cvt_pk_bf16(v1[0], v1[1]); w.w = cvt_pk_bf16(v1[2], v1[3]); return w; }
;     __device__ __forceinline__ void operator()(const f32x4 (&acc)[2][2][4][2], const Unit& u, int wr, int wc, int fr, int fq) const {
;     ...
;             for (int n = 0; n < 2; ++n) bv[bj][n] = *(const f32x4*)(bglu + col0 + bj * HALF + 4 * n);
;         const bf16_t* const zb = Z + (size_t)row0 * 1024 + col0; bf16_t* const sob = SO + (size_t)row0 * 1024 + col0;
; #pragma unroll
;         for (int ai = 0; ai < 2; ++ai)
; #pragma unroll
;             for (int m = 0; m < 4; ++m) { const size_t off = (size_t)(ai * HALF + m * 16) * 1024;
; #pragma unroll
;                 for (int bj = 0; bj < 2; ++bj) { f32x4 z0, z1; unpack8(*(const GAS u32x4*)(zb + off + bj * HALF), z0, z1);
;                     const f32x4 v0 = z0 * sigmoid4(acc[ai][bj][m][0] + bv[bj][0]), v1 = z1 * sigmoid4(acc[ai][bj][m][1] + bv[bj][1]);
;                     *(GAS u32x4*)(sob + off + bj * HALF) = pack8(v0, v1); } }
	v_pk_mul_f32 v[84:85], v[84:85], s[74:75] op_sel_hi:[1,0]
	v_exp_f32_e32 v86, v86
	v_exp_f32_e32 v87, v87
	v_exp_f32_e32 v88, v88
	v_exp_f32_e32 v89, v89
	v_exp_f32_e32 v82, v82
	v_exp_f32_e32 v83, v83
	v_exp_f32_e32 v84, v84
	v_exp_f32_e32 v85, v85
	v_pk_add_f32 v[86:87], v[86:87], 1.0 op_sel_hi:[1,0]
	v_pk_add_f32 v[88:89], v[88:89], 1.0 op_sel_hi:[1,0]
	v_pk_add_f32 v[82:83], v[82:83], 1.0 op_sel_hi:[1,0]
	v_pk_add_f32 v[84:85], v[84:85], 1.0 op_sel_hi:[1,0]
	v_rcp_f32_e32 v86, v86
	v_rcp_f32_e32 v87, v87
	v_rcp_f32_e32 v88, v88
	v_rcp_f32_e32 v89, v89
	v_rcp_f32_e32 v82, v82
	v_rcp_f32_e32 v83, v83
	v_rcp_f32_e32 v84, v84
	v_rcp_f32_e32 v85, v85
	v_pk_add_f32 v[78:79], v[78:79], v[38:39]
	v_pk_add_f32 v[74:75], v[74:75], v[34:35]
	v_pk_add_f32 v[80:81], v[80:81], v[40:41]
	v_pk_mul_f32 v[78:79], v[78:79], s[74:75] op_sel_hi:[1,0]
	v_pk_add_f32 v[76:77], v[76:77], v[36:37]
	v_pk_mul_f32 v[74:75], v[74:75], s[74:75] op_sel_hi:[1,0]
	v_pk_mul_f32 v[80:81], v[80:81], s[74:75] op_sel_hi:[1,0]
	v_exp_f32_e32 v78, v78
	v_exp_f32_e32 v79, v79
	v_pk_mul_f32 v[76:77], v[76:77], s[74:75] op_sel_hi:[1,0]
	v_exp_f32_e32 v74, v74
	v_exp_f32_e32 v75, v75
	v_exp_f32_e32 v80, v80
	v_exp_f32_e32 v81, v81
	v_exp_f32_e32 v76, v76
	v_exp_f32_e32 v77, v77
	v_pk_add_f32 v[78:79], v[78:79], 1.0 op_sel_hi:[1,0]
	v_pk_add_f32 v[74:75], v[74:75], 1.0 op_sel_hi:[1,0]
	v_pk_add_f32 v[80:81], v[80:81], 1.0 op_sel_hi:[1,0]
	v_rcp_f32_e32 v78, v78
	v_rcp_f32_e32 v79, v79
	v_pk_add_f32 v[76:77], v[76:77], 1.0 op_sel_hi:[1,0]
	v_rcp_f32_e32 v74, v74
	v_rcp_f32_e32 v75, v75
	v_rcp_f32_e32 v80, v80
	v_rcp_f32_e32 v81, v81
	v_rcp_f32_e32 v76, v76
	v_rcp_f32_e32 v77, v77
	v_pk_add_f32 v[72:73], v[72:73], v[24:25]
	v_pk_add_f32 v[70:71], v[70:71], v[22:23]
	v_pk_add_f32 v[68:69], v[68:69], v[16:17]
	v_pk_add_f32 v[66:67], v[66:67], v[14:15]
	v_pk_mul_f32 v[70:71], v[70:71], s[74:75] op_sel_hi:[1,0]
	v_pk_mul_f32 v[72:73], v[72:73], s[74:75] op_sel_hi:[1,0]
	v_pk_mul_f32 v[66:67], v[66:67], s[74:75] op_sel_hi:[1,0]
	v_pk_mul_f32 v[68:69], v[68:69], s[74:75] op_sel_hi:[1,0]
	v_exp_f32_e32 v70, v70
	v_exp_f32_e32 v71, v71
	v_exp_f32_e32 v72, v72
	v_exp_f32_e32 v73, v73
	v_exp_f32_e32 v66, v66
	v_exp_f32_e32 v67, v67
	v_exp_f32_e32 v68, v68
	v_exp_f32_e32 v69, v69
	s_waitcnt vmcnt(12)
	v_mov_b32_e32 v126, v196
	v_mov_b32_e32 v127, v197
	v_mov_b32_e32 v128, v198
	v_mov_b32_e32 v129, v199
	global_load_dwordx4 v[196:199], v[242:243], off offset:256
	v_lshlrev_b32_e32 v130, 16, v126
	v_and_b32_e32 v131, 0xffff0000, v126
	v_lshlrev_b32_e32 v126, 16, v127
	v_and_b32_e32 v127, 0xffff0000, v127
	v_lshlrev_b32_e32 v132, 16, v128
	v_and_b32_e32 v133, 0xffff0000, v128
	v_lshlrev_b32_e32 v128, 16, v129
	v_and_b32_e32 v129, 0xffff0000, v129
	v_pk_mul_f32 v[122:123], v[122:123], v[126:127]
	v_pk_mul_f32 v[120:121], v[120:121], v[130:131]
	v_pk_mul_f32 v[126:127], v[118:119], v[128:129]
	v_pk_mul_f32 v[118:119], v[116:117], v[132:133]
	v_cvt_pk_bf16_f32 v116, v120, v121
	v_cvt_pk_bf16_f32 v117, v122, v123
	v_cvt_pk_bf16_f32 v118, v118, v119
	v_cvt_pk_bf16_f32 v119, v126, v127
	global_store_dwordx4 v[124:125], v[116:119], off offset:256
	v_pk_add_f32 v[70:71], v[70:71], 1.0 op_sel_hi:[1,0]
	v_pk_add_f32 v[72:73], v[72:73], 1.0 op_sel_hi:[1,0]
	v_add_co_u32_e32 v116, vcc, s73, v162
	v_pk_add_f32 v[66:67], v[66:67], 1.0 op_sel_hi:[1,0]
	s_nop 0
	v_addc_co_u32_e32 v117, vcc, 0, v163, vcc
	v_pk_add_f32 v[68:69], v[68:69], 1.0 op_sel_hi:[1,0]
	v_rcp_f32_e32 v70, v70
	v_rcp_f32_e32 v71, v71
	v_rcp_f32_e32 v72, v72
	v_rcp_f32_e32 v73, v73
	v_rcp_f32_e32 v66, v66
	v_rcp_f32_e32 v67, v67
	v_rcp_f32_e32 v68, v68
	v_rcp_f32_e32 v69, v69
	v_pk_add_f32 v[62:63], v[62:63], v[38:39]
	v_pk_add_f32 v[58:59], v[58:59], v[34:35]
	v_pk_add_f32 v[64:65], v[64:65], v[40:41]
	v_pk_mul_f32 v[62:63], v[62:63], s[74:75] op_sel_hi:[1,0]
	v_pk_add_f32 v[60:61], v[60:61], v[36:37]
	v_pk_mul_f32 v[58:59], v[58:59], s[74:75] op_sel_hi:[1,0]
	v_pk_mul_f32 v[64:65], v[64:65], s[74:75] op_sel_hi:[1,0]
	v_exp_f32_e32 v62, v62
	v_exp_f32_e32 v63, v63
	v_pk_mul_f32 v[60:61], v[60:61], s[74:75] op_sel_hi:[1,0]
	v_exp_f32_e32 v58, v58
	v_exp_f32_e32 v59, v59
	v_exp_f32_e32 v64, v64
	v_exp_f32_e32 v65, v65
	v_exp_f32_e32 v60, v60
	v_exp_f32_e32 v61, v61
	v_pk_add_f32 v[62:63], v[62:63], 1.0 op_sel_hi:[1,0]
	v_pk_add_f32 v[58:59], v[58:59], 1.0 op_sel_hi:[1,0]
	v_pk_add_f32 v[64:65], v[64:65], 1.0 op_sel_hi:[1,0]
	v_rcp_f32_e32 v62, v62
	v_rcp_f32_e32 v63, v63
	v_pk_add_f32 v[60:61], v[60:61], 1.0 op_sel_hi:[1,0]
	v_rcp_f32_e32 v58, v58
	v_rcp_f32_e32 v59, v59
	v_rcp_f32_e32 v64, v64
	v_rcp_f32_e32 v65, v65
	v_rcp_f32_e32 v60, v60
	v_rcp_f32_e32 v61, v61
	v_pk_add_f32 v[56:57], v[56:57], v[24:25]
	v_pk_add_f32 v[54:55], v[54:55], v[22:23]
	v_pk_add_f32 v[52:53], v[52:53], v[16:17]
	v_pk_add_f32 v[50:51], v[50:51], v[14:15]
	v_pk_mul_f32 v[54:55], v[54:55], s[74:75] op_sel_hi:[1,0]
	v_pk_mul_f32 v[56:57], v[56:57], s[74:75] op_sel_hi:[1,0]
	v_pk_mul_f32 v[50:51], v[50:51], s[74:75] op_sel_hi:[1,0]
	v_pk_mul_f32 v[52:53], v[52:53], s[74:75] op_sel_hi:[1,0]
	v_exp_f32_e32 v54, v54
	v_exp_f32_e32 v55, v55
	v_exp_f32_e32 v56, v56
	v_exp_f32_e32 v57, v57
	v_exp_f32_e32 v50, v50
	v_exp_f32_e32 v51, v51
	v_exp_f32_e32 v52, v52
	v_exp_f32_e32 v53, v53
	v_pk_add_f32 v[54:55], v[54:55], 1.0 op_sel_hi:[1,0]
	v_pk_add_f32 v[56:57], v[56:57], 1.0 op_sel_hi:[1,0]
	v_pk_add_f32 v[50:51], v[50:51], 1.0 op_sel_hi:[1,0]
	v_pk_add_f32 v[52:53], v[52:53], 1.0 op_sel_hi:[1,0]
	v_rcp_f32_e32 v54, v54
	v_rcp_f32_e32 v55, v55
	v_rcp_f32_e32 v56, v56
	v_rcp_f32_e32 v57, v57
	v_rcp_f32_e32 v50, v50
	v_rcp_f32_e32 v51, v51
	v_rcp_f32_e32 v52, v52
	v_rcp_f32_e32 v53, v53
	v_pk_add_f32 v[46:47], v[46:47], v[38:39]
	v_pk_add_f32 v[42:43], v[42:43], v[34:35]
	v_pk_add_f32 v[48:49], v[48:49], v[40:41]
	v_pk_mul_f32 v[46:47], v[46:47], s[74:75] op_sel_hi:[1,0]
	v_pk_add_f32 v[44:45], v[44:45], v[36:37]
	v_pk_mul_f32 v[42:43], v[42:43], s[74:75] op_sel_hi:[1,0]
	v_pk_mul_f32 v[48:49], v[48:49], s[74:75] op_sel_hi:[1,0]
	v_exp_f32_e32 v46, v46
	v_exp_f32_e32 v47, v47
	v_pk_mul_f32 v[44:45], v[44:45], s[74:75] op_sel_hi:[1,0]
	v_exp_f32_e32 v42, v42
	v_exp_f32_e32 v43, v43
	v_exp_f32_e32 v48, v48
	v_exp_f32_e32 v49, v49
	s_waitcnt vmcnt(13)
; #define GAS __attribute__((address_space(1)))
; __device__ __forceinline__ unsigned cvt_pk_bf16(float lo, float hi) { typedef float f32x2_l __attribute__((ext_vector_type(2))); const bf16x2_native b = __builtin_convertvector((f32x2_l){lo, hi}, bf16x2_native); return __builtin_bit_cast(unsigned, b); }
; __device__ __forceinline__ void unpack8(u32x4 w, f32x4& v0, f32x4& v1) { v0 = (f32x4){bflo(w.x), bfhi(w.x), bflo(w.y), bfhi(w.y)}; v1 = (f32x4){bflo(w.z), bfhi(w.z), bflo(w.w), bfhi(w.w)}; }
; #define GAS __attribute__((address_space(1)))
; __device__ __forceinline__ f32x4 sigmoid4(f32x4 v) {
;     const f32x2 t0 = (f32x2){v[0], v[1]} * -1.4426950408889634f, t1 = (f32x2){v[2], v[3]} * -1.4426950408889634f;
;     const f32x2 d0 = (f32x2){__builtin_amdgcn_exp2f(t0.x), __builtin_amdgcn_exp2f(t0.y)} + 1.0f, d1 = (f32x2){__builtin_amdgcn_exp2f(t1.x), __builtin_amdgcn_exp2f(t1.y)} + 1.0f;
;     return (f32x4){__builtin_amdgcn_rcpf(d0.x), __builtin_amdgcn_rcpf(d0.y), __builtin_amdgcn_rcpf(d1.x), __builtin_amdgcn_rcpf(d1.y)}; }
; __device__ __forceinline__ u32x4 pack8(f32x4 v0, f32x4 v1) { u32x4 w; w.x = cvt_pk_bf16(v0[0], v0[1]); w.y = cvt_pk_bf16(v0[2], v0[3]); w.z = cvt_pk_bf16(v1[0], v1[1]); w.w = cvt_pk_bf16(v1[2], v1[3]); return w; }
;     __device__ __forceinline__ void operator()(const f32x4 (&acc)[2][2][4][2], const Unit& u, int wr, int wc, int fr, int fq) const {
;     ...
;             for (int n = 0; n < 2; ++n) bv[bj][n] = *(const f32x4*)(bglu + col0 + bj * HALF + 4 * n);
;         const bf16_t* const zb = Z + (size_t)row0 * 1024 + col0; bf16_t* const sob = SO + (size_t)row0 * 1024 + col0;
; #pragma unroll
;         for (int ai = 0; ai < 2; ++ai)
; #pragma unroll
;             for (int m = 0; m < 4; ++m) { const size_t off = (size_t)(ai * HALF + m * 16) * 1024;
; #pragma unroll
;                 for (int bj = 0; bj < 2; ++bj) { f32x4 z0, z1; unpack8(*(const GAS u32x4*)(zb + off + bj * HALF), z0, z1);
;                     const f32x4 v0 = z0 * sigmoid4(acc[ai][bj][m][0] + bv[bj][0]), v1 = z1 * sigmoid4(acc[ai][bj][m][1] + bv[bj][1]);
;                     *(GAS u32x4*)(sob + off + bj * HALF) = pack8(v0, v1); } }
	v_mov_b32_e32 v118, v200
	v_mov_b32_e32 v119, v201
	v_mov_b32_e32 v120, v202
	v_mov_b32_e32 v121, v203
	v_add_co_u32_e32 v242, vcc, s66, v162
	v_addc_co_u32_e32 v243, vcc, 0, v163, vcc
	global_load_dwordx4 v[200:203], v[242:243], off
	v_lshlrev_b32_e32 v122, 16, v118
	v_and_b32_e32 v123, 0xffff0000, v118
	v_lshlrev_b32_e32 v124, 16, v120
	v_and_b32_e32 v125, 0xffff0000, v120
	v_lshlrev_b32_e32 v118, 16, v119
	v_and_b32_e32 v119, 0xffff0000, v119
	v_lshlrev_b32_e32 v120, 16, v121
	v_and_b32_e32 v121, 0xffff0000, v121
	v_pk_mul_f32 v[112:113], v[112:113], v[122:123]
	v_pk_mul_f32 v[108:109], v[108:109], v[124:125]
	v_pk_mul_f32 v[114:115], v[114:115], v[118:119]
	v_pk_mul_f32 v[118:119], v[110:111], v[120:121]
	v_cvt_pk_bf16_f32 v110, v112, v113
	v_cvt_pk_bf16_f32 v112, v108, v109
	v_add_co_u32_e32 v108, vcc, s73, v160
	v_cvt_pk_bf16_f32 v111, v114, v115
	v_cvt_pk_bf16_f32 v113, v118, v119
	v_addc_co_u32_e32 v109, vcc, 0, v161, vcc
	global_store_dwordx4 v[108:109], v[110:113], off
	v_exp_f32_e32 v44, v44
	v_exp_f32_e32 v45, v45
	v_pk_add_f32 v[46:47], v[46:47], 1.0 op_sel_hi:[1,0]
	v_pk_add_f32 v[42:43], v[42:43], 1.0 op_sel_hi:[1,0]
	v_pk_add_f32 v[48:49], v[48:49], 1.0 op_sel_hi:[1,0]
	v_rcp_f32_e32 v46, v46
	v_rcp_f32_e32 v47, v47
	v_pk_add_f32 v[44:45], v[44:45], 1.0 op_sel_hi:[1,0]
	v_rcp_f32_e32 v42, v42
	v_rcp_f32_e32 v43, v43
	v_rcp_f32_e32 v48, v48
	v_rcp_f32_e32 v49, v49
	v_rcp_f32_e32 v44, v44
	v_rcp_f32_e32 v45, v45
	v_pk_add_f32 v[32:33], v[32:33], v[24:25]
	v_pk_add_f32 v[30:31], v[30:31], v[22:23]
	v_pk_add_f32 v[28:29], v[28:29], v[16:17]
	v_pk_add_f32 v[26:27], v[26:27], v[14:15]
	v_pk_mul_f32 v[30:31], v[30:31], s[74:75] op_sel_hi:[1,0]
	v_pk_mul_f32 v[32:33], v[32:33], s[74:75] op_sel_hi:[1,0]
	v_pk_mul_f32 v[26:27], v[26:27], s[74:75] op_sel_hi:[1,0]
	v_pk_mul_f32 v[28:29], v[28:29], s[74:75] op_sel_hi:[1,0]
	v_exp_f32_e32 v30, v30
	v_exp_f32_e32 v31, v31
	v_exp_f32_e32 v32, v32
	v_exp_f32_e32 v33, v33
	v_exp_f32_e32 v26, v26
	v_exp_f32_e32 v27, v27
	v_exp_f32_e32 v28, v28
	v_exp_f32_e32 v29, v29
	v_pk_add_f32 v[30:31], v[30:31], 1.0 op_sel_hi:[1,0]
	v_pk_add_f32 v[32:33], v[32:33], 1.0 op_sel_hi:[1,0]
	v_pk_add_f32 v[26:27], v[26:27], 1.0 op_sel_hi:[1,0]
	v_pk_add_f32 v[28:29], v[28:29], 1.0 op_sel_hi:[1,0]
	v_rcp_f32_e32 v30, v30
	v_rcp_f32_e32 v31, v31
	v_rcp_f32_e32 v32, v32
	v_rcp_f32_e32 v33, v33
	v_rcp_f32_e32 v26, v26
	v_rcp_f32_e32 v27, v27
	v_rcp_f32_e32 v28, v28
	v_rcp_f32_e32 v29, v29
	v_pk_add_f32 v[18:19], v[18:19], v[38:39]
	v_pk_add_f32 v[20:21], v[20:21], v[40:41]
	v_pk_mul_f32 v[18:19], v[18:19], s[74:75] op_sel_hi:[1,0]
	v_pk_add_f32 v[12:13], v[12:13], v[36:37]
	v_pk_add_f32 v[10:11], v[10:11], v[34:35]
	v_pk_mul_f32 v[20:21], v[20:21], s[74:75] op_sel_hi:[1,0]
	v_exp_f32_e32 v18, v18
	v_exp_f32_e32 v19, v19
	v_pk_mul_f32 v[10:11], v[10:11], s[74:75] op_sel_hi:[1,0]
	v_pk_mul_f32 v[12:13], v[12:13], s[74:75] op_sel_hi:[1,0]
	v_exp_f32_e32 v20, v20
	v_exp_f32_e32 v21, v21
	v_exp_f32_e32 v10, v10
	v_exp_f32_e32 v11, v11
	v_exp_f32_e32 v12, v12
	v_exp_f32_e32 v13, v13
	v_pk_add_f32 v[18:19], v[18:19], 1.0 op_sel_hi:[1,0]
	v_pk_add_f32 v[20:21], v[20:21], 1.0 op_sel_hi:[1,0]
	v_rcp_f32_e32 v18, v18
	v_rcp_f32_e32 v19, v19
	v_pk_add_f32 v[10:11], v[10:11], 1.0 op_sel_hi:[1,0]
	v_pk_add_f32 v[12:13], v[12:13], 1.0 op_sel_hi:[1,0]
	v_rcp_f32_e32 v20, v20
	v_rcp_f32_e32 v21, v21
	v_rcp_f32_e32 v10, v10
	v_rcp_f32_e32 v11, v11
	v_rcp_f32_e32 v12, v12
	v_rcp_f32_e32 v13, v13
	v_pk_add_f32 v[8:9], v[8:9], v[24:25]
	v_pk_add_f32 v[6:7], v[6:7], v[22:23]
	v_pk_add_f32 v[4:5], v[4:5], v[16:17]
	v_pk_add_f32 v[2:3], v[2:3], v[14:15]
	v_pk_mul_f32 v[6:7], v[6:7], s[74:75] op_sel_hi:[1,0]
	v_pk_mul_f32 v[8:9], v[8:9], s[74:75] op_sel_hi:[1,0]
	v_pk_mul_f32 v[2:3], v[2:3], s[74:75] op_sel_hi:[1,0]
	v_pk_mul_f32 v[4:5], v[4:5], s[74:75] op_sel_hi:[1,0]
	v_exp_f32_e32 v6, v6
	s_waitcnt vmcnt(14)
	v_mov_b32_e32 v110, v222
	v_mov_b32_e32 v111, v223
	v_mov_b32_e32 v112, v224
	v_mov_b32_e32 v113, v225
	global_load_dwordx4 v[222:225], v[242:243], off offset:256
	v_lshlrev_b32_e32 v114, 16, v110
	v_and_b32_e32 v115, 0xffff0000, v110
	v_lshlrev_b32_e32 v110, 16, v111
	v_and_b32_e32 v111, 0xffff0000, v111
	v_lshlrev_b32_e32 v116, 16, v112
	v_and_b32_e32 v117, 0xffff0000, v112
	v_lshlrev_b32_e32 v112, 16, v113
	v_and_b32_e32 v113, 0xffff0000, v113
	v_pk_mul_f32 v[106:107], v[106:107], v[110:111]
	v_pk_mul_f32 v[104:105], v[104:105], v[114:115]
	v_pk_mul_f32 v[110:111], v[102:103], v[112:113]
	v_pk_mul_f32 v[102:103], v[100:101], v[116:117]
	v_cvt_pk_bf16_f32 v100, v104, v105
	v_cvt_pk_bf16_f32 v101, v106, v107
	v_cvt_pk_bf16_f32 v102, v102, v103
	v_cvt_pk_bf16_f32 v103, v110, v111
	global_store_dwordx4 v[108:109], v[100:103], off offset:256
	v_exp_f32_e32 v7, v7
	v_exp_f32_e32 v8, v8
	v_add_co_u32_e32 v100, vcc, s93, v162
	v_exp_f32_e32 v9, v9
	s_nop 0
	v_addc_co_u32_e32 v101, vcc, 0, v163, vcc
	v_exp_f32_e32 v2, v2
	v_exp_f32_e32 v3, v3
	v_exp_f32_e32 v4, v4
	v_exp_f32_e32 v5, v5
	v_pk_add_f32 v[6:7], v[6:7], 1.0 op_sel_hi:[1,0]
	v_pk_add_f32 v[8:9], v[8:9], 1.0 op_sel_hi:[1,0]
	v_pk_add_f32 v[2:3], v[2:3], 1.0 op_sel_hi:[1,0]
	v_pk_add_f32 v[4:5], v[4:5], 1.0 op_sel_hi:[1,0]
	v_rcp_f32_e32 v6, v6
	v_rcp_f32_e32 v7, v7
	v_rcp_f32_e32 v8, v8
	v_rcp_f32_e32 v9, v9
	v_rcp_f32_e32 v2, v2
	v_rcp_f32_e32 v3, v3
	v_rcp_f32_e32 v4, v4
	v_rcp_f32_e32 v5, v5
	s_waitcnt vmcnt(15)
; #define GAS __attribute__((address_space(1)))
; __device__ __forceinline__ u32x4 pack8(f32x4 v0, f32x4 v1) { u32x4 w; w.x = cvt_pk_bf16(v0[0], v0[1]); w.y = cvt_pk_bf16(v0[2], v0[3]); w.z = cvt_pk_bf16(v1[0], v1[1]); w.w = cvt_pk_bf16(v1[2], v1[3]); return w; }
; __device__ __forceinline__ void unpack8(u32x4 w, f32x4& v0, f32x4& v1) { v0 = (f32x4){bflo(w.x), bfhi(w.x), bflo(w.y), bfhi(w.y)}; v1 = (f32x4){bflo(w.z), bfhi(w.z), bflo(w.w), bfhi(w.w)}; }
; #define GAS __attribute__((address_space(1)))
;     __device__ __forceinline__ void operator()(const f32x4 (&acc)[2][2][4][2], const Unit& u, int wr, int wc, int fr, int fq) const {
;     ...
;         const bf16_t* const zb = Z + (size_t)row0 * 1024 + col0; bf16_t* const sob = SO + (size_t)row0 * 1024 + col0;
; #pragma unroll
;         for (int ai = 0; ai < 2; ++ai)
; #pragma unroll
;             for (int m = 0; m < 4; ++m) { const size_t off = (size_t)(ai * HALF + m * 16) * 1024;
; #pragma unroll
;                 for (int bj = 0; bj < 2; ++bj) { f32x4 z0, z1; unpack8(*(const GAS u32x4*)(zb + off + bj * HALF), z0, z1);
;                     const f32x4 v0 = z0 * sigmoid4(acc[ai][bj][m][0] + bv[bj][0]), v1 = z1 * sigmoid4(acc[ai][bj][m][1] + bv[bj][1]);
;                     *(GAS u32x4*)(sob + off + bj * HALF) = pack8(v0, v1); } }
	v_mov_b32_e32 v102, v226
	v_mov_b32_e32 v103, v227
	v_mov_b32_e32 v104, v228
	v_mov_b32_e32 v105, v229
	v_lshlrev_b32_e32 v106, 16, v102
	v_and_b32_e32 v107, 0xffff0000, v102
	v_lshlrev_b32_e32 v108, 16, v104
	v_and_b32_e32 v109, 0xffff0000, v104
	v_lshlrev_b32_e32 v102, 16, v103
	v_and_b32_e32 v103, 0xffff0000, v103
	v_lshlrev_b32_e32 v104, 16, v105
	v_and_b32_e32 v105, 0xffff0000, v105
	v_pk_mul_f32 v[94:95], v[94:95], v[106:107]
	v_pk_mul_f32 v[90:91], v[90:91], v[108:109]
	v_pk_mul_f32 v[96:97], v[96:97], v[102:103]
	v_pk_mul_f32 v[102:103], v[92:93], v[104:105]
	v_cvt_pk_bf16_f32 v92, v94, v95
	v_cvt_pk_bf16_f32 v94, v90, v91
	v_add_co_u32_e32 v90, vcc, s93, v160
	v_cvt_pk_bf16_f32 v93, v96, v97
	v_cvt_pk_bf16_f32 v95, v102, v103
	v_addc_co_u32_e32 v91, vcc, 0, v161, vcc
	global_store_dwordx4 v[90:91], v[92:95], off
	s_waitcnt vmcnt(15)
	v_mov_b32_e32 v92, v230
	v_mov_b32_e32 v93, v231
	v_mov_b32_e32 v94, v232
	v_mov_b32_e32 v95, v233
	v_lshlrev_b32_e32 v96, 16, v92
	v_and_b32_e32 v97, 0xffff0000, v92
	v_lshlrev_b32_e32 v92, 16, v93
	v_and_b32_e32 v93, 0xffff0000, v93
	v_lshlrev_b32_e32 v100, 16, v94
	v_and_b32_e32 v101, 0xffff0000, v94
	v_lshlrev_b32_e32 v94, 16, v95
	v_and_b32_e32 v95, 0xffff0000, v95
	v_pk_mul_f32 v[88:89], v[88:89], v[92:93]
	v_pk_mul_f32 v[86:87], v[86:87], v[96:97]
	v_pk_mul_f32 v[92:93], v[84:85], v[94:95]
	v_pk_mul_f32 v[84:85], v[82:83], v[100:101]
	v_cvt_pk_bf16_f32 v82, v86, v87
	v_cvt_pk_bf16_f32 v83, v88, v89
	v_cvt_pk_bf16_f32 v84, v84, v85
	v_cvt_pk_bf16_f32 v85, v92, v93
	global_store_dwordx4 v[90:91], v[82:85], off offset:256
	s_nop 1
	v_add_co_u32_e32 v82, vcc, s49, v162
	s_nop 1
	v_addc_co_u32_e32 v83, vcc, 0, v163, vcc
	s_waitcnt vmcnt(15)
	v_mov_b32_e32 v84, v234
	v_mov_b32_e32 v85, v235
	v_mov_b32_e32 v86, v236
	v_mov_b32_e32 v87, v237
	v_lshlrev_b32_e32 v88, 16, v84
	v_and_b32_e32 v89, 0xffff0000, v84
	v_lshlrev_b32_e32 v90, 16, v86
	v_and_b32_e32 v91, 0xffff0000, v86
	v_lshlrev_b32_e32 v84, 16, v85
	v_and_b32_e32 v85, 0xffff0000, v85
	v_lshlrev_b32_e32 v86, 16, v87
	v_and_b32_e32 v87, 0xffff0000, v87
	v_pk_mul_f32 v[78:79], v[78:79], v[88:89]
	v_pk_mul_f32 v[74:75], v[74:75], v[90:91]
	v_pk_mul_f32 v[80:81], v[80:81], v[84:85]
	v_pk_mul_f32 v[84:85], v[76:77], v[86:87]
	v_cvt_pk_bf16_f32 v76, v78, v79
	v_cvt_pk_bf16_f32 v78, v74, v75
	v_add_co_u32_e32 v74, vcc, s49, v160
	v_cvt_pk_bf16_f32 v77, v80, v81
	v_cvt_pk_bf16_f32 v79, v84, v85
	v_addc_co_u32_e32 v75, vcc, 0, v161, vcc
	global_store_dwordx4 v[74:75], v[76:79], off
	s_waitcnt vmcnt(15)
	v_mov_b32_e32 v76, v238
	v_mov_b32_e32 v77, v239
	v_mov_b32_e32 v78, v240
	v_mov_b32_e32 v79, v241
	v_lshlrev_b32_e32 v80, 16, v76
	v_and_b32_e32 v81, 0xffff0000, v76
	v_lshlrev_b32_e32 v76, 16, v77
	v_and_b32_e32 v77, 0xffff0000, v77
	v_lshlrev_b32_e32 v82, 16, v78
	v_and_b32_e32 v83, 0xffff0000, v78
	v_lshlrev_b32_e32 v78, 16, v79
	v_and_b32_e32 v79, 0xffff0000, v79
	v_pk_mul_f32 v[72:73], v[72:73], v[76:77]
	v_pk_mul_f32 v[70:71], v[70:71], v[80:81]
	v_pk_mul_f32 v[76:77], v[68:69], v[78:79]
	v_pk_mul_f32 v[68:69], v[66:67], v[82:83]
	v_cvt_pk_bf16_f32 v66, v70, v71
	v_cvt_pk_bf16_f32 v67, v72, v73
	v_cvt_pk_bf16_f32 v68, v68, v69
	v_cvt_pk_bf16_f32 v69, v76, v77
	global_store_dwordx4 v[74:75], v[66:69], off offset:256
	s_nop 1
	v_add_co_u32_e32 v66, vcc, s50, v162
	s_nop 1
	v_addc_co_u32_e32 v67, vcc, 0, v163, vcc
	s_waitcnt vmcnt(15)
	v_mov_b32_e32 v68, v184
	v_mov_b32_e32 v69, v185
	v_mov_b32_e32 v70, v186
	v_mov_b32_e32 v71, v187
	v_lshlrev_b32_e32 v72, 16, v68
	v_and_b32_e32 v73, 0xffff0000, v68
	v_lshlrev_b32_e32 v74, 16, v70
	v_and_b32_e32 v75, 0xffff0000, v70
	v_lshlrev_b32_e32 v68, 16, v69
	v_and_b32_e32 v69, 0xffff0000, v69
	v_lshlrev_b32_e32 v70, 16, v71
	v_and_b32_e32 v71, 0xffff0000, v71
	v_pk_mul_f32 v[62:63], v[62:63], v[72:73]
	v_pk_mul_f32 v[58:59], v[58:59], v[74:75]
	v_pk_mul_f32 v[64:65], v[64:65], v[68:69]
	v_pk_mul_f32 v[68:69], v[60:61], v[70:71]
	v_cvt_pk_bf16_f32 v60, v62, v63
	v_cvt_pk_bf16_f32 v62, v58, v59
	v_add_co_u32_e32 v58, vcc, s50, v160
	v_cvt_pk_bf16_f32 v61, v64, v65
	v_cvt_pk_bf16_f32 v63, v68, v69
	v_addc_co_u32_e32 v59, vcc, 0, v161, vcc
	global_store_dwordx4 v[58:59], v[60:63], off
	s_waitcnt vmcnt(14)
; #define GAS __attribute__((address_space(1)))
; __device__ __forceinline__ u32x4 pack8(f32x4 v0, f32x4 v1) { u32x4 w; w.x = cvt_pk_bf16(v0[0], v0[1]); w.y = cvt_pk_bf16(v0[2], v0[3]); w.z = cvt_pk_bf16(v1[0], v1[1]); w.w = cvt_pk_bf16(v1[2], v1[3]); return w; }
; __device__ __forceinline__ void unpack8(u32x4 w, f32x4& v0, f32x4& v1) { v0 = (f32x4){bflo(w.x), bfhi(w.x), bflo(w.y), bfhi(w.y)}; v1 = (f32x4){bflo(w.z), bfhi(w.z), bflo(w.w), bfhi(w.w)}; }
; #define PG8_BAR __builtin_amdgcn_s_barrier()
; #define GAS __attribute__((address_space(1)))
;     __device__ __forceinline__ void operator()(const f32x4 (&acc)[2][2][4][2], const Unit& u, int wr, int wc, int fr, int fq) const {
;     ...
;         const bf16_t* const zb = Z + (size_t)row0 * 1024 + col0; bf16_t* const sob = SO + (size_t)row0 * 1024 + col0;
; #pragma unroll
;         for (int ai = 0; ai < 2; ++ai)
; #pragma unroll
;             for (int m = 0; m < 4; ++m) { const size_t off = (size_t)(ai * HALF + m * 16) * 1024;
; #pragma unroll
;                 for (int bj = 0; bj < 2; ++bj) { f32x4 z0, z1; unpack8(*(const GAS u32x4*)(zb + off + bj * HALF), z0, z1);
;                     const f32x4 v0 = z0 * sigmoid4(acc[ai][bj][m][0] + bv[bj][0]), v1 = z1 * sigmoid4(acc[ai][bj][m][1] + bv[bj][1]);
;                     *(GAS u32x4*)(sob + off + bj * HALF) = pack8(v0, v1); } }
; template <class Epi, class Sched, bool ALIGN_EPI = false, bool SP2 = false>
; __device__ __forceinline__ void gemm_phase(PG8_LAS unsigned char* lds, const Gemm g, const Sched& S, const Epi& E) {
;     ...
;         if (!has_next) break;
; #pragma unroll
;         for (int a = 0; a < 2; ++a)
; #pragma unroll
;             for (int b = 0; b < 2; ++b)
; #pragma unroll
;                 for (int m = 0; m < 4; ++m)
; #pragma unroll
;                     for (int n = 0; n < 2; ++n) acc[a][b][m][n] = (f32x4){0.f, 0.f, 0.f, 0.f};
;         cur = nxt; cA = nA; cB = nB; ++ui;
;         if constexpr (ALIGN_EPI) { if (wr == 1) PG8_BAR; }
;     }
	v_mov_b32_e32 v60, v188
	v_mov_b32_e32 v61, v189
	v_mov_b32_e32 v62, v190
	v_mov_b32_e32 v63, v191
	v_lshlrev_b32_e32 v64, 16, v60
	v_and_b32_e32 v65, 0xffff0000, v60
	v_lshlrev_b32_e32 v60, 16, v61
	v_and_b32_e32 v61, 0xffff0000, v61
	v_lshlrev_b32_e32 v66, 16, v62
	v_and_b32_e32 v67, 0xffff0000, v62
	v_lshlrev_b32_e32 v62, 16, v63
	v_and_b32_e32 v63, 0xffff0000, v63
	v_pk_mul_f32 v[56:57], v[56:57], v[60:61]
	v_pk_mul_f32 v[54:55], v[54:55], v[64:65]
	v_pk_mul_f32 v[60:61], v[52:53], v[62:63]
	v_pk_mul_f32 v[52:53], v[50:51], v[66:67]
	v_cvt_pk_bf16_f32 v50, v54, v55
	v_cvt_pk_bf16_f32 v51, v56, v57
	v_cvt_pk_bf16_f32 v52, v52, v53
	v_cvt_pk_bf16_f32 v53, v60, v61
	global_store_dwordx4 v[58:59], v[50:53], off offset:256
	s_nop 1
	v_add_co_u32_e32 v50, vcc, s51, v162
	s_nop 1
	v_addc_co_u32_e32 v51, vcc, 0, v163, vcc
	s_waitcnt vmcnt(13)
	v_mov_b32_e32 v52, v192
	v_mov_b32_e32 v53, v193
	v_mov_b32_e32 v54, v194
	v_mov_b32_e32 v55, v195
	v_lshlrev_b32_e32 v56, 16, v52
	v_and_b32_e32 v57, 0xffff0000, v52
	v_lshlrev_b32_e32 v58, 16, v54
	v_and_b32_e32 v59, 0xffff0000, v54
	v_lshlrev_b32_e32 v52, 16, v53
	v_and_b32_e32 v53, 0xffff0000, v53
	v_lshlrev_b32_e32 v54, 16, v55
	v_and_b32_e32 v55, 0xffff0000, v55
	v_pk_mul_f32 v[46:47], v[46:47], v[56:57]
	v_pk_mul_f32 v[42:43], v[42:43], v[58:59]
	v_pk_mul_f32 v[48:49], v[48:49], v[52:53]
	v_pk_mul_f32 v[52:53], v[44:45], v[54:55]
	v_cvt_pk_bf16_f32 v44, v46, v47
	v_cvt_pk_bf16_f32 v46, v42, v43
	v_add_co_u32_e32 v42, vcc, s51, v160
	v_cvt_pk_bf16_f32 v45, v48, v49
	v_cvt_pk_bf16_f32 v47, v52, v53
	v_addc_co_u32_e32 v43, vcc, 0, v161, vcc
	global_store_dwordx4 v[42:43], v[44:47], off
	s_waitcnt vmcnt(12)
	v_mov_b32_e32 v44, v196
	v_mov_b32_e32 v45, v197
	v_mov_b32_e32 v46, v198
	v_mov_b32_e32 v47, v199
	v_lshlrev_b32_e32 v48, 16, v44
	v_and_b32_e32 v49, 0xffff0000, v44
	v_lshlrev_b32_e32 v44, 16, v45
	v_and_b32_e32 v45, 0xffff0000, v45
	v_lshlrev_b32_e32 v50, 16, v46
	v_and_b32_e32 v51, 0xffff0000, v46
	v_lshlrev_b32_e32 v46, 16, v47
	v_and_b32_e32 v47, 0xffff0000, v47
	v_pk_mul_f32 v[32:33], v[32:33], v[44:45]
	v_pk_mul_f32 v[30:31], v[30:31], v[48:49]
	v_pk_mul_f32 v[44:45], v[28:29], v[46:47]
	v_pk_mul_f32 v[28:29], v[26:27], v[50:51]
	v_cvt_pk_bf16_f32 v26, v30, v31
	v_cvt_pk_bf16_f32 v27, v32, v33
	v_cvt_pk_bf16_f32 v28, v28, v29
	v_cvt_pk_bf16_f32 v29, v44, v45
	global_store_dwordx4 v[42:43], v[26:29], off offset:256
	s_nop 1
	v_add_co_u32_e32 v26, vcc, s66, v162
	s_nop 1
	v_addc_co_u32_e32 v27, vcc, 0, v163, vcc
	s_waitcnt vmcnt(11)
	v_mov_b32_e32 v28, v200
	v_mov_b32_e32 v29, v201
	v_mov_b32_e32 v30, v202
	v_mov_b32_e32 v31, v203
	v_lshlrev_b32_e32 v32, 16, v28
	v_and_b32_e32 v33, 0xffff0000, v28
	v_lshlrev_b32_e32 v28, 16, v29
	v_and_b32_e32 v29, 0xffff0000, v29
	v_lshlrev_b32_e32 v42, 16, v30
	v_and_b32_e32 v43, 0xffff0000, v30
	v_lshlrev_b32_e32 v30, 16, v31
	v_and_b32_e32 v31, 0xffff0000, v31
	v_pk_mul_f32 v[18:19], v[18:19], v[32:33]
	v_pk_mul_f32 v[20:21], v[20:21], v[28:29]
	v_pk_mul_f32 v[28:29], v[12:13], v[30:31]
	v_pk_mul_f32 v[12:13], v[10:11], v[42:43]
	v_cvt_pk_bf16_f32 v10, v18, v19
	v_add_co_u32_e32 v18, vcc, s66, v160
	v_cvt_pk_bf16_f32 v11, v20, v21
	v_cvt_pk_bf16_f32 v12, v12, v13
	v_cvt_pk_bf16_f32 v13, v28, v29
	v_addc_co_u32_e32 v19, vcc, 0, v161, vcc
	global_store_dwordx4 v[18:19], v[10:13], off
	s_andn2_b64 vcc, exec, s[18:19]
	s_waitcnt vmcnt(10)
	v_mov_b32_e32 v10, v222
	v_mov_b32_e32 v11, v223
	v_mov_b32_e32 v12, v224
	v_mov_b32_e32 v13, v225
	v_lshlrev_b32_e32 v20, 16, v10
	v_and_b32_e32 v21, 0xffff0000, v10
	v_lshlrev_b32_e32 v10, 16, v11
	v_and_b32_e32 v11, 0xffff0000, v11
	v_lshlrev_b32_e32 v26, 16, v12
	v_and_b32_e32 v27, 0xffff0000, v12
	v_lshlrev_b32_e32 v12, 16, v13
	v_and_b32_e32 v13, 0xffff0000, v13
	v_pk_mul_f32 v[8:9], v[8:9], v[10:11]
	v_pk_mul_f32 v[6:7], v[6:7], v[20:21]
	v_pk_mul_f32 v[10:11], v[4:5], v[12:13]
	v_pk_mul_f32 v[4:5], v[2:3], v[26:27]
	v_cvt_pk_bf16_f32 v2, v6, v7
	v_cvt_pk_bf16_f32 v3, v8, v9
	v_cvt_pk_bf16_f32 v4, v4, v5
	v_cvt_pk_bf16_f32 v5, v10, v11
	global_store_dwordx4 v[18:19], v[2:5], off offset:256
	s_cbranch_vccnz .LBB0_923
	s_andn2_b64 vcc, exec, s[6:7]
	s_branch .LBB0_922

; #define PG8_STAGE(bufoff, gbase, voff) do { _Pragma("unroll") for (int _i = 0; _i < 2; ++_i) \
;         __builtin_amdgcn_global_load_lds((const unsigned*)((const char*)(gbase) + (voff)[_i]), (PG8_LAS unsigned*)(lds + (bufoff) + ldsw + _i * 8192), 16, 0, AUX_A); } while (0)
; #define PG8_STAGEB(bufoff, gbase, voff) do { _Pragma("unroll") for (int _i = 0; _i < 2; ++_i) \
;         __builtin_amdgcn_global_load_lds((const unsigned*)((const char*)(gbase) + (voff)[_i]), (PG8_LAS unsigned*)(lds + (bufoff) + ldsw + _i * 8192), 16, 0, AUX_B); } while (0)
; template <class Epi, class Sched, bool ALIGN_EPI = false, bool SP2 = false>
; __device__ __forceinline__ void gemm_phase(PG8_LAS unsigned char* lds, const Gemm g, const Sched& S, const Epi& E) {
;     ...
;     for (int i = 0; i < 2; ++i) { int R, C; stage_rc(tid * 16 + i * 8192, R, C); const int Rb = Epi::PERM ? ((R & ~31) + perm32(R & 31)) : R;
;         voffA[i] = (unsigned)(R * K + C) * 2u; voffB[i] = (unsigned)(Rb * K + C) * 2u; }
;     const size_t kstep = (size_t)(BK * 2);
;     const size_t hstep = (size_t)HALF * K * 2;
;     const size_t tstep = 2 * hstep;
;     const unsigned ldsw = (unsigned)wid * 1024u;
;     const int aoff = lds_byte(wr * 64 + fr, fq * 8), boff = lds_byte(wc * 32 + fr, fq * 8);
;     ...
;     { const int rot0 = cur.krot, nt0 = cur.nkt; const char* sA0 = PG8_KP(cA, 0, rot0, nt0); const char* sA1 = PG8_KP(cA, 1, rot0, nt0); const char* sB0 = PG8_KP(cB, 0, rot0, nt0); const char* sB1 = PG8_KP(cB, 1, rot0, nt0);
;     if constexpr (SP2) {
;         PG8_STAGEB(PG8_SB(0, 0), sB0, voffB); PG8_STAGEB(PG8_SB(0, 1), sB0 + hstep, voffB); PG8_STAGE(PG8_SA(0, 0), sA0, voffA); PG8_STAGE(PG8_SA(0, 1), sA0 + hstep, voffA);
;         if (wr == 1) PG8_BAR;
;         PG8_WAIT_V(2); PG8_BAR;
;         PG8_STAGEB(PG8_SB(1, 0), sB1, voffB); PG8_STAGE(PG8_SA(1, 0), sA1, voffA); PG8_STAGEB(PG8_SB(1, 1), sB1 + hstep, voffB);
;         PG8_WAIT_V(6); PG8_BAR;
;     } else {
;         PG8_STAGEB(PG8_SB(0, 0), sB0, voffB); PG8_STAGE(PG8_SA(0, 0), sA0, voffA); PG8_STAGEB(PG8_SB(0, 1), sB0 + hstep, voffB); PG8_STAGE(PG8_SA(0, 1), sA0 + hstep, voffA);
;         if (wr == 1) PG8_BAR;
;         PG8_WAIT_V(4); PG8_BAR;
;         PG8_STAGEB(PG8_SB(1, 0), sB1, voffB); PG8_STAGE(PG8_SA(1, 0), sA1, voffA); PG8_STAGEB(PG8_SB(1, 1), sB1 + hstep, voffB);
;         PG8_WAIT_V(6); PG8_BAR;
;     }
.LBB0_1052:
	s_andn2_b64 vcc, exec, s[4:5]
	s_cbranch_vccnz .LBB0_1288
	v_readlane_b32 s0, v254, 53
	v_readlane_b32 s1, v254, 54
	s_mov_b32 s1, s79
	s_lshl_b64 s[44:45], s[0:1], 22
	v_writelane_b32 v254, s0, 53
	s_mov_b64 s[4:5], s[66:67]
	v_mov_b32_e32 v16, v0
	v_writelane_b32 v254, s1, 54
	s_lshl_b64 s[0:1], s[0:1], 13
	s_add_u32 s2, s4, s44
	s_addc_u32 s6, s5, s45
	s_add_u32 s34, s2, 0x8000000
	s_addc_u32 s35, s6, 0
	s_add_u32 s8, s4, 0x1ec00000
	s_addc_u32 s9, s5, 0
	s_add_u32 s10, s4, 0x2ad80000
	s_addc_u32 s11, s5, 0
	s_add_u32 s0, s4, s0
	s_addc_u32 s1, s5, s1
	s_add_u32 s30, s0, 0x8000
	s_addc_u32 s31, s1, 0
	v_readlane_b32 s0, v252, 55
	v_readlane_b32 s1, v252, 56
	s_andn2_b64 vcc, exec, s[0:1]
	v_readfirstlane_b32 s12, v16
	v_cndmask_b32_e64 v1, 0, 1, s[0:1]
	v_cmp_ne_u32_e64 s[38:39], 1, v1
	s_cbranch_vccnz .LBB0_1143
	v_lshlrev_b32_e32 v1, 4, v16
	v_add_u32_e32 v2, 0x2000, v1
	v_ashrrev_i32_e32 v3, 31, v2
	v_lshrrev_b32_e32 v3, 22, v3
	v_add_u32_e32 v3, v2, v3
	v_ashrrev_i32_e32 v10, 10, v3
	v_mul_i32_i24_e32 v3, 0x400, v10
	v_sub_u32_e32 v2, v2, v3
	v_lshrrev_b32_e32 v3, 4, v2
	v_bitop3_b32 v2, v3, v2, 32 bitop3:0x6c
	v_ashrrev_i32_e32 v3, 31, v2
	v_lshrrev_b32_e32 v3, 26, v3
	v_add_u32_e32 v3, v2, v3
	v_lshlrev_b32_e32 v4, 3, v10
	v_ashrrev_i32_e32 v11, 6, v3
	v_and_b32_e32 v4, -16, v4
	v_add_u32_e32 v4, v11, v4
	v_and_b32_e32 v5, 3, v11
	s_mov_b32 s2, 0x1fffe0
	v_lshrrev_b32_e32 v6, 2, v4
	v_lshlrev_b32_e32 v7, 1, v4
	v_and_b32_e32 v3, 0xc0, v3
	v_and_or_b32 v5, v4, s2, v5
	v_and_b32_e32 v6, 4, v6
	v_and_b32_e32 v7, 24, v7
	v_sub_u32_e32 v2, v2, v3
	v_or3_b32 v5, v5, v6, v7
	v_lshlrev_b32_e32 v6, 5, v10
	v_ashrrev_i16_sdwa v2, v207, sext(v2) dst_sel:DWORD dst_unused:UNUSED_PAD src0_sel:DWORD src1_sel:BYTE_0
	v_and_b32_e32 v6, 32, v6
	v_bfe_i32 v12, v2, 0, 16
	v_add_lshl_u32 v2, v6, v12, 1
	s_waitcnt vmcnt(0)
	v_lshl_add_u32 v132, v5, 11, v2
	v_lshl_add_u32 v134, v4, 11, v2
	v_bfe_i32 v2, v16, 27, 1
	v_lshrrev_b32_e32 v2, 22, v2
	v_add_u32_e32 v2, v1, v2
	v_and_b32_e32 v2, 0xfffffc00, v2
	v_sub_u32_e32 v1, v1, v2
	v_lshrrev_b32_e32 v2, 4, v1
	v_ashrrev_i32_e32 v3, 31, v16
	v_bitop3_b32 v1, v2, v1, 32 bitop3:0x6c
	v_lshrrev_b32_e32 v3, 26, v3
	v_ashrrev_i32_e32 v2, 31, v1
	v_add_u32_e32 v3, v16, v3
	v_lshrrev_b32_e32 v2, 26, v2
	v_ashrrev_i32_e32 v14, 6, v3
	v_add_u32_e32 v2, v1, v2
	v_lshlrev_b32_e32 v3, 3, v14
	v_ashrrev_i32_e32 v13, 6, v2
	v_and_b32_e32 v3, -16, v3
	v_add_u32_e32 v3, v13, v3
	s_add_u32 s33, s4, 0x28980000
	v_and_b32_e32 v4, 3, v13
	v_lshrrev_b32_e32 v5, 2, v3
	v_lshlrev_b32_e32 v6, 1, v3
	v_and_b32_e32 v2, 0xc0, v2
	s_addc_u32 s69, s5, 0
	s_ashr_i32 s0, s12, 6
	v_and_or_b32 v4, v3, s2, v4
	v_and_b32_e32 v5, 4, v5
	v_and_b32_e32 v6, 24, v6
	v_sub_u32_e32 v1, v1, v2
	s_ashr_i32 s1, s12, 8
	s_lshl_b32 s70, s0, 10
	v_or3_b32 v4, v4, v5, v6
	v_lshlrev_b32_e32 v5, 5, v14
	v_ashrrev_i16_sdwa v1, v207, sext(v1) dst_sel:DWORD dst_unused:UNUSED_PAD src0_sel:DWORD src1_sel:BYTE_0
	v_readlane_b32 s2, v253, 3
	v_and_b32_e32 v5, 32, v5
	v_bfe_i32 v15, v1, 0, 16
	v_readlane_b32 s3, v253, 4
	s_add_u32 s42, s34, s2
	v_add_lshl_u32 v1, v5, v15, 1
	s_addc_u32 s43, s35, s3
	s_add_i32 s71, s70, 0
	v_lshl_add_u32 v136, v4, 11, v1
	s_add_i32 m0, s71, 0x10000
	v_readlane_b32 s2, v252, 63
	global_load_lds_dwordx4 v136, s[42:43]
	s_add_i32 m0, s71, 0x12000
	v_readlane_b32 s3, v253, 0
	s_add_u32 s52, s33, s2
	s_addc_u32 s53, s69, s3
	s_add_u32 s6, s42, 0x40000
	global_load_lds_dwordx4 v132, s[42:43]
	s_addc_u32 s7, s43, 0
	s_add_i32 m0, s71, 0x14000
	s_add_i32 s75, s71, 0x2000
	global_load_lds_dwordx4 v136, s[6:7]
	s_add_i32 m0, s71, 0x16000
	v_lshl_add_u32 v138, v3, 11, v1
	global_load_lds_dwordx4 v132, s[6:7]
	s_mov_b32 m0, s71
	s_add_u32 s6, s52, 0x40000
	global_load_lds_dwordx4 v138, s[52:53]
	s_mov_b32 m0, s75
	s_addc_u32 s7, s53, 0
	s_add_i32 s78, s71, 0x4000
	global_load_lds_dwordx4 v134, s[52:53]
	s_mov_b32 m0, s78
	s_add_i32 s82, s71, 0x6000
	global_load_lds_dwordx4 v138, s[6:7]
	s_mov_b32 m0, s82
	v_mov_b32_e32 v137, v98
	global_load_lds_dwordx4 v134, s[6:7]
	v_mov_b32_e32 v133, v98
	v_mov_b32_e32 v139, v98
	v_mov_b32_e32 v135, v98
	s_cmp_eq_u32 s1, 1
	v_lshl_add_u64 v[8:9], s[42:43], 0, v[136:137]
	v_lshl_add_u64 v[6:7], s[42:43], 0, v[132:133]
	v_lshl_add_u64 v[2:3], s[52:53], 0, v[138:139]
	s_cselect_b64 s[6:7], -1, 0
	s_cmp_lg_u32 s1, 1
	v_lshl_add_u64 v[4:5], s[52:53], 0, v[134:135]
.LBB0_1056:
	v_bfe_u32 v18, v16, 4, 2
	s_lshl_b32 s0, s0, 5
	v_and_b32_e32 v17, 15, v16
	v_lshlrev_b32_e32 v19, 4, v18
	v_lshlrev_b32_e32 v16, 2, v16
	s_and_b32 s2, s0, 0x60
	s_add_i32 m0, s71, 0x18000
	v_lshl_add_u64 v[8:9], v[8:9], 0, s[76:77]
	v_lshl_or_b32 v1, s1, 6, v17
	v_lshl_or_b32 v19, v17, 6, v19
	s_lshl_b32 s1, s1, 13
	v_and_b32_e32 v16, 32, v16
	s_lshl_b32 s0, s2, 7
	global_load_lds_dwordx4 v[8:9], off
	v_lshl_add_u64 v[6:7], v[6:7], 0, s[76:77]
	s_add_i32 m0, s71, 0x1a000
	s_add_i32 s83, s71, 0x8000
	s_add_i32 s88, s71, 0xa000
	v_bitop3_b32 v99, v19, s0, v16 bitop3:0xde
	global_load_lds_dwordx4 v[6:7], off
	v_lshl_add_u64 v[2:3], v[2:3], 0, s[76:77]
	s_mov_b32 m0, s83
	s_add_u32 s0, s42, 0x40080
	v_bitop3_b32 v20, v19, s1, v16 bitop3:0xde
	global_load_lds_dwordx4 v[2:3], off
	v_lshl_add_u64 v[2:3], v[4:5], 0, s[76:77]
	s_mov_b32 m0, s88
	s_addc_u32 s1, s43, 0
	global_load_lds_dwordx4 v[2:3], off
	s_add_i32 m0, s71, 0x1c000
	v_lshl_add_u64 v[2:3], s[0:1], 0, v[136:137]
	global_load_lds_dwordx4 v[2:3], off
	v_lshl_add_u64 v[2:3], s[0:1], 0, v[132:133]
	s_add_i32 m0, s71, 0x1e000
	v_lshl_or_b32 v150, v18, 3, s2
	global_load_lds_dwordx4 v[2:3], off
	v_or_b32_e32 v2, v18, v17
	v_cmp_eq_u32_e64 s[40:41], 0, v2
	v_lshlrev_b32_e32 v2, 14, v10
	v_and_b32_e32 v2, 0xffff8000, v2
	v_lshl_add_u32 v2, v11, 11, v2
	v_and_b32_e32 v3, 1, v10
	v_lshl_or_b32 v2, v3, 6, v2
	v_lshl_add_u32 v140, v12, 1, v2
	v_lshlrev_b32_e32 v2, 14, v14
	v_and_b32_e32 v2, 0xffff8000, v2
	v_readlane_b32 s2, v253, 1
	s_waitcnt vmcnt(6)
	v_lshl_add_u32 v2, v13, 11, v2
	v_and_b32_e32 v3, 1, v14
	v_readlane_b32 s3, v253, 2
	s_cmpk_lt_u32 s12, 0x100
	v_lshl_or_b32 v2, v3, 6, v2
	s_mov_b32 s91, s2
	v_readlane_b32 s2, v252, 61
	s_cselect_b64 s[12:13], -1, 0
	s_mov_b32 s0, 0
	v_mov_b32_e32 v141, v98
	v_lshl_add_u32 v142, v15, 1, v2
	v_mov_b32_e32 v143, v98
	v_add_u32_e32 v151, 0, v20
	s_mov_b32 s90, s2
	s_barrier
	v_readlane_b32 s3, v252, 62
	s_branch .LBB0_1059

; #define PG8_BAR __builtin_amdgcn_s_barrier()
; template <class Epi, class Sched, bool ALIGN_EPI = false, bool SP2 = false>
; __device__ __forceinline__ void gemm_phase(PG8_LAS unsigned char* lds, const Gemm g, const Sched& S, const Epi& E) {
;     ...
;         if constexpr (ALIGN_EPI) { if (wr == 1) PG8_BAR; }
.LBB0_1140:
	s_andn2_b64 vcc, exec, s[6:7]
	s_branch .LBB0_1057

; #define PG8_WAIT_V(n) asm volatile("s_waitcnt vmcnt(" #n ")" ::: "memory")
; #define PG8_BAR __builtin_amdgcn_s_barrier()
; template <class Epi, class Sched, bool ALIGN_EPI = false, bool SP2 = false>
; __device__ __forceinline__ void gemm_phase(PG8_LAS unsigned char* lds, const Gemm g, const Sched& S, const Epi& E) {
;     ...
;     for (int i = 0; i < 2; ++i) { int R, C; stage_rc(tid * 16 + i * 8192, R, C); const int Rb = Epi::PERM ? ((R & ~31) + perm32(R & 31)) : R;
;         voffA[i] = (unsigned)(R * K + C) * 2u; voffB[i] = (unsigned)(Rb * K + C) * 2u; }
;     const size_t kstep = (size_t)(BK * 2);
;     const size_t hstep = (size_t)HALF * K * 2;
;     const size_t tstep = 2 * hstep;
;     const unsigned ldsw = (unsigned)wid * 1024u;
;     const int aoff = lds_byte(wr * 64 + fr, fq * 8), boff = lds_byte(wc * 32 + fr, fq * 8);
;     ...
;     { const int rot0 = cur.krot, nt0 = cur.nkt; const char* sA0 = PG8_KP(cA, 0, rot0, nt0); const char* sA1 = PG8_KP(cA, 1, rot0, nt0); const char* sB0 = PG8_KP(cB, 0, rot0, nt0); const char* sB1 = PG8_KP(cB, 1, rot0, nt0);
;     if constexpr (SP2) {
;         PG8_STAGEB(PG8_SB(0, 0), sB0, voffB); PG8_STAGEB(PG8_SB(0, 1), sB0 + hstep, voffB); PG8_STAGE(PG8_SA(0, 0), sA0, voffA); PG8_STAGE(PG8_SA(0, 1), sA0 + hstep, voffA);
;         if (wr == 1) PG8_BAR;
;         PG8_WAIT_V(2); PG8_BAR;
;         PG8_STAGEB(PG8_SB(1, 0), sB1, voffB); PG8_STAGE(PG8_SA(1, 0), sA1, voffA); PG8_STAGEB(PG8_SB(1, 1), sB1 + hstep, voffB);
;         PG8_WAIT_V(6); PG8_BAR;
;     } else {
;         PG8_STAGEB(PG8_SB(0, 0), sB0, voffB); PG8_STAGE(PG8_SA(0, 0), sA0, voffA); PG8_STAGEB(PG8_SB(0, 1), sB0 + hstep, voffB); PG8_STAGE(PG8_SA(0, 1), sA0 + hstep, voffA);
;         if (wr == 1) PG8_BAR;
;         PG8_WAIT_V(4); PG8_BAR;
;         PG8_STAGEB(PG8_SB(1, 0), sB1, voffB); PG8_STAGE(PG8_SA(1, 0), sA1, voffA); PG8_STAGEB(PG8_SB(1, 1), sB1 + hstep, voffB);
;         PG8_WAIT_V(6); PG8_BAR;
;     }
; __global__ void __launch_bounds__(NWAVES * 64, 2) enc_fwd(Args args) {
;     ...
;             VM_WAIT(); __syncthreads();
;             { pg8::Gemm g{AO, (const bf16*)(ws + WS_WPA + l * SZ_WP), NTOK, 2048, 1024}; pg8::PROrder S; S.init(NTOK, 2048, 1024, G, bx, 4);
;               pg8::EpiPR<1> E{P, T1, MX, (unsigned*)(ws + WS_CTL + 32768) + (size_t)l * 32 * 64};
;               pg8::gemm_phase<pg8::EpiPR<1>, pg8::PROrder, PG8_ALIGN, PG8_SP2>(lds + RING_OFF, g, S, E); }
.LBB0_1143:
	s_add_u32 s0, s4, s44
	s_waitcnt vmcnt(0)
	s_addc_u32 s1, s5, s45
	s_add_u32 s6, s0, 0x9000000
	v_mov_b32_e32 v16, v0
	s_waitcnt vmcnt(0) lgkmcnt(0)
	s_barrier
	s_addc_u32 s7, s1, 0
	s_and_b64 vcc, exec, s[38:39]
	v_readfirstlane_b32 s16, v16
	s_cbranch_vccnz .LBB0_1182
	v_lshlrev_b32_e32 v1, 4, v16
	v_add_u32_e32 v2, 0x2000, v1
	v_ashrrev_i32_e32 v3, 31, v2
	v_lshrrev_b32_e32 v3, 22, v3
	v_add_u32_e32 v3, v2, v3
	v_ashrrev_i32_e32 v10, 10, v3
	v_mul_i32_i24_e32 v3, 0x400, v10
	v_sub_u32_e32 v2, v2, v3
	v_lshrrev_b32_e32 v3, 4, v2
	v_bitop3_b32 v2, v3, v2, 32 bitop3:0x6c
	v_ashrrev_i32_e32 v3, 31, v2
	v_lshrrev_b32_e32 v3, 26, v3
	v_add_u32_e32 v3, v2, v3
	v_lshlrev_b32_e32 v4, 3, v10
	v_ashrrev_i32_e32 v11, 6, v3
	v_and_b32_e32 v4, -16, v4
	v_add_u32_e32 v4, v11, v4
	v_and_b32_e32 v5, 3, v11
	s_mov_b32 s2, 0x1fffe0
	v_lshrrev_b32_e32 v6, 2, v4
	v_lshlrev_b32_e32 v7, 1, v4
	v_and_b32_e32 v3, 0xc0, v3
	v_and_or_b32 v5, v4, s2, v5
	v_and_b32_e32 v6, 4, v6
	v_and_b32_e32 v7, 24, v7
	v_sub_u32_e32 v2, v2, v3
	v_or3_b32 v5, v5, v6, v7
	v_lshlrev_b32_e32 v6, 5, v10
	v_ashrrev_i16_sdwa v2, v207, sext(v2) dst_sel:DWORD dst_unused:UNUSED_PAD src0_sel:DWORD src1_sel:BYTE_0
	v_and_b32_e32 v6, 32, v6
	v_bfe_i32 v12, v2, 0, 16
	v_add_lshl_u32 v2, v6, v12, 1
	v_lshl_add_u32 v132, v5, 11, v2
	v_lshl_add_u32 v134, v4, 11, v2
	v_bfe_i32 v2, v16, 27, 1
	v_lshrrev_b32_e32 v2, 22, v2
	v_add_u32_e32 v2, v1, v2
	v_and_b32_e32 v2, 0xfffffc00, v2
	v_sub_u32_e32 v1, v1, v2
	v_lshrrev_b32_e32 v2, 4, v1
	v_ashrrev_i32_e32 v3, 31, v16
	v_bitop3_b32 v1, v2, v1, 32 bitop3:0x6c
	v_lshrrev_b32_e32 v3, 26, v3
	v_ashrrev_i32_e32 v2, 31, v1
	v_add_u32_e32 v3, v16, v3
	v_lshrrev_b32_e32 v2, 26, v2
	v_ashrrev_i32_e32 v14, 6, v3
	v_add_u32_e32 v2, v1, v2
	v_lshlrev_b32_e32 v3, 3, v14
	v_ashrrev_i32_e32 v13, 6, v2
	v_and_b32_e32 v3, -16, v3
	v_add_u32_e32 v3, v13, v3
	s_add_u32 s33, s4, 0x29b80000
	v_and_b32_e32 v4, 3, v13
	v_lshrrev_b32_e32 v5, 2, v3
	v_lshlrev_b32_e32 v6, 1, v3
	v_and_b32_e32 v2, 0xc0, v2
	s_addc_u32 s69, s5, 0
	s_ashr_i32 s0, s16, 6
	v_and_or_b32 v4, v3, s2, v4
	v_and_b32_e32 v5, 4, v5
	v_and_b32_e32 v6, 24, v6
	v_sub_u32_e32 v1, v1, v2
	s_ashr_i32 s1, s16, 8
	s_lshl_b32 s70, s0, 10
	v_or3_b32 v4, v4, v5, v6
	v_lshlrev_b32_e32 v5, 5, v14
	v_ashrrev_i16_sdwa v1, v207, sext(v1) dst_sel:DWORD dst_unused:UNUSED_PAD src0_sel:DWORD src1_sel:BYTE_0
	v_readlane_b32 s2, v253, 3
	v_and_b32_e32 v5, 32, v5
	v_bfe_i32 v15, v1, 0, 16
	v_readlane_b32 s3, v253, 4
	s_add_u32 s50, s6, s2
	v_add_lshl_u32 v1, v5, v15, 1
	s_addc_u32 s51, s7, s3
	s_add_i32 s71, s70, 0
	v_lshl_add_u32 v136, v4, 11, v1
	s_add_i32 m0, s71, 0x10000
	v_readlane_b32 s2, v252, 63
	global_load_lds_dwordx4 v136, s[50:51]
	s_add_i32 m0, s71, 0x12000
	v_readlane_b32 s3, v253, 0
	s_add_u32 s52, s33, s2
	s_addc_u32 s53, s69, s3
	s_add_u32 s12, s50, 0x40000
	global_load_lds_dwordx4 v132, s[50:51]
	s_addc_u32 s13, s51, 0
	s_add_i32 m0, s71, 0x14000
	s_add_i32 s75, s71, 0x2000
	global_load_lds_dwordx4 v136, s[12:13]
	s_add_i32 m0, s71, 0x16000
	v_lshl_add_u32 v138, v3, 11, v1
	global_load_lds_dwordx4 v132, s[12:13]
	s_mov_b32 m0, s71
	s_add_u32 s12, s52, 0x40000
	global_load_lds_dwordx4 v138, s[52:53]
	s_mov_b32 m0, s75
	s_addc_u32 s13, s53, 0
	s_add_i32 s78, s71, 0x4000
	global_load_lds_dwordx4 v134, s[52:53]
	s_mov_b32 m0, s78
	s_add_i32 s82, s71, 0x6000
	global_load_lds_dwordx4 v138, s[12:13]
	s_mov_b32 m0, s82
	v_mov_b32_e32 v137, v98
	global_load_lds_dwordx4 v134, s[12:13]
	v_mov_b32_e32 v133, v98
	v_mov_b32_e32 v139, v98
	v_mov_b32_e32 v135, v98
	s_cmp_eq_u32 s1, 1
	v_lshl_add_u64 v[8:9], s[50:51], 0, v[136:137]
	v_lshl_add_u64 v[6:7], s[50:51], 0, v[132:133]
	v_lshl_add_u64 v[2:3], s[52:53], 0, v[138:139]
	s_cselect_b64 s[12:13], -1, 0
	s_cmp_lg_u32 s1, 1
	v_lshl_add_u64 v[4:5], s[52:53], 0, v[134:135]
.LBB0_1146:
	s_add_u32 s14, s4, 0x2d180000
	v_lshrrev_b32_e32 v18, 1, v16
	s_addc_u32 s15, s5, 0
	v_and_b32_e32 v18, 24, v18
	s_lshl_b32 s0, s0, 5
	v_and_b32_e32 v17, 15, v16
	v_lshlrev_b32_e32 v19, 1, v18
	v_lshlrev_b32_e32 v16, 2, v16
	s_and_b32 s2, s0, 0x60
	s_add_i32 m0, s71, 0x18000
	v_lshl_add_u64 v[8:9], v[8:9], 0, s[76:77]
	v_lshl_or_b32 v1, s1, 6, v17
	v_lshl_or_b32 v17, v17, 6, v19
	s_lshl_b32 s1, s1, 13
	v_and_b32_e32 v16, 32, v16
	s_lshl_b32 s0, s2, 7
	global_load_lds_dwordx4 v[8:9], off
	v_lshl_add_u64 v[6:7], v[6:7], 0, s[76:77]
	s_add_i32 m0, s71, 0x1a000
	s_add_i32 s83, s71, 0x8000
	s_add_i32 s88, s71, 0xa000
	v_bitop3_b32 v99, v17, s0, v16 bitop3:0xde
	global_load_lds_dwordx4 v[6:7], off
	v_lshl_add_u64 v[2:3], v[2:3], 0, s[76:77]
	s_mov_b32 m0, s83
	s_add_u32 s0, s50, 0x40080
	v_bitop3_b32 v19, v17, s1, v16 bitop3:0xde
	global_load_lds_dwordx4 v[2:3], off
	v_lshl_add_u64 v[2:3], v[4:5], 0, s[76:77]
	s_mov_b32 m0, s88
	s_addc_u32 s1, s51, 0
	global_load_lds_dwordx4 v[2:3], off
	s_add_i32 m0, s71, 0x1c000
	v_lshl_add_u64 v[2:3], s[0:1], 0, v[136:137]
	global_load_lds_dwordx4 v[2:3], off
	v_lshl_add_u64 v[2:3], s[0:1], 0, v[132:133]
	s_add_i32 m0, s71, 0x1e000
	v_or_b32_e32 v152, s2, v18
	global_load_lds_dwordx4 v[2:3], off
	v_lshlrev_b32_e32 v2, 14, v10
	v_and_b32_e32 v2, 0xffff8000, v2
	v_lshl_add_u32 v2, v11, 11, v2
	v_and_b32_e32 v3, 1, v10
	v_lshl_or_b32 v2, v3, 6, v2
	v_lshl_add_u32 v140, v12, 1, v2
	v_lshlrev_b32_e32 v2, 14, v14
	v_and_b32_e32 v2, 0xffff8000, v2
	v_readlane_b32 s2, v253, 1
	s_waitcnt vmcnt(6)
	v_lshl_add_u32 v2, v13, 11, v2
	v_and_b32_e32 v3, 1, v14
	v_readlane_b32 s3, v253, 2
	s_cmpk_lt_u32 s16, 0x100
	v_lshl_or_b32 v2, v3, 6, v2
	s_mov_b32 s91, s2
	v_readlane_b32 s2, v252, 61
	s_cselect_b64 s[16:17], -1, 0
	v_mov_b32_e32 v141, v98
	v_lshl_add_u32 v142, v15, 1, v2
	v_mov_b32_e32 v143, v98
	s_mov_b32 s0, 0
	v_add_u32_e32 v153, 0, v19
	s_mov_b32 s90, s2
	s_barrier
	v_readlane_b32 s3, v252, 62
	s_branch .LBB0_1149

; #define GAS __attribute__((address_space(1)))
; __device__ __forceinline__ u32x4 pack8(f32x4 v0, f32x4 v1) { u32x4 w; w.x = cvt_pk_bf16(v0[0], v0[1]); w.y = cvt_pk_bf16(v0[2], v0[3]); w.z = cvt_pk_bf16(v1[0], v1[1]); w.w = cvt_pk_bf16(v1[2], v1[3]); return w; }
; __device__ __forceinline__ void unpack8(u32x4 w, f32x4& v0, f32x4& v1) { v0 = (f32x4){bflo(w.x), bfhi(w.x), bflo(w.y), bfhi(w.y)}; v1 = (f32x4){bflo(w.z), bfhi(w.z), bflo(w.w), bfhi(w.w)}; }
; #define GAS __attribute__((address_space(1)))
;     __device__ __forceinline__ void operator()(const f32x4 (&acc)[2][2][4][2], const Unit& u, int wr, int wc, int fr, int fq) const {
;     ...
;             for (int m = 0; m < 4; ++m) { const size_t r = (size_t)(row0 + ai * HALF + m * 16); const size_t off = r * 2048 + col0; const bf16_t* gp = P + r * NPJ + 2560 + MODE * 2048 + col0;
; #pragma unroll
;                 for (int bj = 0; bj < 2; ++bj) { f32x4 g0, g1; unpack8(*(const GAS u32x4*)(gp + bj * HALF), g0, g1);
;                     f32x4 v0 = g0 * acc[ai][bj][m][0], v1 = g1 * acc[ai][bj][m][1];
;                     if (MODE == 1) { f32x4 t0, t1; unpack8(*(const GAS u32x4*)(T1 + off + bj * HALF), t0, t1); v0 += t0; v1 += t1; }
;                     const u32x4 w = pack8(v0, v1);
;                     if (MODE == 0 && samp) asm volatile("global_store_dwordx4 %0, %1, off sc1\n\ts_nop 1" :: "v"(O + off + bj * HALF), "v"(w) : "memory");
;                     else *(GAS u32x4*)(O + off + bj * HALF) = w; } }
.LBB0_1178:
	v_or_b32_e32 v144, s19, v152
	v_lshl_add_u32 v146, s90, 8, v1
	v_ashrrev_i32_e32 v145, 31, v144
	v_mov_b64_e32 v[148:149], s[8:9]
	v_ashrrev_i32_e32 v147, 31, v146
	v_mad_i64_i32 v[154:155], s[0:1], v146, s95, v[148:149]
	v_lshlrev_b64 v[150:151], 1, v[144:145]
	v_lshlrev_b64 v[158:159], 11, v[146:147]
	v_lshl_add_u64 v[162:163], v[154:155], 0, v[150:151]
	v_lshl_add_u64 v[158:159], v[158:159], 0, v[144:145]
	v_add_co_u32_e32 v154, vcc, 0x2000, v162
	v_lshlrev_b64 v[164:165], 1, v[158:159]
	s_nop 0
	v_addc_co_u32_e32 v155, vcc, 0, v163, vcc
	v_lshl_add_u64 v[166:167], s[10:11], 0, v[164:165]
	global_load_dwordx4 v[222:225], v[154:155], off offset:1024
	global_load_dwordx4 v[226:229], v[166:167], off
	global_load_dwordx4 v[230:233], v[154:155], off offset:1280
	global_load_dwordx4 v[234:237], v[166:167], off offset:256
	v_add_co_u32_e32 v192, vcc, 0x34000, v154
	s_nop 1
	v_addc_co_u32_e32 v193, vcc, 0, v155, vcc
	global_load_dwordx4 v[238:241], v[192:193], off offset:1024
	v_add_co_u32_e32 v194, vcc, 0x10000, v166
	s_nop 1
	v_addc_co_u32_e32 v195, vcc, 0, v167, vcc
	global_load_dwordx4 v[242:245], v[194:195], off
	global_load_dwordx4 v[184:187], v[192:193], off offset:1280
	global_load_dwordx4 v[188:191], v[194:195], off offset:256
	s_mov_b64 s[2:3], 0x2400
	v_lshl_add_u64 v[164:165], s[14:15], 0, v[164:165]
	v_lshl_add_u64 v[162:163], v[162:163], 0, s[2:3]
	s_movk_i32 s19, 0x2000
	s_waitcnt vmcnt(6)
	s_nop 1
	v_mov_b32_e32 v154, v222
	v_mov_b32_e32 v155, v223
	v_mov_b32_e32 v156, v224
	v_mov_b32_e32 v157, v225
	v_mov_b32_e32 v158, v226
	v_mov_b32_e32 v159, v227
	v_mov_b32_e32 v160, v228
	v_mov_b32_e32 v161, v229
	v_lshlrev_b32_e32 v168, 16, v154
	v_and_b32_e32 v169, 0xffff0000, v154
	v_lshlrev_b32_e32 v154, 16, v155
	v_and_b32_e32 v155, 0xffff0000, v155
	v_lshlrev_b32_e32 v172, 16, v156
	v_and_b32_e32 v173, 0xffff0000, v156
	v_lshlrev_b32_e32 v156, 16, v157
	v_and_b32_e32 v157, 0xffff0000, v157
	v_lshlrev_b32_e32 v180, 16, v158
	v_and_b32_e32 v181, 0xffff0000, v158
	v_lshlrev_b32_e32 v158, 16, v159
	v_and_b32_e32 v159, 0xffff0000, v159
	v_lshlrev_b32_e32 v182, 16, v160
	v_and_b32_e32 v183, 0xffff0000, v160
	v_lshlrev_b32_e32 v160, 16, v161
	v_and_b32_e32 v161, 0xffff0000, v161
	v_pk_fma_f32 v[130:131], v[130:131], v[154:155], v[158:159]
	v_pk_fma_f32 v[128:129], v[128:129], v[168:169], v[180:181]
	v_pk_fma_f32 v[154:155], v[126:127], v[156:157], v[160:161]
	v_pk_fma_f32 v[126:127], v[124:125], v[172:173], v[182:183]
	v_cvt_pk_bf16_f32 v124, v128, v129
	v_cvt_pk_bf16_f32 v125, v130, v131
	v_cvt_pk_bf16_f32 v126, v126, v127
	v_cvt_pk_bf16_f32 v127, v154, v155
	global_store_dwordx4 v[164:165], v[124:127], off
	s_nop 0
	v_or_b32_e32 v154, 16, v146
	v_ashrrev_i32_e32 v155, 31, v154
	v_mad_i64_i32 v[156:157], s[0:1], v154, s95, v[148:149]
	v_lshl_add_u64 v[156:157], v[156:157], 0, v[150:151]
	v_add_co_u32_e32 v158, vcc, s19, v156
	s_waitcnt vmcnt(6)
	s_nop 1
	v_mov_b32_e32 v124, v230
	v_mov_b32_e32 v125, v231
	v_mov_b32_e32 v126, v232
	v_mov_b32_e32 v127, v233
	v_lshlrev_b32_e32 v160, 16, v124
	v_and_b32_e32 v161, 0xffff0000, v124
	s_waitcnt vmcnt(5)
	s_nop 1
	v_mov_b32_e32 v128, v234
	v_mov_b32_e32 v129, v235
	v_mov_b32_e32 v130, v236
	v_mov_b32_e32 v131, v237
	v_lshlrev_b32_e32 v166, 16, v128
	v_and_b32_e32 v167, 0xffff0000, v128
	v_lshlrev_b32_e32 v124, 16, v125
	v_and_b32_e32 v125, 0xffff0000, v125
	v_lshlrev_b32_e32 v162, 16, v126
	v_and_b32_e32 v163, 0xffff0000, v126
	v_lshlrev_b32_e32 v126, 16, v127
	v_and_b32_e32 v127, 0xffff0000, v127
	v_lshlrev_b32_e32 v128, 16, v129
	v_and_b32_e32 v129, 0xffff0000, v129
	v_lshlrev_b32_e32 v168, 16, v130
	v_and_b32_e32 v169, 0xffff0000, v130
	v_lshlrev_b32_e32 v130, 16, v131
	v_and_b32_e32 v131, 0xffff0000, v131
	v_pk_fma_f32 v[120:121], v[120:121], v[160:161], v[166:167]
	v_pk_fma_f32 v[122:123], v[122:123], v[124:125], v[128:129]
	v_pk_fma_f32 v[124:125], v[118:119], v[126:127], v[130:131]
	v_pk_fma_f32 v[118:119], v[116:117], v[162:163], v[168:169]
	v_cvt_pk_bf16_f32 v116, v120, v121
	v_lshlrev_b64 v[120:121], 11, v[154:155]
	v_lshl_add_u64 v[120:121], v[120:121], 0, v[144:145]
	v_cvt_pk_bf16_f32 v117, v122, v123
	v_cvt_pk_bf16_f32 v118, v118, v119
	v_cvt_pk_bf16_f32 v119, v124, v125
	v_lshlrev_b64 v[124:125], 1, v[120:121]
	v_addc_co_u32_e32 v159, vcc, 0, v157, vcc
	global_store_dwordx4 v[164:165], v[116:119], off offset:256
	v_lshl_add_u64 v[126:127], s[10:11], 0, v[124:125]
	v_lshl_add_u64 v[128:129], v[156:157], 0, s[2:3]
	v_lshl_add_u64 v[124:125], s[14:15], 0, v[124:125]
	s_waitcnt vmcnt(5)
	s_nop 1
	v_mov_b32_e32 v116, v238
	v_mov_b32_e32 v117, v239
	v_mov_b32_e32 v118, v240
	v_mov_b32_e32 v119, v241
	v_lshlrev_b32_e32 v130, 16, v116
	v_and_b32_e32 v131, 0xffff0000, v116
	v_lshlrev_b32_e32 v116, 16, v117
	v_and_b32_e32 v117, 0xffff0000, v117
	v_lshlrev_b32_e32 v154, 16, v118
	v_and_b32_e32 v155, 0xffff0000, v118
	v_lshlrev_b32_e32 v118, 16, v119
	v_and_b32_e32 v119, 0xffff0000, v119
	s_waitcnt vmcnt(4)
	s_nop 1
	v_mov_b32_e32 v120, v242
	v_mov_b32_e32 v121, v243
	v_mov_b32_e32 v122, v244
	v_mov_b32_e32 v123, v245
	v_lshlrev_b32_e32 v156, 16, v120
	v_and_b32_e32 v157, 0xffff0000, v120
	v_lshlrev_b32_e32 v120, 16, v121
	v_and_b32_e32 v121, 0xffff0000, v121
	v_lshlrev_b32_e32 v158, 16, v122
	v_and_b32_e32 v159, 0xffff0000, v122
	v_lshlrev_b32_e32 v122, 16, v123
	v_and_b32_e32 v123, 0xffff0000, v123
	v_pk_fma_f32 v[114:115], v[114:115], v[116:117], v[120:121]
	v_pk_fma_f32 v[112:113], v[112:113], v[130:131], v[156:157]
	v_pk_fma_f32 v[116:117], v[110:111], v[118:119], v[122:123]
	v_pk_fma_f32 v[110:111], v[108:109], v[154:155], v[158:159]
	v_cvt_pk_bf16_f32 v108, v112, v113
	v_cvt_pk_bf16_f32 v109, v114, v115
	v_cvt_pk_bf16_f32 v110, v110, v111
	v_cvt_pk_bf16_f32 v111, v116, v117
	global_store_dwordx4 v[124:125], v[108:111], off
	s_nop 0
	v_or_b32_e32 v116, 32, v146
	v_ashrrev_i32_e32 v117, 31, v116
	v_mad_i64_i32 v[118:119], s[0:1], v116, s95, v[148:149]
	v_lshl_add_u64 v[118:119], v[118:119], 0, v[150:151]
	v_add_co_u32_e32 v120, vcc, s19, v118
	s_waitcnt vmcnt(4)
; #define GAS __attribute__((address_space(1)))
; __device__ __forceinline__ u32x4 pack8(f32x4 v0, f32x4 v1) { u32x4 w; w.x = cvt_pk_bf16(v0[0], v0[1]); w.y = cvt_pk_bf16(v0[2], v0[3]); w.z = cvt_pk_bf16(v1[0], v1[1]); w.w = cvt_pk_bf16(v1[2], v1[3]); return w; }
; __device__ __forceinline__ void unpack8(u32x4 w, f32x4& v0, f32x4& v1) { v0 = (f32x4){bflo(w.x), bfhi(w.x), bflo(w.y), bfhi(w.y)}; v1 = (f32x4){bflo(w.z), bfhi(w.z), bflo(w.w), bfhi(w.w)}; }
; #define GAS __attribute__((address_space(1)))
;     __device__ __forceinline__ void operator()(const f32x4 (&acc)[2][2][4][2], const Unit& u, int wr, int wc, int fr, int fq) const {
;     ...
;             for (int m = 0; m < 4; ++m) { const size_t r = (size_t)(row0 + ai * HALF + m * 16); const size_t off = r * 2048 + col0; const bf16_t* gp = P + r * NPJ + 2560 + MODE * 2048 + col0;
; #pragma unroll
;                 for (int bj = 0; bj < 2; ++bj) { f32x4 g0, g1; unpack8(*(const GAS u32x4*)(gp + bj * HALF), g0, g1);
;                     f32x4 v0 = g0 * acc[ai][bj][m][0], v1 = g1 * acc[ai][bj][m][1];
;                     if (MODE == 1) { f32x4 t0, t1; unpack8(*(const GAS u32x4*)(T1 + off + bj * HALF), t0, t1); v0 += t0; v1 += t1; }
;                     const u32x4 w = pack8(v0, v1);
;                     if (MODE == 0 && samp) asm volatile("global_store_dwordx4 %0, %1, off sc1\n\ts_nop 1" :: "v"(O + off + bj * HALF), "v"(w) : "memory");
;                     else *(GAS u32x4*)(O + off + bj * HALF) = w; } }
	s_nop 1
	v_mov_b32_e32 v108, v184
	v_mov_b32_e32 v109, v185
	v_mov_b32_e32 v110, v186
	v_mov_b32_e32 v111, v187
	v_lshlrev_b32_e32 v122, 16, v108
	v_and_b32_e32 v123, 0xffff0000, v108
	s_waitcnt vmcnt(3)
	s_nop 1
	v_mov_b32_e32 v112, v188
	v_mov_b32_e32 v113, v189
	v_mov_b32_e32 v114, v190
	v_mov_b32_e32 v115, v191
	v_lshlrev_b32_e32 v128, 16, v112
	v_and_b32_e32 v129, 0xffff0000, v112
	v_lshlrev_b32_e32 v108, 16, v109
	v_and_b32_e32 v109, 0xffff0000, v109
	v_lshlrev_b32_e32 v126, 16, v110
	v_and_b32_e32 v127, 0xffff0000, v110
	v_lshlrev_b32_e32 v110, 16, v111
	v_and_b32_e32 v111, 0xffff0000, v111
	v_lshlrev_b32_e32 v112, 16, v113
	v_and_b32_e32 v113, 0xffff0000, v113
	v_lshlrev_b32_e32 v130, 16, v114
	v_and_b32_e32 v131, 0xffff0000, v114
	v_lshlrev_b32_e32 v114, 16, v115
	v_and_b32_e32 v115, 0xffff0000, v115
	v_pk_fma_f32 v[104:105], v[104:105], v[122:123], v[128:129]
	v_pk_fma_f32 v[106:107], v[106:107], v[108:109], v[112:113]
	v_pk_fma_f32 v[108:109], v[102:103], v[110:111], v[114:115]
	v_pk_fma_f32 v[102:103], v[100:101], v[126:127], v[130:131]
	v_cvt_pk_bf16_f32 v100, v104, v105
	v_lshlrev_b64 v[104:105], 11, v[116:117]
	v_lshl_add_u64 v[104:105], v[104:105], 0, v[144:145]
	v_cvt_pk_bf16_f32 v101, v106, v107
	v_cvt_pk_bf16_f32 v102, v102, v103
	v_cvt_pk_bf16_f32 v103, v108, v109
	v_lshlrev_b64 v[108:109], 1, v[104:105]
	v_addc_co_u32_e32 v121, vcc, 0, v119, vcc
	global_store_dwordx4 v[124:125], v[100:103], off offset:256
	v_lshl_add_u64 v[110:111], s[10:11], 0, v[108:109]
	global_load_dwordx4 v[222:225], v[120:121], off offset:1024
	global_load_dwordx4 v[226:229], v[110:111], off
	global_load_dwordx4 v[230:233], v[120:121], off offset:1280
	global_load_dwordx4 v[234:237], v[110:111], off offset:256
	v_add_co_u32_e32 v192, vcc, 0x34000, v120
	s_nop 1
	v_addc_co_u32_e32 v193, vcc, 0, v121, vcc
	global_load_dwordx4 v[238:241], v[192:193], off offset:1024
	v_add_co_u32_e32 v194, vcc, 0x10000, v110
	s_nop 1
	v_addc_co_u32_e32 v195, vcc, 0, v111, vcc
	global_load_dwordx4 v[242:245], v[194:195], off
	global_load_dwordx4 v[184:187], v[192:193], off offset:1280
	global_load_dwordx4 v[188:191], v[194:195], off offset:256
	v_lshl_add_u64 v[112:113], v[118:119], 0, s[2:3]
	v_lshl_add_u64 v[108:109], s[14:15], 0, v[108:109]
	s_waitcnt vmcnt(7)
	s_nop 1
	v_mov_b32_e32 v100, v222
	v_mov_b32_e32 v101, v223
	v_mov_b32_e32 v102, v224
	v_mov_b32_e32 v103, v225
	v_lshlrev_b32_e32 v114, 16, v100
	v_and_b32_e32 v115, 0xffff0000, v100
	v_lshlrev_b32_e32 v100, 16, v101
	v_and_b32_e32 v101, 0xffff0000, v101
	v_lshlrev_b32_e32 v116, 16, v102
	v_and_b32_e32 v117, 0xffff0000, v102
	v_lshlrev_b32_e32 v102, 16, v103
	v_and_b32_e32 v103, 0xffff0000, v103
	s_waitcnt vmcnt(6)
	s_nop 1
	v_mov_b32_e32 v104, v226
	v_mov_b32_e32 v105, v227
	v_mov_b32_e32 v106, v228
	v_mov_b32_e32 v107, v229
	v_lshlrev_b32_e32 v118, 16, v104
	v_and_b32_e32 v119, 0xffff0000, v104
	v_lshlrev_b32_e32 v104, 16, v105
	v_and_b32_e32 v105, 0xffff0000, v105
	v_lshlrev_b32_e32 v120, 16, v106
	v_and_b32_e32 v121, 0xffff0000, v106
	v_lshlrev_b32_e32 v106, 16, v107
	v_and_b32_e32 v107, 0xffff0000, v107
	v_pk_fma_f32 v[96:97], v[96:97], v[100:101], v[104:105]
	v_pk_fma_f32 v[94:95], v[94:95], v[114:115], v[118:119]
	v_pk_fma_f32 v[100:101], v[92:93], v[102:103], v[106:107]
	v_pk_fma_f32 v[92:93], v[90:91], v[116:117], v[120:121]
	v_cvt_pk_bf16_f32 v90, v94, v95
	v_cvt_pk_bf16_f32 v91, v96, v97
	v_cvt_pk_bf16_f32 v92, v92, v93
	v_cvt_pk_bf16_f32 v93, v100, v101
	global_store_dwordx4 v[108:109], v[90:93], off
	s_nop 0
	v_or_b32_e32 v100, 48, v146
	v_ashrrev_i32_e32 v101, 31, v100
	v_mad_i64_i32 v[102:103], s[0:1], v100, s95, v[148:149]
	v_lshl_add_u64 v[102:103], v[102:103], 0, v[150:151]
	v_add_co_u32_e32 v104, vcc, s19, v102
	s_waitcnt vmcnt(6)
	s_nop 1
	v_mov_b32_e32 v90, v230
	v_mov_b32_e32 v91, v231
	v_mov_b32_e32 v92, v232
	v_mov_b32_e32 v93, v233
	v_lshlrev_b32_e32 v106, 16, v90
	v_and_b32_e32 v107, 0xffff0000, v90
	s_waitcnt vmcnt(5)
	s_nop 1
	v_mov_b32_e32 v94, v234
	v_mov_b32_e32 v95, v235
	v_mov_b32_e32 v96, v236
	v_mov_b32_e32 v97, v237
	v_lshlrev_b32_e32 v112, 16, v94
	v_and_b32_e32 v113, 0xffff0000, v94
	v_lshlrev_b32_e32 v90, 16, v91
	v_and_b32_e32 v91, 0xffff0000, v91
	v_lshlrev_b32_e32 v110, 16, v92
	v_and_b32_e32 v111, 0xffff0000, v92
	v_lshlrev_b32_e32 v92, 16, v93
	v_and_b32_e32 v93, 0xffff0000, v93
	v_lshlrev_b32_e32 v94, 16, v95
	v_and_b32_e32 v95, 0xffff0000, v95
	v_lshlrev_b32_e32 v114, 16, v96
	v_and_b32_e32 v115, 0xffff0000, v96
	v_lshlrev_b32_e32 v96, 16, v97
	v_and_b32_e32 v97, 0xffff0000, v97
	v_pk_fma_f32 v[86:87], v[86:87], v[106:107], v[112:113]
	v_pk_fma_f32 v[88:89], v[88:89], v[90:91], v[94:95]
	v_pk_fma_f32 v[90:91], v[84:85], v[92:93], v[96:97]
	v_pk_fma_f32 v[84:85], v[82:83], v[110:111], v[114:115]
	v_cvt_pk_bf16_f32 v82, v86, v87
	v_lshlrev_b64 v[86:87], 11, v[100:101]
	v_lshl_add_u64 v[86:87], v[86:87], 0, v[144:145]
	v_cvt_pk_bf16_f32 v83, v88, v89
	v_cvt_pk_bf16_f32 v84, v84, v85
	v_cvt_pk_bf16_f32 v85, v90, v91
	v_lshlrev_b64 v[90:91], 1, v[86:87]
	v_addc_co_u32_e32 v105, vcc, 0, v103, vcc
	global_store_dwordx4 v[108:109], v[82:85], off offset:256
	v_lshl_add_u64 v[92:93], s[10:11], 0, v[90:91]
	v_lshl_add_u64 v[94:95], v[102:103], 0, s[2:3]
	v_lshl_add_u64 v[90:91], s[14:15], 0, v[90:91]
	s_waitcnt vmcnt(5)
	s_nop 1
	v_mov_b32_e32 v82, v238
	v_mov_b32_e32 v83, v239
	v_mov_b32_e32 v84, v240
	v_mov_b32_e32 v85, v241
	v_lshlrev_b32_e32 v96, 16, v82
	v_and_b32_e32 v97, 0xffff0000, v82
	v_lshlrev_b32_e32 v82, 16, v83
	v_and_b32_e32 v83, 0xffff0000, v83
	v_lshlrev_b32_e32 v100, 16, v84
	v_and_b32_e32 v101, 0xffff0000, v84
	v_lshlrev_b32_e32 v84, 16, v85
	v_and_b32_e32 v85, 0xffff0000, v85
	s_waitcnt vmcnt(4)
; #define GAS __attribute__((address_space(1)))
; __device__ __forceinline__ u32x4 pack8(f32x4 v0, f32x4 v1) { u32x4 w; w.x = cvt_pk_bf16(v0[0], v0[1]); w.y = cvt_pk_bf16(v0[2], v0[3]); w.z = cvt_pk_bf16(v1[0], v1[1]); w.w = cvt_pk_bf16(v1[2], v1[3]); return w; }
; __device__ __forceinline__ void unpack8(u32x4 w, f32x4& v0, f32x4& v1) { v0 = (f32x4){bflo(w.x), bfhi(w.x), bflo(w.y), bfhi(w.y)}; v1 = (f32x4){bflo(w.z), bfhi(w.z), bflo(w.w), bfhi(w.w)}; }
; #define GAS __attribute__((address_space(1)))
;     __device__ __forceinline__ void operator()(const f32x4 (&acc)[2][2][4][2], const Unit& u, int wr, int wc, int fr, int fq) const {
;     ...
;             for (int m = 0; m < 4; ++m) { const size_t r = (size_t)(row0 + ai * HALF + m * 16); const size_t off = r * 2048 + col0; const bf16_t* gp = P + r * NPJ + 2560 + MODE * 2048 + col0;
; #pragma unroll
;                 for (int bj = 0; bj < 2; ++bj) { f32x4 g0, g1; unpack8(*(const GAS u32x4*)(gp + bj * HALF), g0, g1);
;                     f32x4 v0 = g0 * acc[ai][bj][m][0], v1 = g1 * acc[ai][bj][m][1];
;                     if (MODE == 1) { f32x4 t0, t1; unpack8(*(const GAS u32x4*)(T1 + off + bj * HALF), t0, t1); v0 += t0; v1 += t1; }
;                     const u32x4 w = pack8(v0, v1);
;                     if (MODE == 0 && samp) asm volatile("global_store_dwordx4 %0, %1, off sc1\n\ts_nop 1" :: "v"(O + off + bj * HALF), "v"(w) : "memory");
;                     else *(GAS u32x4*)(O + off + bj * HALF) = w; } }
	s_nop 1
	v_mov_b32_e32 v86, v242
	v_mov_b32_e32 v87, v243
	v_mov_b32_e32 v88, v244
	v_mov_b32_e32 v89, v245
	v_lshlrev_b32_e32 v102, 16, v86
	v_and_b32_e32 v103, 0xffff0000, v86
	v_lshlrev_b32_e32 v86, 16, v87
	v_and_b32_e32 v87, 0xffff0000, v87
	v_lshlrev_b32_e32 v104, 16, v88
	v_and_b32_e32 v105, 0xffff0000, v88
	v_lshlrev_b32_e32 v88, 16, v89
	v_and_b32_e32 v89, 0xffff0000, v89
	v_pk_fma_f32 v[80:81], v[80:81], v[82:83], v[86:87]
	v_pk_fma_f32 v[78:79], v[78:79], v[96:97], v[102:103]
	v_pk_fma_f32 v[82:83], v[76:77], v[84:85], v[88:89]
	v_pk_fma_f32 v[76:77], v[74:75], v[100:101], v[104:105]
	v_cvt_pk_bf16_f32 v74, v78, v79
	v_cvt_pk_bf16_f32 v75, v80, v81
	v_cvt_pk_bf16_f32 v76, v76, v77
	v_cvt_pk_bf16_f32 v77, v82, v83
	global_store_dwordx4 v[90:91], v[74:77], off
	s_nop 0
	v_add_u32_e32 v82, 0x80, v146
	v_ashrrev_i32_e32 v83, 31, v82
	v_mad_i64_i32 v[84:85], s[0:1], v82, s95, v[148:149]
	v_lshl_add_u64 v[84:85], v[84:85], 0, v[150:151]
	v_add_co_u32_e32 v86, vcc, s19, v84
	s_waitcnt vmcnt(4)
	s_nop 1
	v_mov_b32_e32 v74, v184
	v_mov_b32_e32 v75, v185
	v_mov_b32_e32 v76, v186
	v_mov_b32_e32 v77, v187
	v_lshlrev_b32_e32 v88, 16, v74
	v_and_b32_e32 v89, 0xffff0000, v74
	s_waitcnt vmcnt(3)
	s_nop 1
	v_mov_b32_e32 v78, v188
	v_mov_b32_e32 v79, v189
	v_mov_b32_e32 v80, v190
	v_mov_b32_e32 v81, v191
	v_lshlrev_b32_e32 v94, 16, v78
	v_and_b32_e32 v95, 0xffff0000, v78
	v_lshlrev_b32_e32 v74, 16, v75
	v_and_b32_e32 v75, 0xffff0000, v75
	v_lshlrev_b32_e32 v92, 16, v76
	v_and_b32_e32 v93, 0xffff0000, v76
	v_lshlrev_b32_e32 v76, 16, v77
	v_and_b32_e32 v77, 0xffff0000, v77
	v_lshlrev_b32_e32 v78, 16, v79
	v_and_b32_e32 v79, 0xffff0000, v79
	v_lshlrev_b32_e32 v96, 16, v80
	v_and_b32_e32 v97, 0xffff0000, v80
	v_lshlrev_b32_e32 v80, 16, v81
	v_and_b32_e32 v81, 0xffff0000, v81
	v_pk_fma_f32 v[70:71], v[70:71], v[88:89], v[94:95]
	v_pk_fma_f32 v[72:73], v[72:73], v[74:75], v[78:79]
	v_pk_fma_f32 v[74:75], v[68:69], v[76:77], v[80:81]
	v_pk_fma_f32 v[68:69], v[66:67], v[92:93], v[96:97]
	v_cvt_pk_bf16_f32 v66, v70, v71
	v_lshlrev_b64 v[70:71], 11, v[82:83]
	v_lshl_add_u64 v[70:71], v[70:71], 0, v[144:145]
	v_cvt_pk_bf16_f32 v67, v72, v73
	v_cvt_pk_bf16_f32 v68, v68, v69
	v_cvt_pk_bf16_f32 v69, v74, v75
	v_lshlrev_b64 v[74:75], 1, v[70:71]
	v_addc_co_u32_e32 v87, vcc, 0, v85, vcc
	global_store_dwordx4 v[90:91], v[66:69], off offset:256
	v_lshl_add_u64 v[76:77], s[10:11], 0, v[74:75]
	global_load_dwordx4 v[222:225], v[86:87], off offset:1024
	global_load_dwordx4 v[226:229], v[76:77], off
	global_load_dwordx4 v[230:233], v[86:87], off offset:1280
	global_load_dwordx4 v[234:237], v[76:77], off offset:256
	v_add_co_u32_e32 v192, vcc, 0x34000, v86
	s_nop 1
	v_addc_co_u32_e32 v193, vcc, 0, v87, vcc
	global_load_dwordx4 v[238:241], v[192:193], off offset:1024
	v_add_co_u32_e32 v194, vcc, 0x10000, v76
	s_nop 1
	v_addc_co_u32_e32 v195, vcc, 0, v77, vcc
	global_load_dwordx4 v[242:245], v[194:195], off
	global_load_dwordx4 v[184:187], v[192:193], off offset:1280
	global_load_dwordx4 v[188:191], v[194:195], off offset:256
	v_lshl_add_u64 v[78:79], v[84:85], 0, s[2:3]
	v_lshl_add_u64 v[74:75], s[14:15], 0, v[74:75]
	s_waitcnt vmcnt(7)
	s_nop 1
	v_mov_b32_e32 v66, v222
	v_mov_b32_e32 v67, v223
	v_mov_b32_e32 v68, v224
	v_mov_b32_e32 v69, v225
	v_lshlrev_b32_e32 v80, 16, v66
	v_and_b32_e32 v81, 0xffff0000, v66
	v_lshlrev_b32_e32 v66, 16, v67
	v_and_b32_e32 v67, 0xffff0000, v67
	v_lshlrev_b32_e32 v82, 16, v68
	v_and_b32_e32 v83, 0xffff0000, v68
	v_lshlrev_b32_e32 v68, 16, v69
	v_and_b32_e32 v69, 0xffff0000, v69
	s_waitcnt vmcnt(6)
	s_nop 1
	v_mov_b32_e32 v70, v226
	v_mov_b32_e32 v71, v227
	v_mov_b32_e32 v72, v228
	v_mov_b32_e32 v73, v229
	v_lshlrev_b32_e32 v84, 16, v70
	v_and_b32_e32 v85, 0xffff0000, v70
	v_lshlrev_b32_e32 v70, 16, v71
	v_and_b32_e32 v71, 0xffff0000, v71
	v_lshlrev_b32_e32 v86, 16, v72
	v_and_b32_e32 v87, 0xffff0000, v72
	v_lshlrev_b32_e32 v72, 16, v73
	v_and_b32_e32 v73, 0xffff0000, v73
	v_pk_fma_f32 v[64:65], v[64:65], v[66:67], v[70:71]
	v_pk_fma_f32 v[62:63], v[62:63], v[80:81], v[84:85]
	v_pk_fma_f32 v[66:67], v[60:61], v[68:69], v[72:73]
	v_pk_fma_f32 v[60:61], v[58:59], v[82:83], v[86:87]
	v_cvt_pk_bf16_f32 v58, v62, v63
	v_cvt_pk_bf16_f32 v59, v64, v65
	v_cvt_pk_bf16_f32 v60, v60, v61
	v_cvt_pk_bf16_f32 v61, v66, v67
	global_store_dwordx4 v[74:75], v[58:61], off
	s_nop 0
	v_add_u32_e32 v66, 0x90, v146
	v_ashrrev_i32_e32 v67, 31, v66
	v_mad_i64_i32 v[68:69], s[0:1], v66, s95, v[148:149]
	v_lshl_add_u64 v[68:69], v[68:69], 0, v[150:151]
	v_add_co_u32_e32 v70, vcc, s19, v68
	s_waitcnt vmcnt(6)
	s_nop 1
	v_mov_b32_e32 v58, v230
	v_mov_b32_e32 v59, v231
	v_mov_b32_e32 v60, v232
	v_mov_b32_e32 v61, v233
	v_lshlrev_b32_e32 v72, 16, v58
	v_and_b32_e32 v73, 0xffff0000, v58
	s_waitcnt vmcnt(5)
	s_nop 1
	v_mov_b32_e32 v62, v234
	v_mov_b32_e32 v63, v235
	v_mov_b32_e32 v64, v236
	v_mov_b32_e32 v65, v237
	v_lshlrev_b32_e32 v78, 16, v62
	v_and_b32_e32 v79, 0xffff0000, v62
	v_lshlrev_b32_e32 v58, 16, v59
	v_and_b32_e32 v59, 0xffff0000, v59
	v_lshlrev_b32_e32 v76, 16, v60
	v_and_b32_e32 v77, 0xffff0000, v60
	v_lshlrev_b32_e32 v60, 16, v61
	v_and_b32_e32 v61, 0xffff0000, v61
	v_lshlrev_b32_e32 v62, 16, v63
	v_and_b32_e32 v63, 0xffff0000, v63
	v_lshlrev_b32_e32 v80, 16, v64
	v_and_b32_e32 v81, 0xffff0000, v64
	v_lshlrev_b32_e32 v64, 16, v65
	v_and_b32_e32 v65, 0xffff0000, v65
	v_pk_fma_f32 v[54:55], v[54:55], v[72:73], v[78:79]
	v_pk_fma_f32 v[56:57], v[56:57], v[58:59], v[62:63]
	v_pk_fma_f32 v[58:59], v[52:53], v[60:61], v[64:65]
	v_pk_fma_f32 v[52:53], v[50:51], v[76:77], v[80:81]
	v_cvt_pk_bf16_f32 v50, v54, v55
	v_lshlrev_b64 v[54:55], 11, v[66:67]
	v_lshl_add_u64 v[54:55], v[54:55], 0, v[144:145]
	v_cvt_pk_bf16_f32 v51, v56, v57
	v_cvt_pk_bf16_f32 v52, v52, v53
	v_cvt_pk_bf16_f32 v53, v58, v59
	v_lshlrev_b64 v[58:59], 1, v[54:55]
	v_addc_co_u32_e32 v71, vcc, 0, v69, vcc
	global_store_dwordx4 v[74:75], v[50:53], off offset:256
	v_lshl_add_u64 v[60:61], s[10:11], 0, v[58:59]
	v_lshl_add_u64 v[62:63], v[68:69], 0, s[2:3]
	v_lshl_add_u64 v[58:59], s[14:15], 0, v[58:59]
	s_waitcnt vmcnt(5)
; #define GAS __attribute__((address_space(1)))
; __device__ __forceinline__ u32x4 pack8(f32x4 v0, f32x4 v1) { u32x4 w; w.x = cvt_pk_bf16(v0[0], v0[1]); w.y = cvt_pk_bf16(v0[2], v0[3]); w.z = cvt_pk_bf16(v1[0], v1[1]); w.w = cvt_pk_bf16(v1[2], v1[3]); return w; }
; __device__ __forceinline__ void unpack8(u32x4 w, f32x4& v0, f32x4& v1) { v0 = (f32x4){bflo(w.x), bfhi(w.x), bflo(w.y), bfhi(w.y)}; v1 = (f32x4){bflo(w.z), bfhi(w.z), bflo(w.w), bfhi(w.w)}; }
; #define GAS __attribute__((address_space(1)))
;     __device__ __forceinline__ void operator()(const f32x4 (&acc)[2][2][4][2], const Unit& u, int wr, int wc, int fr, int fq) const {
;     ...
;             for (int m = 0; m < 4; ++m) { const size_t r = (size_t)(row0 + ai * HALF + m * 16); const size_t off = r * 2048 + col0; const bf16_t* gp = P + r * NPJ + 2560 + MODE * 2048 + col0;
; #pragma unroll
;                 for (int bj = 0; bj < 2; ++bj) { f32x4 g0, g1; unpack8(*(const GAS u32x4*)(gp + bj * HALF), g0, g1);
;                     f32x4 v0 = g0 * acc[ai][bj][m][0], v1 = g1 * acc[ai][bj][m][1];
;                     if (MODE == 1) { f32x4 t0, t1; unpack8(*(const GAS u32x4*)(T1 + off + bj * HALF), t0, t1); v0 += t0; v1 += t1; }
;                     const u32x4 w = pack8(v0, v1);
;                     if (MODE == 0 && samp) asm volatile("global_store_dwordx4 %0, %1, off sc1\n\ts_nop 1" :: "v"(O + off + bj * HALF), "v"(w) : "memory");
;                     else *(GAS u32x4*)(O + off + bj * HALF) = w; } }
	s_nop 1
	v_mov_b32_e32 v50, v238
	v_mov_b32_e32 v51, v239
	v_mov_b32_e32 v52, v240
	v_mov_b32_e32 v53, v241
	v_lshlrev_b32_e32 v64, 16, v50
	v_and_b32_e32 v65, 0xffff0000, v50
	v_lshlrev_b32_e32 v50, 16, v51
	v_and_b32_e32 v51, 0xffff0000, v51
	v_lshlrev_b32_e32 v66, 16, v52
	v_and_b32_e32 v67, 0xffff0000, v52
	v_lshlrev_b32_e32 v52, 16, v53
	v_and_b32_e32 v53, 0xffff0000, v53
	s_waitcnt vmcnt(4)
	s_nop 1
	v_mov_b32_e32 v54, v242
	v_mov_b32_e32 v55, v243
	v_mov_b32_e32 v56, v244
	v_mov_b32_e32 v57, v245
	v_lshlrev_b32_e32 v68, 16, v54
	v_and_b32_e32 v69, 0xffff0000, v54
	v_lshlrev_b32_e32 v54, 16, v55
	v_and_b32_e32 v55, 0xffff0000, v55
	v_lshlrev_b32_e32 v70, 16, v56
	v_and_b32_e32 v71, 0xffff0000, v56
	v_lshlrev_b32_e32 v56, 16, v57
	v_and_b32_e32 v57, 0xffff0000, v57
	v_pk_fma_f32 v[48:49], v[48:49], v[50:51], v[54:55]
	v_pk_fma_f32 v[46:47], v[46:47], v[64:65], v[68:69]
	v_pk_fma_f32 v[50:51], v[44:45], v[52:53], v[56:57]
	v_pk_fma_f32 v[44:45], v[42:43], v[66:67], v[70:71]
	v_cvt_pk_bf16_f32 v42, v46, v47
	v_cvt_pk_bf16_f32 v43, v48, v49
	v_cvt_pk_bf16_f32 v44, v44, v45
	v_cvt_pk_bf16_f32 v45, v50, v51
	global_store_dwordx4 v[58:59], v[42:45], off
	s_nop 0
	v_add_u32_e32 v50, 0xa0, v146
	v_ashrrev_i32_e32 v51, 31, v50
	v_mad_i64_i32 v[52:53], s[0:1], v50, s95, v[148:149]
	v_lshl_add_u64 v[52:53], v[52:53], 0, v[150:151]
	v_add_co_u32_e32 v54, vcc, s19, v52
	s_waitcnt vmcnt(4)
	s_nop 1
	v_mov_b32_e32 v42, v184
	v_mov_b32_e32 v43, v185
	v_mov_b32_e32 v44, v186
	v_mov_b32_e32 v45, v187
	v_lshlrev_b32_e32 v56, 16, v42
	v_and_b32_e32 v57, 0xffff0000, v42
	s_waitcnt vmcnt(3)
	s_nop 1
	v_mov_b32_e32 v46, v188
	v_mov_b32_e32 v47, v189
	v_mov_b32_e32 v48, v190
	v_mov_b32_e32 v49, v191
	v_lshlrev_b32_e32 v62, 16, v46
	v_and_b32_e32 v63, 0xffff0000, v46
	v_lshlrev_b32_e32 v42, 16, v43
	v_and_b32_e32 v43, 0xffff0000, v43
	v_lshlrev_b32_e32 v60, 16, v44
	v_and_b32_e32 v61, 0xffff0000, v44
	v_lshlrev_b32_e32 v44, 16, v45
	v_and_b32_e32 v45, 0xffff0000, v45
	v_lshlrev_b32_e32 v46, 16, v47
	v_and_b32_e32 v47, 0xffff0000, v47
	v_lshlrev_b32_e32 v64, 16, v48
	v_and_b32_e32 v65, 0xffff0000, v48
	v_lshlrev_b32_e32 v48, 16, v49
	v_and_b32_e32 v49, 0xffff0000, v49
	v_pk_fma_f32 v[38:39], v[38:39], v[56:57], v[62:63]
	v_pk_fma_f32 v[40:41], v[40:41], v[42:43], v[46:47]
	v_pk_fma_f32 v[42:43], v[36:37], v[44:45], v[48:49]
	v_pk_fma_f32 v[36:37], v[34:35], v[60:61], v[64:65]
	v_cvt_pk_bf16_f32 v34, v38, v39
	v_lshlrev_b64 v[38:39], 11, v[50:51]
	v_lshl_add_u64 v[38:39], v[38:39], 0, v[144:145]
	v_cvt_pk_bf16_f32 v35, v40, v41
	v_cvt_pk_bf16_f32 v36, v36, v37
	v_cvt_pk_bf16_f32 v37, v42, v43
	v_lshlrev_b64 v[42:43], 1, v[38:39]
	v_addc_co_u32_e32 v55, vcc, 0, v53, vcc
	global_store_dwordx4 v[58:59], v[34:37], off offset:256
	v_lshl_add_u64 v[44:45], s[10:11], 0, v[42:43]
	global_load_dwordx4 v[222:225], v[54:55], off offset:1024
	global_load_dwordx4 v[226:229], v[44:45], off
	global_load_dwordx4 v[230:233], v[54:55], off offset:1280
	global_load_dwordx4 v[234:237], v[44:45], off offset:256
	v_add_co_u32_e32 v192, vcc, 0x34000, v54
	s_nop 1
	v_addc_co_u32_e32 v193, vcc, 0, v55, vcc
	global_load_dwordx4 v[238:241], v[192:193], off offset:1024
	v_add_co_u32_e32 v194, vcc, 0x10000, v44
	s_nop 1
	v_addc_co_u32_e32 v195, vcc, 0, v45, vcc
	global_load_dwordx4 v[242:245], v[194:195], off
	global_load_dwordx4 v[184:187], v[192:193], off offset:1280
	global_load_dwordx4 v[188:191], v[194:195], off offset:256
	v_lshl_add_u64 v[46:47], v[52:53], 0, s[2:3]
	v_lshl_add_u64 v[42:43], s[14:15], 0, v[42:43]
	s_waitcnt vmcnt(7)
	s_nop 1
	v_mov_b32_e32 v34, v222
	v_mov_b32_e32 v35, v223
	v_mov_b32_e32 v36, v224
	v_mov_b32_e32 v37, v225
	v_lshlrev_b32_e32 v48, 16, v34
	v_and_b32_e32 v49, 0xffff0000, v34
	v_lshlrev_b32_e32 v34, 16, v35
	v_and_b32_e32 v35, 0xffff0000, v35
	v_lshlrev_b32_e32 v50, 16, v36
	v_and_b32_e32 v51, 0xffff0000, v36
	v_lshlrev_b32_e32 v36, 16, v37
	v_and_b32_e32 v37, 0xffff0000, v37
	s_waitcnt vmcnt(6)
	s_nop 1
	v_mov_b32_e32 v38, v226
	v_mov_b32_e32 v39, v227
	v_mov_b32_e32 v40, v228
	v_mov_b32_e32 v41, v229
	v_lshlrev_b32_e32 v52, 16, v38
	v_and_b32_e32 v53, 0xffff0000, v38
	v_lshlrev_b32_e32 v38, 16, v39
	v_and_b32_e32 v39, 0xffff0000, v39
	v_lshlrev_b32_e32 v54, 16, v40
	v_and_b32_e32 v55, 0xffff0000, v40
	v_lshlrev_b32_e32 v40, 16, v41
	v_and_b32_e32 v41, 0xffff0000, v41
	v_pk_fma_f32 v[32:33], v[32:33], v[34:35], v[38:39]
	v_pk_fma_f32 v[30:31], v[30:31], v[48:49], v[52:53]
	v_pk_fma_f32 v[34:35], v[28:29], v[36:37], v[40:41]
	v_pk_fma_f32 v[28:29], v[26:27], v[50:51], v[54:55]
	v_cvt_pk_bf16_f32 v26, v30, v31
	v_cvt_pk_bf16_f32 v27, v32, v33
	v_cvt_pk_bf16_f32 v28, v28, v29
	v_cvt_pk_bf16_f32 v29, v34, v35
	global_store_dwordx4 v[42:43], v[26:29], off
	s_nop 0
	v_add_u32_e32 v34, 0xb0, v146
	v_ashrrev_i32_e32 v35, 31, v34
	v_mad_i64_i32 v[36:37], s[0:1], v34, s95, v[148:149]
	v_lshl_add_u64 v[36:37], v[36:37], 0, v[150:151]
	v_add_co_u32_e32 v38, vcc, s19, v36
	s_waitcnt vmcnt(6)
; #define GAS __attribute__((address_space(1)))
; __device__ __forceinline__ u32x4 pack8(f32x4 v0, f32x4 v1) { u32x4 w; w.x = cvt_pk_bf16(v0[0], v0[1]); w.y = cvt_pk_bf16(v0[2], v0[3]); w.z = cvt_pk_bf16(v1[0], v1[1]); w.w = cvt_pk_bf16(v1[2], v1[3]); return w; }
; __device__ __forceinline__ void unpack8(u32x4 w, f32x4& v0, f32x4& v1) { v0 = (f32x4){bflo(w.x), bfhi(w.x), bflo(w.y), bfhi(w.y)}; v1 = (f32x4){bflo(w.z), bfhi(w.z), bflo(w.w), bfhi(w.w)}; }
; #define PG8_BAR __builtin_amdgcn_s_barrier()
; #define GAS __attribute__((address_space(1)))
;     __device__ __forceinline__ void operator()(const f32x4 (&acc)[2][2][4][2], const Unit& u, int wr, int wc, int fr, int fq) const {
;     ...
;             for (int m = 0; m < 4; ++m) { const size_t r = (size_t)(row0 + ai * HALF + m * 16); const size_t off = r * 2048 + col0; const bf16_t* gp = P + r * NPJ + 2560 + MODE * 2048 + col0;
; #pragma unroll
;                 for (int bj = 0; bj < 2; ++bj) { f32x4 g0, g1; unpack8(*(const GAS u32x4*)(gp + bj * HALF), g0, g1);
;                     f32x4 v0 = g0 * acc[ai][bj][m][0], v1 = g1 * acc[ai][bj][m][1];
;                     if (MODE == 1) { f32x4 t0, t1; unpack8(*(const GAS u32x4*)(T1 + off + bj * HALF), t0, t1); v0 += t0; v1 += t1; }
;                     const u32x4 w = pack8(v0, v1);
;                     if (MODE == 0 && samp) asm volatile("global_store_dwordx4 %0, %1, off sc1\n\ts_nop 1" :: "v"(O + off + bj * HALF), "v"(w) : "memory");
;                     else *(GAS u32x4*)(O + off + bj * HALF) = w; } }
; template <class Epi, class Sched, bool ALIGN_EPI = false, bool SP2 = false>
; __device__ __forceinline__ void gemm_phase(PG8_LAS unsigned char* lds, const Gemm g, const Sched& S, const Epi& E) {
;     ...
;         if (!has_next) break;
; #pragma unroll
;         for (int a = 0; a < 2; ++a)
; #pragma unroll
;             for (int b = 0; b < 2; ++b)
; #pragma unroll
;                 for (int m = 0; m < 4; ++m)
; #pragma unroll
;                     for (int n = 0; n < 2; ++n) acc[a][b][m][n] = (f32x4){0.f, 0.f, 0.f, 0.f};
;         cur = nxt; cA = nA; cB = nB; ++ui;
;         if constexpr (ALIGN_EPI) { if (wr == 1) PG8_BAR; }
;     }
	s_nop 1
	v_mov_b32_e32 v26, v230
	v_mov_b32_e32 v27, v231
	v_mov_b32_e32 v28, v232
	v_mov_b32_e32 v29, v233
	v_lshlrev_b32_e32 v40, 16, v26
	v_and_b32_e32 v41, 0xffff0000, v26
	s_waitcnt vmcnt(5)
	s_nop 1
	v_mov_b32_e32 v30, v234
	v_mov_b32_e32 v31, v235
	v_mov_b32_e32 v32, v236
	v_mov_b32_e32 v33, v237
	v_lshlrev_b32_e32 v46, 16, v30
	v_and_b32_e32 v47, 0xffff0000, v30
	v_lshlrev_b32_e32 v26, 16, v27
	v_and_b32_e32 v27, 0xffff0000, v27
	v_lshlrev_b32_e32 v44, 16, v28
	v_and_b32_e32 v45, 0xffff0000, v28
	v_lshlrev_b32_e32 v28, 16, v29
	v_and_b32_e32 v29, 0xffff0000, v29
	v_lshlrev_b32_e32 v30, 16, v31
	v_and_b32_e32 v31, 0xffff0000, v31
	v_lshlrev_b32_e32 v48, 16, v32
	v_and_b32_e32 v49, 0xffff0000, v32
	v_lshlrev_b32_e32 v32, 16, v33
	v_and_b32_e32 v33, 0xffff0000, v33
	v_pk_fma_f32 v[22:23], v[22:23], v[40:41], v[46:47]
	v_pk_fma_f32 v[24:25], v[24:25], v[26:27], v[30:31]
	v_pk_fma_f32 v[26:27], v[20:21], v[28:29], v[32:33]
	v_pk_fma_f32 v[20:21], v[18:19], v[44:45], v[48:49]
	v_cvt_pk_bf16_f32 v18, v22, v23
	v_lshlrev_b64 v[22:23], 11, v[34:35]
	v_lshl_add_u64 v[22:23], v[22:23], 0, v[144:145]
	v_cvt_pk_bf16_f32 v19, v24, v25
	v_cvt_pk_bf16_f32 v20, v20, v21
	v_cvt_pk_bf16_f32 v21, v26, v27
	v_lshlrev_b64 v[26:27], 1, v[22:23]
	v_addc_co_u32_e32 v39, vcc, 0, v37, vcc
	global_store_dwordx4 v[42:43], v[18:21], off offset:256
	v_lshl_add_u64 v[28:29], s[10:11], 0, v[26:27]
	v_lshl_add_u64 v[30:31], v[36:37], 0, s[2:3]
	v_lshl_add_u64 v[26:27], s[14:15], 0, v[26:27]
	s_andn2_b64 vcc, exec, s[42:43]
	s_mov_b64 s[42:43], -1
	s_waitcnt vmcnt(5)
	s_nop 1
	v_mov_b32_e32 v18, v238
	v_mov_b32_e32 v19, v239
	v_mov_b32_e32 v20, v240
	v_mov_b32_e32 v21, v241
	v_lshlrev_b32_e32 v32, 16, v18
	v_and_b32_e32 v33, 0xffff0000, v18
	v_lshlrev_b32_e32 v18, 16, v19
	v_and_b32_e32 v19, 0xffff0000, v19
	v_lshlrev_b32_e32 v34, 16, v20
	v_and_b32_e32 v35, 0xffff0000, v20
	v_lshlrev_b32_e32 v20, 16, v21
	v_and_b32_e32 v21, 0xffff0000, v21
	s_waitcnt vmcnt(4)
	s_nop 1
	v_mov_b32_e32 v22, v242
	v_mov_b32_e32 v23, v243
	v_mov_b32_e32 v24, v244
	v_mov_b32_e32 v25, v245
	v_lshlrev_b32_e32 v36, 16, v22
	v_and_b32_e32 v37, 0xffff0000, v22
	v_lshlrev_b32_e32 v22, 16, v23
	v_and_b32_e32 v23, 0xffff0000, v23
	v_lshlrev_b32_e32 v38, 16, v24
	v_and_b32_e32 v39, 0xffff0000, v24
	v_lshlrev_b32_e32 v24, 16, v25
	v_and_b32_e32 v25, 0xffff0000, v25
	v_pk_fma_f32 v[16:17], v[16:17], v[18:19], v[22:23]
	v_pk_fma_f32 v[14:15], v[14:15], v[32:33], v[36:37]
	v_pk_fma_f32 v[18:19], v[12:13], v[20:21], v[24:25]
	v_pk_fma_f32 v[12:13], v[10:11], v[34:35], v[38:39]
	v_cvt_pk_bf16_f32 v10, v14, v15
	v_cvt_pk_bf16_f32 v11, v16, v17
	v_cvt_pk_bf16_f32 v12, v12, v13
	v_cvt_pk_bf16_f32 v13, v18, v19
	global_store_dwordx4 v[26:27], v[10:13], off
	s_nop 0
	s_waitcnt vmcnt(4)
	s_nop 1
	v_mov_b32_e32 v10, v184
	v_mov_b32_e32 v11, v185
	v_mov_b32_e32 v12, v186
	v_mov_b32_e32 v13, v187
	v_lshlrev_b32_e32 v18, 16, v10
	v_and_b32_e32 v19, 0xffff0000, v10
	v_lshlrev_b32_e32 v10, 16, v11
	v_and_b32_e32 v11, 0xffff0000, v11
	v_lshlrev_b32_e32 v20, 16, v12
	v_and_b32_e32 v21, 0xffff0000, v12
	v_lshlrev_b32_e32 v12, 16, v13
	v_and_b32_e32 v13, 0xffff0000, v13
	s_waitcnt vmcnt(3)
	s_nop 1
	v_mov_b32_e32 v14, v188
	v_mov_b32_e32 v15, v189
	v_mov_b32_e32 v16, v190
	v_mov_b32_e32 v17, v191
	v_lshlrev_b32_e32 v22, 16, v14
	v_and_b32_e32 v23, 0xffff0000, v14
	v_lshlrev_b32_e32 v14, 16, v15
	v_and_b32_e32 v15, 0xffff0000, v15
	v_lshlrev_b32_e32 v24, 16, v16
	v_and_b32_e32 v25, 0xffff0000, v16
	v_lshlrev_b32_e32 v16, 16, v17
	v_and_b32_e32 v17, 0xffff0000, v17
	v_pk_fma_f32 v[8:9], v[8:9], v[10:11], v[14:15]
	v_pk_fma_f32 v[6:7], v[6:7], v[18:19], v[22:23]
	v_pk_fma_f32 v[10:11], v[4:5], v[12:13], v[16:17]
	v_pk_fma_f32 v[4:5], v[2:3], v[20:21], v[24:25]
	v_cvt_pk_bf16_f32 v2, v6, v7
	v_cvt_pk_bf16_f32 v3, v8, v9
	v_cvt_pk_bf16_f32 v4, v4, v5
	v_cvt_pk_bf16_f32 v5, v10, v11
	global_store_dwordx4 v[26:27], v[2:5], off offset:256
	s_cbranch_vccnz .LBB0_1148
	s_andn2_b64 vcc, exec, s[12:13]
	s_branch .LBB0_1147

; #define PG8_WAIT_V(n) asm volatile("s_waitcnt vmcnt(" #n ")" ::: "memory")
; template <class Epi, class Sched, bool ALIGN_EPI = false, bool SP2 = false>
; __device__ __forceinline__ void gemm_phase(PG8_LAS unsigned char* lds, const Gemm g, const Sched& S, const Epi& E) {
;     ...
;     for (int i = 0; i < 2; ++i) { int R, C; stage_rc(tid * 16 + i * 8192, R, C); const int Rb = Epi::PERM ? ((R & ~31) + perm32(R & 31)) : R;
;         voffA[i] = (unsigned)(R * K + C) * 2u; voffB[i] = (unsigned)(Rb * K + C) * 2u; }
;     const size_t kstep = (size_t)(BK * 2);
;     const size_t hstep = (size_t)HALF * K * 2;
;     const size_t tstep = 2 * hstep;
;     const unsigned ldsw = (unsigned)wid * 1024u;
;     const int aoff = lds_byte(wr * 64 + fr, fq * 8), boff = lds_byte(wc * 32 + fr, fq * 8);
;     ...
;     { const int rot0 = cur.krot, nt0 = cur.nkt; const char* sA0 = PG8_KP(cA, 0, rot0, nt0); const char* sA1 = PG8_KP(cA, 1, rot0, nt0); const char* sB0 = PG8_KP(cB, 0, rot0, nt0); const char* sB1 = PG8_KP(cB, 1, rot0, nt0);
;     if constexpr (SP2) {
;         PG8_STAGEB(PG8_SB(0, 0), sB0, voffB); PG8_STAGEB(PG8_SB(0, 1), sB0 + hstep, voffB); PG8_STAGE(PG8_SA(0, 0), sA0, voffA); PG8_STAGE(PG8_SA(0, 1), sA0 + hstep, voffA);
;         if (wr == 1) PG8_BAR;
;         PG8_WAIT_V(2); PG8_BAR;
;         PG8_STAGEB(PG8_SB(1, 0), sB1, voffB); PG8_STAGE(PG8_SA(1, 0), sA1, voffA); PG8_STAGEB(PG8_SB(1, 1), sB1 + hstep, voffB);
;         PG8_WAIT_V(6); PG8_BAR;
;     } else {
;         PG8_STAGEB(PG8_SB(0, 0), sB0, voffB); PG8_STAGE(PG8_SA(0, 0), sA0, voffA); PG8_STAGEB(PG8_SB(0, 1), sB0 + hstep, voffB); PG8_STAGE(PG8_SA(0, 1), sA0 + hstep, voffA);
;         if (wr == 1) PG8_BAR;
;         PG8_WAIT_V(4); PG8_BAR;
;         PG8_STAGEB(PG8_SB(1, 0), sB1, voffB); PG8_STAGE(PG8_SA(1, 0), sA1, voffA); PG8_STAGEB(PG8_SB(1, 1), sB1 + hstep, voffB);
;         PG8_WAIT_V(6); PG8_BAR;
;     }
; __global__ void __launch_bounds__(NWAVES * 64, 2) enc_fwd(Args args) {
;     ...
;         if (EN(7) && IN(pb + 6)) { for (int rep = 0; rep < NREP(7); ++rep) { FRESH_WS(); pg8::Gemm g{MX, (const bf16*)(ws + WS_WOUT + l * SZ_WOUT), NTOK, 2048, 2048}; pg8::SplitOrder S; S.init(2048, G, bx);
;             pg8::EpiRes E{(NREP(7) == 2 && rep == 0) ? (bf16*)(ws + WS_ACT) : XB, nullptr, MODL + 4096, SL};
;             pg8::gemm_phase<pg8::EpiRes, pg8::SplitOrder, PG8_ALIGN, PG8_SP2>(lds + RING_OFF, g, S, E); } SEAM(pb + 6); }
.LBB0_1290:
	v_readlane_b32 s0, v252, 26
	v_readlane_b32 s1, v252, 27
	s_andn2_b64 vcc, exec, s[4:5]
	s_nop 0
	v_cndmask_b32_e64 v1, 0, 1, s[0:1]
	v_cmp_ne_u32_e64 s[0:1], 1, v1
	s_nop 1
	v_writelane_b32 v254, s0, 58
	s_nop 1
	v_writelane_b32 v254, s1, 59
	s_cbranch_vccnz .LBB0_1377
	v_readlane_b32 s0, v254, 58
	s_mov_b64 s[8:9], s[66:67]
	v_mov_b32_e32 v16, v0
	v_readlane_b32 s1, v254, 59
	s_and_b64 vcc, exec, s[0:1]
	v_readfirstlane_b32 s10, v16
	s_cbranch_vccnz .LBB0_1323
	v_lshlrev_b32_e32 v1, 4, v16
	v_add_u32_e32 v2, 0x2000, v1
	v_ashrrev_i32_e32 v3, 31, v2
	v_lshrrev_b32_e32 v3, 22, v3
	v_add_u32_e32 v3, v2, v3
	v_ashrrev_i32_e32 v10, 10, v3
	v_mul_i32_i24_e32 v3, 0x400, v10
	v_sub_u32_e32 v2, v2, v3
	v_lshrrev_b32_e32 v3, 4, v2
	v_bitop3_b32 v2, v3, v2, 32 bitop3:0x6c
	v_ashrrev_i32_e32 v3, 31, v2
	v_lshrrev_b32_e32 v3, 26, v3
	v_add_u32_e32 v3, v2, v3
	v_lshlrev_b32_e32 v4, 3, v10
	v_ashrrev_i32_e32 v11, 6, v3
	v_and_b32_e32 v4, -16, v4
	v_add_u32_e32 v4, v11, v4
	v_and_b32_e32 v5, 3, v11
	s_mov_b32 s2, 0xfffe0
	v_lshrrev_b32_e32 v6, 2, v4
	v_lshlrev_b32_e32 v7, 1, v4
	v_and_b32_e32 v3, 0xc0, v3
	v_and_or_b32 v5, v4, s2, v5
	v_and_b32_e32 v6, 4, v6
	v_and_b32_e32 v7, 24, v7
	v_sub_u32_e32 v2, v2, v3
	v_or3_b32 v5, v5, v6, v7
	v_lshlrev_b32_e32 v6, 5, v10
	v_ashrrev_i16_sdwa v2, v207, sext(v2) dst_sel:DWORD dst_unused:UNUSED_PAD src0_sel:DWORD src1_sel:BYTE_0
	v_and_b32_e32 v6, 32, v6
	v_bfe_i32 v12, v2, 0, 16
	v_add_lshl_u32 v2, v6, v12, 1
	v_lshl_add_u32 v152, v5, 12, v2
	v_lshl_add_u32 v154, v4, 12, v2
	v_bfe_i32 v2, v16, 27, 1
	v_lshrrev_b32_e32 v2, 22, v2
	v_readlane_b32 s64, v254, 53
	v_add_u32_e32 v2, v1, v2
	v_readlane_b32 s65, v254, 54
	v_and_b32_e32 v2, 0xfffffc00, v2
	s_mov_b32 s65, s79
	v_sub_u32_e32 v1, v1, v2
	s_lshl_b64 s[0:1], s[64:65], 23
	v_lshrrev_b32_e32 v2, 4, v1
	v_ashrrev_i32_e32 v3, 31, v16
	s_add_u32 s30, s8, 0x2d180000
	v_bitop3_b32 v1, v2, v1, 32 bitop3:0x6c
	v_lshrrev_b32_e32 v3, 26, v3
	s_addc_u32 s31, s9, 0
	v_ashrrev_i32_e32 v2, 31, v1
	v_add_u32_e32 v3, v16, v3
	s_add_u32 s0, s8, s0
	v_lshrrev_b32_e32 v2, 26, v2
	v_ashrrev_i32_e32 v14, 6, v3
	s_addc_u32 s1, s9, s1
	v_add_u32_e32 v2, v1, v2
	v_lshlrev_b32_e32 v3, 3, v14
	s_add_u32 s33, s0, 0xa000000
	v_ashrrev_i32_e32 v13, 6, v2
	v_and_b32_e32 v3, -16, v3
	s_addc_u32 s48, s1, 0
	s_ashr_i32 s0, s10, 6
	v_add_u32_e32 v3, v13, v3
	v_and_b32_e32 v4, 3, v13
	s_ashr_i32 s1, s10, 8
	s_lshl_b32 s49, s0, 10
	v_and_or_b32 v4, v3, s2, v4
	v_readlane_b32 s2, v252, 58
	s_add_u32 s2, s30, s2
	v_lshrrev_b32_e32 v5, 2, v3
	v_lshlrev_b32_e32 v6, 1, v3
	v_and_b32_e32 v2, 0xc0, v2
	s_addc_u32 s4, s31, 0
	v_readlane_b32 s3, v252, 60
	v_and_b32_e32 v5, 4, v5
	v_and_b32_e32 v6, 24, v6
	v_sub_u32_e32 v1, v1, v2
	s_add_u32 s5, s33, s3
	v_or3_b32 v4, v4, v5, v6
	v_lshlrev_b32_e32 v5, 5, v14
	v_ashrrev_i16_sdwa v1, v207, sext(v1) dst_sel:DWORD dst_unused:UNUSED_PAD src0_sel:DWORD src1_sel:BYTE_0
	s_addc_u32 s6, s48, 0
	v_readlane_b32 s3, v252, 41
	v_and_b32_e32 v5, 32, v5
	v_bfe_i32 v15, v1, 0, 16
	s_add_u32 s34, s5, s3
	v_add_lshl_u32 v1, v5, v15, 1
	s_addc_u32 s35, s6, 0
	s_add_i32 s50, s49, 0
	v_lshl_add_u32 v156, v4, 12, v1
	s_add_i32 m0, s50, 0x10000
	v_lshl_add_u32 v158, v3, 12, v1
	global_load_lds_dwordx4 v156, s[34:35]
	s_add_i32 m0, s50, 0x12000
	s_add_u32 s40, s2, s3
	s_addc_u32 s41, s4, 0
	s_add_u32 s4, s34, 0x80000
	global_load_lds_dwordx4 v152, s[34:35]
	s_addc_u32 s5, s35, 0
	s_add_i32 m0, s50, 0x14000
	s_add_i32 s51, s50, 0x2000
	global_load_lds_dwordx4 v156, s[4:5]
	s_add_i32 m0, s50, 0x16000
	v_mov_b32_e32 v157, v98
	global_load_lds_dwordx4 v152, s[4:5]
	s_mov_b32 m0, s50
	s_add_u32 s4, s40, 0x80000
	global_load_lds_dwordx4 v158, s[40:41]
	s_mov_b32 m0, s51
	s_addc_u32 s5, s41, 0
	s_add_i32 s52, s50, 0x4000
	global_load_lds_dwordx4 v154, s[40:41]
	s_mov_b32 m0, s52
	s_add_i32 s53, s50, 0x6000
	global_load_lds_dwordx4 v158, s[4:5]
	s_mov_b32 m0, s53
	v_mov_b32_e32 v153, v98
	global_load_lds_dwordx4 v154, s[4:5]
	v_mov_b32_e32 v159, v98
	v_mov_b32_e32 v155, v98
	s_cmp_eq_u32 s1, 1
	v_lshl_add_u64 v[8:9], s[34:35], 0, v[156:157]
	v_lshl_add_u64 v[6:7], s[34:35], 0, v[152:153]
	v_lshl_add_u64 v[2:3], s[40:41], 0, v[158:159]
	s_cselect_b64 s[4:5], -1, 0
	s_cmp_lg_u32 s1, 1
	v_lshl_add_u64 v[4:5], s[40:41], 0, v[154:155]
.LBB0_1294:
	s_add_u32 s6, s8, 0x39880000
	s_mul_i32 s11, s64, 0xf0000
	s_addc_u32 s7, s9, 0
	s_mul_hi_u32 s2, s64, 0xf0000
	s_add_u32 s11, s8, s11
	s_addc_u32 s2, s9, s2
	s_add_u32 s54, s11, 0x104000
	s_addc_u32 s55, s2, 0
	s_add_u32 s56, s8, 0x35880000
	v_lshrrev_b32_e32 v17, 1, v16
	s_addc_u32 s57, s9, 0
	v_and_b32_e32 v17, 24, v17
	s_lshl_b32 s0, s0, 5
	v_and_b32_e32 v1, 15, v16
	v_lshlrev_b32_e32 v18, 1, v17
	v_lshlrev_b32_e32 v16, 2, v16
	s_and_b32 s2, s0, 0x60
	s_add_i32 m0, s50, 0x18000
	v_lshl_add_u64 v[8:9], v[8:9], 0, s[76:77]
	s_lshl_b32 s58, s1, 6
	v_lshl_or_b32 v18, v1, 6, v18
	s_lshl_b32 s1, s1, 13
	v_and_b32_e32 v16, 32, v16
	s_lshl_b32 s0, s2, 7
	global_load_lds_dwordx4 v[8:9], off
	v_lshl_add_u64 v[6:7], v[6:7], 0, s[76:77]
	s_add_i32 m0, s50, 0x1a000
	s_add_i32 s59, s50, 0x8000
	s_add_i32 s60, s50, 0xa000
	v_bitop3_b32 v99, v18, s0, v16 bitop3:0xde
	global_load_lds_dwordx4 v[6:7], off
	v_lshl_add_u64 v[2:3], v[2:3], 0, s[76:77]
	s_mov_b32 m0, s59
	s_add_u32 s0, s34, 0x80080
	v_bitop3_b32 v19, v18, s1, v16 bitop3:0xde
	global_load_lds_dwordx4 v[2:3], off
	v_lshl_add_u64 v[2:3], v[4:5], 0, s[76:77]
	s_mov_b32 m0, s60
	s_addc_u32 s1, s35, 0
	global_load_lds_dwordx4 v[2:3], off
	s_add_i32 m0, s50, 0x1c000
	v_lshl_add_u64 v[2:3], s[0:1], 0, v[156:157]
	global_load_lds_dwordx4 v[2:3], off
	v_lshl_add_u64 v[2:3], s[0:1], 0, v[152:153]
	s_add_i32 m0, s50, 0x1e000
	s_cmpk_lt_u32 s10, 0x100
	global_load_lds_dwordx4 v[2:3], off
	v_lshlrev_b32_e32 v2, 15, v10
	v_and_b32_e32 v2, 0xffff0000, v2
	v_lshl_add_u32 v2, v11, 12, v2
	v_and_b32_e32 v3, 1, v10
	v_lshl_or_b32 v2, v3, 6, v2
	v_lshl_add_u32 v160, v12, 1, v2
	v_lshlrev_b32_e32 v2, 15, v14
	v_and_b32_e32 v2, 0xffff0000, v2
	s_waitcnt vmcnt(6)
	v_lshl_add_u32 v2, v13, 12, v2
	v_and_b32_e32 v3, 1, v14
	v_lshl_or_b32 v2, v3, 6, v2
	v_readlane_b32 s0, v252, 45
	s_cselect_b64 s[8:9], -1, 0
	v_or_b32_e32 v180, s2, v17
	v_mov_b32_e32 v161, v98
	v_lshl_add_u32 v162, v15, 1, v2
	v_mov_b32_e32 v163, v98
	s_mov_b32 s61, 0
	v_add_u32_e32 v181, 0, v19
	s_mov_b32 s78, s0
	v_readlane_b32 s71, v252, 46
	v_readlane_b32 s70, v252, 59
	v_readlane_b32 s69, v252, 57
	s_mov_b32 s3, 0x20000
	s_mov_b32 s46, 0x30000
	s_barrier
	s_branch .LBB0_1297

; #define PG8_BAR __builtin_amdgcn_s_barrier()
; template <class Epi, class Sched, bool ALIGN_EPI = false, bool SP2 = false>
; __device__ __forceinline__ void gemm_phase(PG8_LAS unsigned char* lds, const Gemm g, const Sched& S, const Epi& E) {
;     ...
;         if constexpr (ALIGN_EPI) { if (wr == 1) PG8_BAR; }
.LBB0_1320:
	s_andn2_b64 vcc, exec, s[4:5]
	s_branch .LBB0_1295

;     __host__ __device__ void init(int M, int N, int K, int G_, int c_) { so.init(M, N, K, G_, c_); nN = N / BM; nkt = K / BK; G = G_; c = c_; }
; template <class Epi, class Sched, bool ALIGN_EPI = false, bool SP2 = false>
; __device__ __forceinline__ void gemm_phase(PG8_LAS unsigned char* lds, const Gemm g, const Sched& S, const Epi& E) {
;     ...
;     for (int i = 0; i < 2; ++i) { int R, C; stage_rc(tid * 16 + i * 8192, R, C); const int Rb = Epi::PERM ? ((R & ~31) + perm32(R & 31)) : R;
;         voffA[i] = (unsigned)(R * K + C) * 2u; voffB[i] = (unsigned)(Rb * K + C) * 2u; }
;     const size_t kstep = (size_t)(BK * 2);
;     const size_t hstep = (size_t)HALF * K * 2;
;     const size_t tstep = 2 * hstep;
;     const unsigned ldsw = (unsigned)wid * 1024u;
;     const int aoff = lds_byte(wr * 64 + fr, fq * 8), boff = lds_byte(wc * 32 + fr, fq * 8);
;     ...
;     { const int rot0 = cur.krot, nt0 = cur.nkt; const char* sA0 = PG8_KP(cA, 0, rot0, nt0); const char* sA1 = PG8_KP(cA, 1, rot0, nt0); const char* sB0 = PG8_KP(cB, 0, rot0, nt0); const char* sB1 = PG8_KP(cB, 1, rot0, nt0);
;     if constexpr (SP2) {
;         PG8_STAGEB(PG8_SB(0, 0), sB0, voffB); PG8_STAGEB(PG8_SB(0, 1), sB0 + hstep, voffB); PG8_STAGE(PG8_SA(0, 0), sA0, voffA); PG8_STAGE(PG8_SA(0, 1), sA0 + hstep, voffA);
;         if (wr == 1) PG8_BAR;
;         PG8_WAIT_V(2); PG8_BAR;
;         PG8_STAGEB(PG8_SB(1, 0), sB1, voffB); PG8_STAGE(PG8_SA(1, 0), sA1, voffA); PG8_STAGEB(PG8_SB(1, 1), sB1 + hstep, voffB);
;         PG8_WAIT_V(6); PG8_BAR;
;     } else {
;         PG8_STAGEB(PG8_SB(0, 0), sB0, voffB); PG8_STAGE(PG8_SA(0, 0), sA0, voffA); PG8_STAGEB(PG8_SB(0, 1), sB0 + hstep, voffB); PG8_STAGE(PG8_SA(0, 1), sA0 + hstep, voffA);
;         if (wr == 1) PG8_BAR;
;         PG8_WAIT_V(4); PG8_BAR;
;         PG8_STAGEB(PG8_SB(1, 0), sB1, voffB); PG8_STAGE(PG8_SA(1, 0), sA1, voffA); PG8_STAGEB(PG8_SB(1, 1), sB1 + hstep, voffB);
;         PG8_WAIT_V(6); PG8_BAR;
;     }
; __global__ void __launch_bounds__(NWAVES * 64, 2) enc_fwd(Args args) {
;     ...
;         if (EN(9) && IN(pb + 8)) { for (int rep = 0; rep < NREP(9); ++rep) { FRESH_WS(); pg8::Gemm g{H, (const bf16*)(ws + WS_WGU + l * SZ_WGU), NTOK, 11264, 2048}; pg8::StaticOrder S; S.init(NTOK, 11264, 2048, G, bx);
;             pg8::EpiFU E{ACT};
;             pg8::gemm_phase<pg8::EpiFU, pg8::StaticOrder, PG8_ALIGN, PG8_SP2>(lds + RING_OFF, g, S, E);
.LBB0_1448:
	s_andn2_b64 vcc, exec, s[4:5]
	s_cbranch_vccnz .LBB0_1637
	v_readlane_b32 s0, v254, 53
	v_readlane_b32 s1, v254, 54
	s_mul_i32 s33, s0, 0x2c00000
	s_mov_b64 s[4:5], s[66:67]
	v_readlane_b32 s0, v252, 28
	s_add_u32 s89, s4, 0xc000000
	v_mov_b32_e32 v16, v0
	v_readlane_b32 s1, v252, 29
	s_addc_u32 s96, s5, 0
	s_andn2_b64 vcc, exec, s[0:1]
	v_readfirstlane_b32 s10, v16
	s_cbranch_vccnz .LBB0_1465
	v_lshlrev_b32_e32 v1, 4, v16
	v_add_u32_e32 v2, 0x2000, v1
	v_ashrrev_i32_e32 v3, 31, v2
	v_lshrrev_b32_e32 v3, 22, v3
	v_add_u32_e32 v3, v2, v3
	v_ashrrev_i32_e32 v10, 10, v3
	v_mul_i32_i24_e32 v3, 0x400, v10
	v_sub_u32_e32 v2, v2, v3
	v_lshrrev_b32_e32 v3, 4, v2
	v_bitop3_b32 v2, v3, v2, 32 bitop3:0x6c
	v_ashrrev_i32_e32 v3, 31, v2
	v_lshrrev_b32_e32 v3, 26, v3
	v_add_u32_e32 v3, v2, v3
	v_lshlrev_b32_e32 v4, 3, v10
	v_ashrrev_i32_e32 v11, 6, v3
	v_and_b32_e32 v4, -16, v4
	v_add_u32_e32 v4, v11, v4
	v_and_b32_e32 v5, 3, v11
	s_mov_b32 s2, 0xfffe0
	v_lshrrev_b32_e32 v6, 2, v4
	v_lshlrev_b32_e32 v7, 1, v4
	v_and_b32_e32 v3, 0xc0, v3
	v_and_or_b32 v5, v4, s2, v5
	v_and_b32_e32 v6, 4, v6
	v_and_b32_e32 v7, 24, v7
	v_sub_u32_e32 v2, v2, v3
	v_or3_b32 v5, v5, v6, v7
	v_lshlrev_b32_e32 v6, 5, v10
	v_ashrrev_i16_sdwa v2, v207, sext(v2) dst_sel:DWORD dst_unused:UNUSED_PAD src0_sel:DWORD src1_sel:BYTE_0
	v_and_b32_e32 v6, 32, v6
	v_bfe_i32 v12, v2, 0, 16
	v_add_lshl_u32 v2, v6, v12, 1
	s_waitcnt vmcnt(0)
	v_lshl_add_u32 v132, v5, 12, v2
	v_lshl_add_u32 v134, v4, 12, v2
	v_bfe_i32 v2, v16, 27, 1
	v_lshrrev_b32_e32 v2, 22, v2
	v_add_u32_e32 v2, v1, v2
	v_and_b32_e32 v2, 0xfffffc00, v2
	v_sub_u32_e32 v1, v1, v2
	v_lshrrev_b32_e32 v2, 4, v1
	v_ashrrev_i32_e32 v3, 31, v16
	v_bitop3_b32 v1, v2, v1, 32 bitop3:0x6c
	v_lshrrev_b32_e32 v3, 26, v3
	v_ashrrev_i32_e32 v2, 31, v1
	v_add_u32_e32 v3, v16, v3
	v_lshrrev_b32_e32 v2, 26, v2
	v_ashrrev_i32_e32 v14, 6, v3
	v_add_u32_e32 v2, v1, v2
	v_lshlrev_b32_e32 v3, 3, v14
	s_add_u32 s52, s4, 0x1c800000
	v_ashrrev_i32_e32 v13, 6, v2
	v_and_b32_e32 v3, -16, v3
	s_addc_u32 s53, s5, 0
	v_add_u32_e32 v3, v13, v3
	s_add_u32 s54, s89, s33
	v_and_b32_e32 v4, 3, v13
	v_lshrrev_b32_e32 v5, 2, v3
	v_lshlrev_b32_e32 v6, 1, v3
	v_and_b32_e32 v2, 0xc0, v2
	s_addc_u32 s55, s96, 0
	s_ashr_i32 s0, s10, 6
	v_and_or_b32 v4, v3, s2, v4
	v_and_b32_e32 v5, 4, v5
	v_and_b32_e32 v6, 24, v6
	v_sub_u32_e32 v1, v1, v2
	s_ashr_i32 s1, s10, 8
	s_lshl_b32 s56, s0, 10
	v_or3_b32 v4, v4, v5, v6
	v_lshlrev_b32_e32 v5, 5, v14
	v_ashrrev_i16_sdwa v1, v207, sext(v1) dst_sel:DWORD dst_unused:UNUSED_PAD src0_sel:DWORD src1_sel:BYTE_0
	v_readlane_b32 s2, v252, 35
	v_and_b32_e32 v5, 32, v5
	v_bfe_i32 v15, v1, 0, 16
	v_readlane_b32 s3, v252, 36
	s_add_u32 s34, s54, s2
	v_add_lshl_u32 v1, v5, v15, 1
	s_addc_u32 s35, s55, s3
	s_add_i32 s57, s56, 0
	v_lshl_add_u32 v136, v4, 12, v1
	s_add_i32 m0, s57, 0x10000
	v_readlane_b32 s2, v252, 39
	global_load_lds_dwordx4 v136, s[34:35]
	s_add_i32 m0, s57, 0x12000
	v_readlane_b32 s3, v252, 40
	s_add_u32 s40, s52, s2
	s_addc_u32 s41, s53, s3
	s_add_u32 s6, s34, 0x80000
	global_load_lds_dwordx4 v132, s[34:35]
	s_addc_u32 s7, s35, 0
	s_add_i32 m0, s57, 0x14000
	s_add_i32 s58, s57, 0x2000
	global_load_lds_dwordx4 v136, s[6:7]
	s_add_i32 m0, s57, 0x16000
	v_lshl_add_u32 v138, v3, 12, v1
	global_load_lds_dwordx4 v132, s[6:7]
	s_mov_b32 m0, s57
	s_add_u32 s6, s40, 0x80000
	global_load_lds_dwordx4 v138, s[40:41]
	s_mov_b32 m0, s58
	s_addc_u32 s7, s41, 0
	s_add_i32 s59, s57, 0x4000
	global_load_lds_dwordx4 v134, s[40:41]
	s_mov_b32 m0, s59
	s_add_i32 s60, s57, 0x6000
	global_load_lds_dwordx4 v138, s[6:7]
	s_mov_b32 m0, s60
	v_mov_b32_e32 v137, v98
	global_load_lds_dwordx4 v134, s[6:7]
	v_mov_b32_e32 v133, v98
	v_mov_b32_e32 v139, v98
	v_mov_b32_e32 v135, v98
	s_cmp_eq_u32 s1, 1
	v_lshl_add_u64 v[8:9], s[34:35], 0, v[136:137]
	v_lshl_add_u64 v[6:7], s[34:35], 0, v[132:133]
	v_lshl_add_u64 v[2:3], s[40:41], 0, v[138:139]
	s_cselect_b64 s[6:7], -1, 0
	s_cmp_lg_u32 s1, 1
	v_lshl_add_u64 v[4:5], s[40:41], 0, v[134:135]
.LBB0_1452:
	s_add_u32 s8, s4, 0x2f580000
	v_lshrrev_b32_e32 v18, 1, v16
	s_addc_u32 s9, s5, 0
	v_and_b32_e32 v18, 24, v18
	s_lshl_b32 s0, s0, 5
	v_and_b32_e32 v17, 15, v16
	v_lshlrev_b32_e32 v19, 1, v18
	v_lshlrev_b32_e32 v16, 2, v16
	s_and_b32 s2, s0, 0x60
	s_add_i32 m0, s57, 0x18000
	v_lshl_add_u64 v[8:9], v[8:9], 0, s[76:77]
	v_lshl_or_b32 v1, s1, 6, v17
	v_lshl_or_b32 v17, v17, 6, v19
	s_lshl_b32 s1, s1, 13
	v_and_b32_e32 v16, 32, v16
	s_lshl_b32 s0, s2, 7
	global_load_lds_dwordx4 v[8:9], off
	v_lshl_add_u64 v[6:7], v[6:7], 0, s[76:77]
	s_add_i32 m0, s57, 0x1a000
	s_add_i32 s61, s57, 0x8000
	s_add_i32 s62, s57, 0xa000
	v_bitop3_b32 v99, v17, s0, v16 bitop3:0xde
	global_load_lds_dwordx4 v[6:7], off
	s_add_u32 s0, s34, 0x80080
	v_bitop3_b32 v19, v17, s1, v16 bitop3:0xde
	s_addc_u32 s1, s35, 0
	s_add_i32 m0, s57, 0x1c000
	v_lshl_add_u64 v[2:3], s[0:1], 0, v[136:137]
	global_load_lds_dwordx4 v[2:3], off
	v_lshl_add_u64 v[2:3], s[0:1], 0, v[132:133]
	s_add_i32 m0, s57, 0x1e000
	s_cmpk_lt_u32 s10, 0x100
	global_load_lds_dwordx4 v[2:3], off
	v_lshlrev_b32_e32 v2, 15, v10
	v_and_b32_e32 v2, 0xffff0000, v2
	v_lshl_add_u32 v2, v11, 12, v2
	v_and_b32_e32 v3, 1, v10
	v_lshl_or_b32 v2, v3, 6, v2
	v_lshl_add_u32 v140, v12, 1, v2
	v_lshlrev_b32_e32 v2, 15, v14
	v_and_b32_e32 v2, 0xffff0000, v2
	s_waitcnt vmcnt(4)
	v_lshl_add_u32 v2, v13, 12, v2
	v_and_b32_e32 v3, 1, v14
	v_lshl_or_b32 v2, v3, 6, v2
	v_readlane_b32 s0, v252, 37
	s_cselect_b64 s[10:11], -1, 0
	v_or_b32_e32 v148, s2, v18
	v_mov_b32_e32 v141, v98
	v_lshl_add_u32 v142, v15, 1, v2
	v_mov_b32_e32 v143, v98
	s_mov_b32 s63, 0
	v_add_u32_e32 v149, 0, v19
	v_readlane_b32 s69, v253, 6
	s_mov_b32 s70, s0
	s_movk_i32 s3, 0xc7
	s_mov_b32 s64, 0x58000
	s_mov_b32 s65, 0x2c000
	s_mov_b32 s66, 0x84000
	s_barrier
	v_readlane_b32 s1, v252, 38
	s_branch .LBB0_1455

; __device__ __forceinline__ u32x4 pack8(f32x4 v0, f32x4 v1) { u32x4 w; w.x = cvt_pk_bf16(v0[0], v0[1]); w.y = cvt_pk_bf16(v0[2], v0[3]); w.z = cvt_pk_bf16(v1[0], v1[1]); w.w = cvt_pk_bf16(v1[2], v1[3]); return w; }
;     __device__ __forceinline__ void operator()(const f32x4 (&acc)[2][2][4][2], const Unit& u, int wr, int wc, int fr, int fq) const {
;         const int row0 = u.pm * BM + wr * 64 + fr, col0 = u.pn * HALF + wc * 32 + 8 * fq;
;         bf16_t* const p0 = ACT + (size_t)row0 * 5632 + col0;
; #pragma unroll
;         for (int ai = 0; ai < 2; ++ai)
; #pragma unroll
;             for (int m = 0; m < 4; ++m) {
;                 const f32x4 g0 = acc[ai][0][m][0], g1 = acc[ai][0][m][1];
;                 const f32x4 v0 = g0 * sigmoid4(g0) * acc[ai][1][m][0], v1 = g1 * sigmoid4(g1) * acc[ai][1][m][1];
;                 store16_wt(p0 + (size_t)(ai * HALF + m * 16) * 5632, pack8(v0, v1)); }
.LBB0_1461:
	v_pk_mul_f32 v[146:147], v[128:129], s[74:75] op_sel_hi:[1,0]
	v_pk_mul_f32 v[150:151], v[130:131], s[74:75] op_sel_hi:[1,0]
	v_exp_f32_e32 v146, v146
	v_exp_f32_e32 v147, v147
	v_exp_f32_e32 v150, v150
	v_exp_f32_e32 v151, v151
	s_mov_b32 s0, 0x160000
	v_pk_add_f32 v[146:147], v[146:147], 1.0 op_sel_hi:[1,0]
	s_mov_b64 s[34:35], -1
	v_pk_add_f32 v[150:151], v[150:151], 1.0 op_sel_hi:[1,0]
	v_rcp_f32_e32 v146, v146
	v_rcp_f32_e32 v147, v147
	v_rcp_f32_e32 v150, v150
	v_rcp_f32_e32 v151, v151
	v_pk_mul_f32 v[128:129], v[128:129], v[146:147]
	s_nop 0
	v_pk_mul_f32 v[124:125], v[124:125], v[128:129]
	v_pk_mul_f32 v[130:131], v[130:131], v[150:151]
	v_pk_mul_f32 v[128:129], v[120:121], s[74:75] op_sel_hi:[1,0]
	v_pk_mul_f32 v[126:127], v[126:127], v[130:131]
	v_pk_mul_f32 v[130:131], v[122:123], s[74:75] op_sel_hi:[1,0]
	v_exp_f32_e32 v128, v128
	v_exp_f32_e32 v129, v129
	v_exp_f32_e32 v130, v130
	v_exp_f32_e32 v131, v131
	v_pk_add_f32 v[128:129], v[128:129], 1.0 op_sel_hi:[1,0]
	s_nop 0
	v_rcp_f32_e32 v128, v128
	v_pk_add_f32 v[130:131], v[130:131], 1.0 op_sel_hi:[1,0]
	v_rcp_f32_e32 v129, v129
	v_rcp_f32_e32 v130, v130
	v_rcp_f32_e32 v131, v131
	v_pk_mul_f32 v[120:121], v[120:121], v[128:129]
	v_pk_mul_f32 v[122:123], v[122:123], v[130:131]
	s_nop 0
	v_pk_mul_f32 v[122:123], v[118:119], v[122:123]
	v_pk_mul_f32 v[118:119], v[116:117], v[120:121]
	v_cvt_pk_bf16_f32 v116, v124, v125
	v_cvt_pk_bf16_f32 v117, v126, v127
	v_cvt_pk_bf16_f32 v118, v118, v119
	v_cvt_pk_bf16_f32 v119, v122, v123
	global_store_dwordx4 v[144:145], v[116:119], off sc1
	s_nop 1
	v_pk_mul_f32 v[116:117], v[112:113], s[74:75] op_sel_hi:[1,0]
	v_pk_mul_f32 v[118:119], v[114:115], s[74:75] op_sel_hi:[1,0]
	v_exp_f32_e32 v116, v116
	v_exp_f32_e32 v117, v117
	v_exp_f32_e32 v118, v118
	v_exp_f32_e32 v119, v119
	v_pk_add_f32 v[116:117], v[116:117], 1.0 op_sel_hi:[1,0]
	s_nop 0
	v_rcp_f32_e32 v116, v116
	v_pk_add_f32 v[118:119], v[118:119], 1.0 op_sel_hi:[1,0]
	v_rcp_f32_e32 v117, v117
	v_rcp_f32_e32 v118, v118
	v_rcp_f32_e32 v119, v119
	v_pk_mul_f32 v[112:113], v[112:113], v[116:117]
	s_nop 0
	v_pk_mul_f32 v[108:109], v[108:109], v[112:113]
	v_pk_mul_f32 v[114:115], v[114:115], v[118:119]
	v_pk_mul_f32 v[112:113], v[104:105], s[74:75] op_sel_hi:[1,0]
	v_pk_mul_f32 v[110:111], v[110:111], v[114:115]
	v_pk_mul_f32 v[114:115], v[106:107], s[74:75] op_sel_hi:[1,0]
	v_exp_f32_e32 v112, v112
	v_exp_f32_e32 v113, v113
	v_exp_f32_e32 v114, v114
	v_exp_f32_e32 v115, v115
	v_pk_add_f32 v[112:113], v[112:113], 1.0 op_sel_hi:[1,0]
	s_nop 0
	v_rcp_f32_e32 v112, v112
	v_pk_add_f32 v[114:115], v[114:115], 1.0 op_sel_hi:[1,0]
	v_rcp_f32_e32 v113, v113
	v_rcp_f32_e32 v114, v114
	v_rcp_f32_e32 v115, v115
	v_pk_mul_f32 v[104:105], v[104:105], v[112:113]
	v_pk_mul_f32 v[106:107], v[106:107], v[114:115]
	s_nop 0
	v_pk_mul_f32 v[106:107], v[102:103], v[106:107]
	v_pk_mul_f32 v[102:103], v[100:101], v[104:105]
	v_add_co_u32_e32 v104, vcc, s65, v144
	v_cvt_pk_bf16_f32 v100, v108, v109
	v_cvt_pk_bf16_f32 v101, v110, v111
	v_cvt_pk_bf16_f32 v102, v102, v103
	v_cvt_pk_bf16_f32 v103, v106, v107
	v_addc_co_u32_e32 v105, vcc, 0, v145, vcc
	global_store_dwordx4 v[104:105], v[100:103], off sc1
	s_nop 1
	v_pk_mul_f32 v[100:101], v[94:95], s[74:75] op_sel_hi:[1,0]
	v_pk_mul_f32 v[102:103], v[96:97], s[74:75] op_sel_hi:[1,0]
	v_exp_f32_e32 v100, v100
	v_exp_f32_e32 v101, v101
	v_exp_f32_e32 v102, v102
	v_exp_f32_e32 v103, v103
	v_pk_add_f32 v[100:101], v[100:101], 1.0 op_sel_hi:[1,0]
	s_nop 0
	v_rcp_f32_e32 v100, v100
	v_pk_add_f32 v[102:103], v[102:103], 1.0 op_sel_hi:[1,0]
	v_rcp_f32_e32 v101, v101
	v_rcp_f32_e32 v102, v102
	v_rcp_f32_e32 v103, v103
	v_pk_mul_f32 v[94:95], v[94:95], v[100:101]
	s_nop 0
	v_pk_mul_f32 v[90:91], v[90:91], v[94:95]
	v_pk_mul_f32 v[96:97], v[96:97], v[102:103]
	v_pk_mul_f32 v[94:95], v[86:87], s[74:75] op_sel_hi:[1,0]
	v_pk_mul_f32 v[92:93], v[92:93], v[96:97]
	v_pk_mul_f32 v[96:97], v[88:89], s[74:75] op_sel_hi:[1,0]
	v_exp_f32_e32 v94, v94
	v_exp_f32_e32 v95, v95
	v_exp_f32_e32 v96, v96
	v_exp_f32_e32 v97, v97
	v_pk_add_f32 v[94:95], v[94:95], 1.0 op_sel_hi:[1,0]
	s_nop 0
	v_rcp_f32_e32 v94, v94
	v_pk_add_f32 v[96:97], v[96:97], 1.0 op_sel_hi:[1,0]
	v_rcp_f32_e32 v95, v95
	v_rcp_f32_e32 v96, v96
	v_rcp_f32_e32 v97, v97
	v_pk_mul_f32 v[86:87], v[86:87], v[94:95]
	v_pk_mul_f32 v[88:89], v[88:89], v[96:97]
	s_nop 0
	v_pk_mul_f32 v[88:89], v[84:85], v[88:89]
	v_pk_mul_f32 v[84:85], v[82:83], v[86:87]
	v_add_co_u32_e32 v86, vcc, s64, v144
	v_cvt_pk_bf16_f32 v82, v90, v91
	v_cvt_pk_bf16_f32 v83, v92, v93
	v_cvt_pk_bf16_f32 v84, v84, v85
	v_cvt_pk_bf16_f32 v85, v88, v89
	v_addc_co_u32_e32 v87, vcc, 0, v145, vcc
	global_store_dwordx4 v[86:87], v[82:85], off sc1
	s_nop 1
	v_pk_mul_f32 v[82:83], v[78:79], s[74:75] op_sel_hi:[1,0]
	v_pk_mul_f32 v[84:85], v[80:81], s[74:75] op_sel_hi:[1,0]
	v_exp_f32_e32 v82, v82
	v_exp_f32_e32 v83, v83
	v_exp_f32_e32 v84, v84
	v_exp_f32_e32 v85, v85
	v_pk_add_f32 v[82:83], v[82:83], 1.0 op_sel_hi:[1,0]
	s_nop 0
	v_rcp_f32_e32 v82, v82
	v_pk_add_f32 v[84:85], v[84:85], 1.0 op_sel_hi:[1,0]
	v_rcp_f32_e32 v83, v83
	v_rcp_f32_e32 v84, v84
	v_rcp_f32_e32 v85, v85
	v_pk_mul_f32 v[78:79], v[78:79], v[82:83]
	s_nop 0
	v_pk_mul_f32 v[74:75], v[74:75], v[78:79]
	v_pk_mul_f32 v[80:81], v[80:81], v[84:85]
	v_pk_mul_f32 v[78:79], v[70:71], s[74:75] op_sel_hi:[1,0]
	v_pk_mul_f32 v[76:77], v[76:77], v[80:81]
	v_pk_mul_f32 v[80:81], v[72:73], s[74:75] op_sel_hi:[1,0]
	v_exp_f32_e32 v78, v78
	v_exp_f32_e32 v79, v79
	v_exp_f32_e32 v80, v80
	v_exp_f32_e32 v81, v81
	v_pk_add_f32 v[78:79], v[78:79], 1.0 op_sel_hi:[1,0]
	s_nop 0
	v_rcp_f32_e32 v78, v78
; __device__ __forceinline__ u32x4 pack8(f32x4 v0, f32x4 v1) { u32x4 w; w.x = cvt_pk_bf16(v0[0], v0[1]); w.y = cvt_pk_bf16(v0[2], v0[3]); w.z = cvt_pk_bf16(v1[0], v1[1]); w.w = cvt_pk_bf16(v1[2], v1[3]); return w; }
; #define PG8_BAR __builtin_amdgcn_s_barrier()
;     __device__ __forceinline__ void operator()(const f32x4 (&acc)[2][2][4][2], const Unit& u, int wr, int wc, int fr, int fq) const {
;         const int row0 = u.pm * BM + wr * 64 + fr, col0 = u.pn * HALF + wc * 32 + 8 * fq;
;         bf16_t* const p0 = ACT + (size_t)row0 * 5632 + col0;
; #pragma unroll
;         for (int ai = 0; ai < 2; ++ai)
; #pragma unroll
;             for (int m = 0; m < 4; ++m) {
;                 const f32x4 g0 = acc[ai][0][m][0], g1 = acc[ai][0][m][1];
;                 const f32x4 v0 = g0 * sigmoid4(g0) * acc[ai][1][m][0], v1 = g1 * sigmoid4(g1) * acc[ai][1][m][1];
;                 store16_wt(p0 + (size_t)(ai * HALF + m * 16) * 5632, pack8(v0, v1)); }
; template <class Epi, class Sched, bool ALIGN_EPI = false, bool SP2 = false>
; __device__ __forceinline__ void gemm_phase(PG8_LAS unsigned char* lds, const Gemm g, const Sched& S, const Epi& E) {
;     ...
;         if (!has_next) break;
; #pragma unroll
;         for (int a = 0; a < 2; ++a)
; #pragma unroll
;             for (int b = 0; b < 2; ++b)
; #pragma unroll
;                 for (int m = 0; m < 4; ++m)
; #pragma unroll
;                     for (int n = 0; n < 2; ++n) acc[a][b][m][n] = (f32x4){0.f, 0.f, 0.f, 0.f};
;         cur = nxt; cA = nA; cB = nB; ++ui;
;         if constexpr (ALIGN_EPI) { if (wr == 1) PG8_BAR; }
;     }
	v_pk_add_f32 v[80:81], v[80:81], 1.0 op_sel_hi:[1,0]
	v_rcp_f32_e32 v79, v79
	v_rcp_f32_e32 v80, v80
	v_rcp_f32_e32 v81, v81
	v_pk_mul_f32 v[70:71], v[70:71], v[78:79]
	v_pk_mul_f32 v[72:73], v[72:73], v[80:81]
	s_nop 0
	v_pk_mul_f32 v[72:73], v[68:69], v[72:73]
	v_pk_mul_f32 v[68:69], v[66:67], v[70:71]
	v_add_co_u32_e32 v70, vcc, s66, v144
	v_cvt_pk_bf16_f32 v66, v74, v75
	v_cvt_pk_bf16_f32 v67, v76, v77
	v_cvt_pk_bf16_f32 v68, v68, v69
	v_cvt_pk_bf16_f32 v69, v72, v73
	v_addc_co_u32_e32 v71, vcc, 0, v145, vcc
	global_store_dwordx4 v[70:71], v[66:69], off sc1
	s_nop 1
	v_pk_mul_f32 v[66:67], v[62:63], s[74:75] op_sel_hi:[1,0]
	v_pk_mul_f32 v[68:69], v[64:65], s[74:75] op_sel_hi:[1,0]
	v_exp_f32_e32 v66, v66
	v_exp_f32_e32 v67, v67
	v_exp_f32_e32 v68, v68
	v_exp_f32_e32 v69, v69
	v_pk_add_f32 v[66:67], v[66:67], 1.0 op_sel_hi:[1,0]
	s_nop 0
	v_rcp_f32_e32 v66, v66
	v_pk_add_f32 v[68:69], v[68:69], 1.0 op_sel_hi:[1,0]
	v_rcp_f32_e32 v67, v67
	v_rcp_f32_e32 v68, v68
	v_rcp_f32_e32 v69, v69
	v_pk_mul_f32 v[62:63], v[62:63], v[66:67]
	s_nop 0
	v_pk_mul_f32 v[58:59], v[58:59], v[62:63]
	v_pk_mul_f32 v[64:65], v[64:65], v[68:69]
	v_pk_mul_f32 v[62:63], v[54:55], s[74:75] op_sel_hi:[1,0]
	v_pk_mul_f32 v[60:61], v[60:61], v[64:65]
	v_pk_mul_f32 v[64:65], v[56:57], s[74:75] op_sel_hi:[1,0]
	v_exp_f32_e32 v62, v62
	v_exp_f32_e32 v63, v63
	v_exp_f32_e32 v64, v64
	v_exp_f32_e32 v65, v65
	v_pk_add_f32 v[62:63], v[62:63], 1.0 op_sel_hi:[1,0]
	s_nop 0
	v_rcp_f32_e32 v62, v62
	v_pk_add_f32 v[64:65], v[64:65], 1.0 op_sel_hi:[1,0]
	v_rcp_f32_e32 v63, v63
	v_rcp_f32_e32 v64, v64
	v_rcp_f32_e32 v65, v65
	v_pk_mul_f32 v[54:55], v[54:55], v[62:63]
	v_pk_mul_f32 v[56:57], v[56:57], v[64:65]
	s_nop 0
	v_pk_mul_f32 v[56:57], v[52:53], v[56:57]
	v_pk_mul_f32 v[52:53], v[50:51], v[54:55]
	v_add_co_u32_e32 v54, vcc, s0, v144
	v_cvt_pk_bf16_f32 v50, v58, v59
	v_cvt_pk_bf16_f32 v51, v60, v61
	v_cvt_pk_bf16_f32 v52, v52, v53
	v_cvt_pk_bf16_f32 v53, v56, v57
	v_addc_co_u32_e32 v55, vcc, 0, v145, vcc
	global_store_dwordx4 v[54:55], v[50:53], off sc1
	s_mov_b32 s0, 0x18c000
	s_nop 0
	v_pk_mul_f32 v[50:51], v[46:47], s[74:75] op_sel_hi:[1,0]
	v_pk_mul_f32 v[52:53], v[48:49], s[74:75] op_sel_hi:[1,0]
	v_exp_f32_e32 v50, v50
	v_exp_f32_e32 v51, v51
	v_exp_f32_e32 v52, v52
	v_exp_f32_e32 v53, v53
	v_pk_add_f32 v[50:51], v[50:51], 1.0 op_sel_hi:[1,0]
	s_nop 0
	v_rcp_f32_e32 v50, v50
	v_pk_add_f32 v[52:53], v[52:53], 1.0 op_sel_hi:[1,0]
	v_rcp_f32_e32 v51, v51
	v_rcp_f32_e32 v52, v52
	v_rcp_f32_e32 v53, v53
	v_pk_mul_f32 v[46:47], v[46:47], v[50:51]
	s_nop 0
	v_pk_mul_f32 v[42:43], v[42:43], v[46:47]
	v_pk_mul_f32 v[48:49], v[48:49], v[52:53]
	v_pk_mul_f32 v[46:47], v[38:39], s[74:75] op_sel_hi:[1,0]
	v_pk_mul_f32 v[44:45], v[44:45], v[48:49]
	v_pk_mul_f32 v[48:49], v[40:41], s[74:75] op_sel_hi:[1,0]
	v_exp_f32_e32 v46, v46
	v_exp_f32_e32 v47, v47
	v_exp_f32_e32 v48, v48
	v_exp_f32_e32 v49, v49
	v_pk_add_f32 v[46:47], v[46:47], 1.0 op_sel_hi:[1,0]
	s_nop 0
	v_rcp_f32_e32 v46, v46
	v_pk_add_f32 v[48:49], v[48:49], 1.0 op_sel_hi:[1,0]
	v_rcp_f32_e32 v47, v47
	v_rcp_f32_e32 v48, v48
	v_rcp_f32_e32 v49, v49
	v_pk_mul_f32 v[38:39], v[38:39], v[46:47]
	v_pk_mul_f32 v[40:41], v[40:41], v[48:49]
	s_nop 0
	v_pk_mul_f32 v[40:41], v[36:37], v[40:41]
	v_pk_mul_f32 v[36:37], v[34:35], v[38:39]
	v_add_co_u32_e32 v38, vcc, s0, v144
	v_cvt_pk_bf16_f32 v34, v42, v43
	v_cvt_pk_bf16_f32 v35, v44, v45
	v_cvt_pk_bf16_f32 v36, v36, v37
	v_cvt_pk_bf16_f32 v37, v40, v41
	v_addc_co_u32_e32 v39, vcc, 0, v145, vcc
	global_store_dwordx4 v[38:39], v[34:37], off sc1
	s_mov_b32 s0, 0x1b8000
	s_nop 0
	v_pk_mul_f32 v[34:35], v[30:31], s[74:75] op_sel_hi:[1,0]
	v_pk_mul_f32 v[36:37], v[32:33], s[74:75] op_sel_hi:[1,0]
	v_exp_f32_e32 v34, v34
	v_exp_f32_e32 v35, v35
	v_exp_f32_e32 v36, v36
	v_exp_f32_e32 v37, v37
	v_pk_add_f32 v[34:35], v[34:35], 1.0 op_sel_hi:[1,0]
	s_nop 0
	v_rcp_f32_e32 v34, v34
	v_pk_add_f32 v[36:37], v[36:37], 1.0 op_sel_hi:[1,0]
	v_rcp_f32_e32 v35, v35
	v_rcp_f32_e32 v36, v36
	v_rcp_f32_e32 v37, v37
	v_pk_mul_f32 v[30:31], v[30:31], v[34:35]
	s_nop 0
	v_pk_mul_f32 v[26:27], v[26:27], v[30:31]
	v_pk_mul_f32 v[32:33], v[32:33], v[36:37]
	v_pk_mul_f32 v[30:31], v[22:23], s[74:75] op_sel_hi:[1,0]
	v_pk_mul_f32 v[28:29], v[28:29], v[32:33]
	v_pk_mul_f32 v[32:33], v[24:25], s[74:75] op_sel_hi:[1,0]
	v_exp_f32_e32 v30, v30
	v_exp_f32_e32 v31, v31
	v_exp_f32_e32 v32, v32
	v_exp_f32_e32 v33, v33
	v_pk_add_f32 v[30:31], v[30:31], 1.0 op_sel_hi:[1,0]
	s_nop 0
	v_rcp_f32_e32 v30, v30
	v_pk_add_f32 v[32:33], v[32:33], 1.0 op_sel_hi:[1,0]
	v_rcp_f32_e32 v31, v31
	v_rcp_f32_e32 v32, v32
	v_rcp_f32_e32 v33, v33
	v_pk_mul_f32 v[22:23], v[22:23], v[30:31]
	v_pk_mul_f32 v[24:25], v[24:25], v[32:33]
	s_nop 0
	v_pk_mul_f32 v[24:25], v[20:21], v[24:25]
	v_pk_mul_f32 v[20:21], v[18:19], v[22:23]
	v_add_co_u32_e32 v22, vcc, s0, v144
	v_cvt_pk_bf16_f32 v18, v26, v27
	v_cvt_pk_bf16_f32 v19, v28, v29
	v_cvt_pk_bf16_f32 v20, v20, v21
	v_cvt_pk_bf16_f32 v21, v24, v25
	v_addc_co_u32_e32 v23, vcc, 0, v145, vcc
	global_store_dwordx4 v[22:23], v[18:21], off sc1
	s_nop 1
	v_pk_mul_f32 v[18:19], v[14:15], s[74:75] op_sel_hi:[1,0]
	v_pk_mul_f32 v[20:21], v[16:17], s[74:75] op_sel_hi:[1,0]
	v_exp_f32_e32 v18, v18
	v_exp_f32_e32 v19, v19
	v_exp_f32_e32 v20, v20
	v_exp_f32_e32 v21, v21
	v_pk_add_f32 v[18:19], v[18:19], 1.0 op_sel_hi:[1,0]
	s_nop 0
	v_rcp_f32_e32 v18, v18
	v_pk_add_f32 v[20:21], v[20:21], 1.0 op_sel_hi:[1,0]
	v_rcp_f32_e32 v19, v19
	v_rcp_f32_e32 v20, v20
	v_rcp_f32_e32 v21, v21
	v_pk_mul_f32 v[14:15], v[14:15], v[18:19]
	s_nop 0
	v_pk_mul_f32 v[10:11], v[10:11], v[14:15]
	v_pk_mul_f32 v[16:17], v[16:17], v[20:21]
	v_pk_mul_f32 v[14:15], v[6:7], s[74:75] op_sel_hi:[1,0]
	v_pk_mul_f32 v[12:13], v[12:13], v[16:17]
	v_pk_mul_f32 v[16:17], v[8:9], s[74:75] op_sel_hi:[1,0]
	v_exp_f32_e32 v14, v14
	v_exp_f32_e32 v15, v15
	v_exp_f32_e32 v16, v16
	v_exp_f32_e32 v17, v17
	v_pk_add_f32 v[14:15], v[14:15], 1.0 op_sel_hi:[1,0]
	s_nop 0
	v_rcp_f32_e32 v14, v14
	v_pk_add_f32 v[16:17], v[16:17], 1.0 op_sel_hi:[1,0]
	v_rcp_f32_e32 v15, v15
	v_rcp_f32_e32 v16, v16
	v_rcp_f32_e32 v17, v17
	v_pk_mul_f32 v[6:7], v[6:7], v[14:15]
	v_pk_mul_f32 v[8:9], v[8:9], v[16:17]
	s_nop 0
	v_pk_mul_f32 v[8:9], v[4:5], v[8:9]
	v_pk_mul_f32 v[4:5], v[2:3], v[6:7]
	v_add_co_u32_e32 v6, vcc, 0x1e4000, v144
	v_cvt_pk_bf16_f32 v2, v10, v11
	s_nop 0
	v_addc_co_u32_e32 v7, vcc, 0, v145, vcc
	v_cvt_pk_bf16_f32 v3, v12, v13
	v_cvt_pk_bf16_f32 v4, v4, v5
	v_cvt_pk_bf16_f32 v5, v8, v9
	s_andn2_b64 vcc, exec, s[38:39]
	global_store_dwordx4 v[6:7], v[2:5], off sc1
	s_cbranch_vccnz .LBB0_1454
	s_andn2_b64 vcc, exec, s[6:7]
	s_branch .LBB0_1453

; #define PG8_BAR __builtin_amdgcn_s_barrier()
; template <class Epi, class Sched, bool ALIGN_EPI = false, bool SP2 = false>
; __device__ __forceinline__ void gemm_phase(PG8_LAS unsigned char* lds, const Gemm g, const Sched& S, const Epi& E) {
;     ...
;     for (int i = 0; i < 2; ++i) { int R, C; stage_rc(tid * 16 + i * 8192, R, C); const int Rb = Epi::PERM ? ((R & ~31) + perm32(R & 31)) : R;
;         voffA[i] = (unsigned)(R * K + C) * 2u; voffB[i] = (unsigned)(Rb * K + C) * 2u; }
;     const size_t kstep = (size_t)(BK * 2);
;     const size_t hstep = (size_t)HALF * K * 2;
;     const size_t tstep = 2 * hstep;
;     const unsigned ldsw = (unsigned)wid * 1024u;
;     const int aoff = lds_byte(wr * 64 + fr, fq * 8), boff = lds_byte(wc * 32 + fr, fq * 8);
;     ...
;     { const int rot0 = cur.krot, nt0 = cur.nkt; const char* sA0 = PG8_KP(cA, 0, rot0, nt0); const char* sA1 = PG8_KP(cA, 1, rot0, nt0); const char* sB0 = PG8_KP(cB, 0, rot0, nt0); const char* sB1 = PG8_KP(cB, 1, rot0, nt0);
;     if constexpr (SP2) {
;         PG8_STAGEB(PG8_SB(0, 0), sB0, voffB); PG8_STAGEB(PG8_SB(0, 1), sB0 + hstep, voffB); PG8_STAGE(PG8_SA(0, 0), sA0, voffA); PG8_STAGE(PG8_SA(0, 1), sA0 + hstep, voffA);
;         if (wr == 1) PG8_BAR;
;         PG8_WAIT_V(2); PG8_BAR;
;         PG8_STAGEB(PG8_SB(1, 0), sB1, voffB); PG8_STAGE(PG8_SA(1, 0), sA1, voffA); PG8_STAGEB(PG8_SB(1, 1), sB1 + hstep, voffB);
;         PG8_WAIT_V(6); PG8_BAR;
;     } else {
;         PG8_STAGEB(PG8_SB(0, 0), sB0, voffB); PG8_STAGE(PG8_SA(0, 0), sA0, voffA); PG8_STAGEB(PG8_SB(0, 1), sB0 + hstep, voffB); PG8_STAGE(PG8_SA(0, 1), sA0 + hstep, voffA);
;         if (wr == 1) PG8_BAR;
;         PG8_WAIT_V(4); PG8_BAR;
;         PG8_STAGEB(PG8_SB(1, 0), sB1, voffB); PG8_STAGE(PG8_SA(1, 0), sA1, voffA); PG8_STAGEB(PG8_SB(1, 1), sB1 + hstep, voffB);
;         PG8_WAIT_V(6); PG8_BAR;
;     }
; __global__ void __launch_bounds__(NWAVES * 64, 2) enc_fwd(Args args) {
;     ...
;         if (EN(10) && IN(pb + 9)) { for (int rep = 0; rep < NREP(10); ++rep) { FRESH_WS(); pg8::Gemm g{ACT, (const bf16*)(ws + WS_WDN + l * SZ_WDN), NTOK, 2048, 5632}; pg8::SplitOrder S; S.init(5632, G, bx);
;             pg8::EpiRes E{(NREP(10) == 2 && rep == 0) ? (bf16*)(ws + WS_P) : XB, l == NL - 1 ? X : nullptr, MODL + 10240, SL};
;             pg8::gemm_phase<pg8::EpiRes, pg8::SplitOrder, PG8_ALIGN, PG8_SP2>(lds + RING_OFF, g, S, E); } SEAM(pb + 9); }
.LBB0_1638:
	v_readlane_b32 s0, v254, 58
	s_mov_b64 s[12:13], s[66:67]
	v_mov_b32_e32 v18, v0
	v_readlane_b32 s1, v254, 59
	s_and_b64 vcc, exec, s[0:1]
	v_readfirstlane_b32 s14, v18
	s_cbranch_vccnz .LBB0_1733
	v_lshlrev_b32_e32 v1, 4, v18
	v_add_u32_e32 v2, 0x2000, v1
	v_ashrrev_i32_e32 v3, 31, v2
	v_lshrrev_b32_e32 v3, 22, v3
	v_add_u32_e32 v3, v2, v3
	v_ashrrev_i32_e32 v10, 10, v3
	v_mul_i32_i24_e32 v3, 0x400, v10
	v_sub_u32_e32 v2, v2, v3
	v_lshrrev_b32_e32 v3, 4, v2
	v_bitop3_b32 v2, v3, v2, 32 bitop3:0x6c
	v_ashrrev_i32_e32 v3, 31, v2
	v_lshrrev_b32_e32 v3, 26, v3
	v_add_u32_e32 v3, v2, v3
	v_lshlrev_b32_e32 v4, 3, v10
	v_ashrrev_i32_e32 v11, 6, v3
	v_and_b32_e32 v4, -16, v4
	v_add_u32_e32 v4, v11, v4
	v_and_b32_e32 v5, 3, v11
	s_mov_b32 s3, 0x7fffe0
	v_lshrrev_b32_e32 v6, 2, v4
	v_lshlrev_b32_e32 v7, 1, v4
	v_and_b32_e32 v3, 0xc0, v3
	v_and_or_b32 v5, v4, s3, v5
	v_and_b32_e32 v6, 4, v6
	v_and_b32_e32 v7, 24, v7
	v_sub_u32_e32 v2, v2, v3
	v_or3_b32 v5, v5, v6, v7
	v_lshlrev_b32_e32 v6, 5, v10
	v_ashrrev_i16_sdwa v2, v207, sext(v2) dst_sel:DWORD dst_unused:UNUSED_PAD src0_sel:DWORD src1_sel:BYTE_0
	v_and_b32_e32 v12, 32, v6
	v_bfe_i32 v13, v2, 0, 16
	s_movk_i32 s2, 0x1600
	v_mul_u32_u24_e32 v5, 0x1600, v5
	v_add_u32_e32 v2, v12, v13
	v_mul_lo_u32 v3, v4, s2
	v_add_lshl_u32 v156, v5, v2, 1
	v_add_lshl_u32 v158, v2, v3, 1
	v_bfe_i32 v2, v18, 27, 1
	v_lshrrev_b32_e32 v2, 22, v2
	v_add_u32_e32 v2, v1, v2
	v_and_b32_e32 v2, 0xfffffc00, v2
	v_sub_u32_e32 v1, v1, v2
	v_lshrrev_b32_e32 v2, 4, v1
	v_ashrrev_i32_e32 v3, 31, v18
	v_bitop3_b32 v1, v2, v1, 32 bitop3:0x6c
	v_lshrrev_b32_e32 v3, 26, v3
	v_readlane_b32 s8, v254, 53
	s_add_u32 s30, s12, 0x2f580000
	v_ashrrev_i32_e32 v2, 31, v1
	v_add_u32_e32 v3, v18, v3
	s_mul_i32 s1, s8, 0x1600000
	s_addc_u32 s31, s13, 0
	v_lshrrev_b32_e32 v2, 26, v2
	v_ashrrev_i32_e32 v15, 6, v3
	s_mul_hi_u32 s0, s8, 0x1600000
	s_add_u32 s1, s12, s1
	v_add_u32_e32 v2, v1, v2
	v_lshlrev_b32_e32 v3, 3, v15
	s_addc_u32 s0, s13, s0
	v_ashrrev_i32_e32 v14, 6, v2
	v_and_b32_e32 v3, -16, v3
	s_add_u32 s33, s1, 0x17000000
	v_add_u32_e32 v3, v14, v3
	v_and_b32_e32 v2, 0xc0, v2
	s_addc_u32 s48, s0, 0
	s_ashr_i32 s0, s14, 6
	v_sub_u32_e32 v1, v1, v2
	v_mul_lo_u32 v2, v3, s2
	v_readlane_b32 s2, v252, 57
	s_ashr_i32 s1, s14, 8
	s_lshl_b32 s49, s0, 10
	v_and_b32_e32 v4, 3, v14
	s_mul_i32 s2, s2, 0x2c0000
	v_and_or_b32 v4, v3, s3, v4
	s_add_u32 s2, s30, s2
	v_readlane_b32 s3, v252, 59
	v_lshrrev_b32_e32 v5, 2, v3
	v_lshlrev_b32_e32 v6, 1, v3
	s_addc_u32 s4, s31, 0
	s_mul_i32 s5, s3, 0x2c0000
	v_and_b32_e32 v5, 4, v5
	v_and_b32_e32 v6, 24, v6
	s_add_u32 s5, s33, s5
	v_or3_b32 v4, v4, v5, v6
	v_lshlrev_b32_e32 v5, 5, v15
	v_ashrrev_i16_sdwa v1, v207, sext(v1) dst_sel:DWORD dst_unused:UNUSED_PAD src0_sel:DWORD src1_sel:BYTE_0
	s_addc_u32 s6, s48, 0
	v_readlane_b32 s3, v252, 43
	v_and_b32_e32 v16, 32, v5
	v_bfe_i32 v17, v1, 0, 16
	s_add_u32 s34, s5, s3
	v_mul_u32_u24_e32 v4, 0x1600, v4
	v_add_u32_e32 v1, v16, v17
	s_addc_u32 s35, s6, 0
	s_add_i32 s50, s49, 0
	v_add_lshl_u32 v160, v4, v1, 1
	s_add_i32 m0, s50, 0x10000
	v_add_lshl_u32 v162, v1, v2, 1
	global_load_lds_dwordx4 v160, s[34:35]
	s_add_i32 m0, s50, 0x12000
	s_add_u32 s38, s2, s3
	s_addc_u32 s39, s4, 0
	s_add_u32 s4, s34, 0x160000
	global_load_lds_dwordx4 v156, s[34:35]
	s_addc_u32 s5, s35, 0
	s_add_i32 m0, s50, 0x14000
	s_add_i32 s51, s50, 0x2000
	global_load_lds_dwordx4 v160, s[4:5]
	s_add_i32 m0, s50, 0x16000
	v_mov_b32_e32 v161, v98
	global_load_lds_dwordx4 v156, s[4:5]
	s_mov_b32 m0, s50
	s_add_u32 s4, s38, 0x160000
	global_load_lds_dwordx4 v162, s[38:39]
	s_mov_b32 m0, s51
	s_addc_u32 s5, s39, 0
	s_add_i32 s52, s50, 0x4000
	global_load_lds_dwordx4 v158, s[38:39]
	s_mov_b32 m0, s52
	s_add_i32 s53, s50, 0x6000
	global_load_lds_dwordx4 v162, s[4:5]
	s_mov_b32 m0, s53
	v_mov_b32_e32 v157, v98
	global_load_lds_dwordx4 v158, s[4:5]
	v_mov_b32_e32 v163, v98
	v_mov_b32_e32 v159, v98
	s_cmp_eq_u32 s1, 1
	v_lshl_add_u64 v[8:9], s[34:35], 0, v[160:161]
	v_lshl_add_u64 v[6:7], s[34:35], 0, v[156:157]
	v_lshl_add_u64 v[2:3], s[38:39], 0, v[162:163]
	s_cselect_b64 s[4:5], -1, 0
	s_cmp_lg_u32 s1, 1
	v_lshl_add_u64 v[4:5], s[38:39], 0, v[158:159]
	v_readlane_b32 s9, v254, 54
.LBB0_1641:
	s_cmp_eq_u32 s8, 3
	s_cselect_b32 s7, s65, 0
	s_cselect_b32 s6, s64, 0
	s_cmp_lg_u64 s[6:7], 0
	s_cselect_b64 s[8:9], -1, 0
	s_add_u32 s10, s12, 0x39880000
	s_addc_u32 s11, s13, 0
	v_readlane_b32 s2, v254, 57
	s_add_u32 s2, s12, s2
	v_readlane_b32 s3, v254, 56
	s_addc_u32 s15, s13, s3
	s_add_u32 s55, s2, 0x10a000
	s_addc_u32 s56, s15, 0
	s_add_u32 s57, s12, 0x35880000
	v_lshrrev_b32_e32 v19, 1, v18
	s_addc_u32 s58, s13, 0
	v_and_b32_e32 v19, 24, v19
	s_lshl_b32 s0, s0, 5
	v_and_b32_e32 v1, 15, v18
	v_lshlrev_b32_e32 v20, 1, v19
	v_lshlrev_b32_e32 v18, 2, v18
	s_and_b32 s2, s0, 0x60
	s_add_i32 m0, s50, 0x18000
	v_lshl_add_u64 v[8:9], v[8:9], 0, s[76:77]
	s_lshl_b32 s59, s1, 6
	v_lshl_or_b32 v20, v1, 6, v20
	s_lshl_b32 s1, s1, 13
	v_and_b32_e32 v18, 32, v18
	s_lshl_b32 s0, s2, 7
	global_load_lds_dwordx4 v[8:9], off
	v_lshl_add_u64 v[6:7], v[6:7], 0, s[76:77]
	s_add_i32 m0, s50, 0x1a000
	s_add_i32 s60, s50, 0x8000
	s_add_i32 s61, s50, 0xa000
	v_bitop3_b32 v99, v20, s0, v18 bitop3:0xde
	global_load_lds_dwordx4 v[6:7], off
	v_lshl_add_u64 v[2:3], v[2:3], 0, s[76:77]
	s_mov_b32 m0, s60
	s_add_u32 s0, s34, 0x160080
	v_bitop3_b32 v21, v20, s1, v18 bitop3:0xde
	global_load_lds_dwordx4 v[2:3], off
	v_lshl_add_u64 v[2:3], v[4:5], 0, s[76:77]
	s_mov_b32 m0, s61
	s_addc_u32 s1, s35, 0
	global_load_lds_dwordx4 v[2:3], off
	s_add_i32 m0, s50, 0x1c000
	v_lshl_add_u64 v[2:3], s[0:1], 0, v[160:161]
	global_load_lds_dwordx4 v[2:3], off
	v_lshl_add_u64 v[2:3], s[0:1], 0, v[156:157]
	s_add_i32 m0, s50, 0x1e000
	v_or_b32_e32 v188, s2, v19
	global_load_lds_dwordx4 v[2:3], off
	s_movk_i32 s2, 0x1600
	v_lshrrev_b32_e32 v3, 1, v10
	v_mul_lo_u32 v2, v11, s2
	s_mov_b32 s3, 0x16000
	v_mad_u64_u32 v[2:3], s[0:1], v3, s3, v[2:3]
	v_or_b32_e32 v2, v2, v12
	v_add_lshl_u32 v164, v2, v13, 1
	v_lshrrev_b32_e32 v3, 1, v15
	v_mul_lo_u32 v2, v14, s2
	s_waitcnt vmcnt(6)
	v_mad_u64_u32 v[2:3], s[0:1], v3, s3, v[2:3]
	s_cmpk_lt_u32 s14, 0x100
	v_or_b32_e32 v2, v2, v16
	v_readlane_b32 s0, v252, 45
	s_mov_b32 s54, 0
	s_cselect_b64 s[12:13], -1, 0
	v_mov_b32_e32 v165, v98
	v_add_lshl_u32 v166, v2, v17, 1
	v_mov_b32_e32 v167, v98
	v_add_u32_e32 v189, 0, v21
	s_mov_b32 s78, s0
	v_readlane_b32 s82, v252, 42
	v_readlane_b32 s75, v252, 59
	v_readlane_b32 s71, v252, 57
	s_mov_b32 s3, 0x20000
	s_mov_b32 s47, 0x30000
	s_mov_b64 s[64:65], 0x40000
	s_mov_b64 s[66:67], 0x10000
	s_barrier
	s_branch .LBB0_1644
